# v26 + GEMM K-loops (5 phases): the 16 per-iteration v_add_u32 that formed A-fragment LDS read addresses folded into ds_read_b128 offset: immediates (fragment base pre-biased once per phase)
# speedup vs baseline: 1.0043x; 1.0006x over previous
.LBB0_154:
	v_readlane_b32 s44, v254, 30
	v_mov_b32_e32 v137, v35
	v_readlane_b32 s45, v254, 31
	v_mov_b32_e32 v133, v35
	v_readlane_b32 s42, v254, 26
	v_lshl_add_u64 v[2:3], s[44:45], 0, v[136:137]
	v_lshl_add_u64 v[4:5], s[44:45], 0, v[132:133]
	v_mov_b32_e32 v139, v35
	v_readlane_b32 s43, v254, 27
	s_add_i32 m0, s34, 0x18000
	v_lshl_add_u64 v[2:3], v[2:3], 0, s[10:11]
	v_lshl_add_u64 v[6:7], s[42:43], 0, v[138:139]
	v_mov_b32_e32 v135, v35
	s_waitcnt vmcnt(2)
	s_barrier
	global_load_lds_dwordx4 v[2:3], off
	v_lshl_add_u64 v[2:3], v[4:5], 0, s[10:11]
	s_add_i32 m0, s34, 0x1a000
	s_add_i32 s56, s34, 0x8000
	v_lshl_add_u64 v[8:9], s[42:43], 0, v[134:135]
	global_load_lds_dwordx4 v[2:3], off
	v_lshl_add_u64 v[2:3], v[6:7], 0, s[10:11]
	s_mov_b32 m0, s56
	s_add_i32 s57, s34, 0xa000
	global_load_lds_dwordx4 v[2:3], off
	v_lshl_add_u64 v[2:3], v[8:9], 0, s[10:11]
	v_readlane_b32 s10, v254, 32
	s_mov_b32 m0, s57
	v_readlane_b32 s11, v254, 33
	global_load_lds_dwordx4 v[2:3], off
	s_add_i32 m0, s34, 0x1c000
	v_lshl_add_u64 v[2:3], s[10:11], 0, v[136:137]
	global_load_lds_dwordx4 v[2:3], off
	v_lshl_add_u64 v[2:3], s[10:11], 0, v[132:133]
	s_add_i32 m0, s34, 0x1e000
	s_and_b32 s18, s6, 3
	global_load_lds_dwordx4 v[2:3], off
	v_and_b32_e32 v2, 15, v1
	v_lshlrev_b32_e32 v4, 3, v1
	v_and_b32_e32 v1, 48, v1
	s_movk_i32 s6, 0x70
	v_and_b32_e32 v5, 0x70, v4
	v_bitop3_b32 v4, v4, v1, s6 bitop3:0x6c
	s_lshl_b32 s6, s9, 2
	s_lshl_b32 s58, s9, 6
	s_lshl_b32 s19, s18, 5
	s_or_b32 s20, s6, s18
	s_cmp_lt_i32 s20, 4
	s_cselect_b64 s[6:7], -1, 0
	s_lshl_b32 s12, s20, 6
	s_ashr_i32 s13, s12, 31
	s_cmpk_lt_u32 s8, 0x100
	s_cselect_b64 s[10:11], -1, 0
	s_cmp_lt_u32 s18, 2
	s_cselect_b64 s[38:39], -1, 0
	s_lshl_b64 s[12:13], s[12:13], 2
	s_add_u32 s59, s76, s12
	s_addc_u32 s60, s77, s13
	s_lshl_b32 s8, s20, 8
	v_readlane_b32 s12, v255, 19
	v_or_b32_e32 v3, s58, v2
	v_or_b32_e32 v2, s19, v2
	s_add_i32 s61, s12, s8
	s_lshl_b32 s8, s9, 8
	v_lshlrev_b32_e32 v3, 7, v3
	v_lshlrev_b32_e32 v2, 7, v2
	s_waitcnt vmcnt(6)
	s_add_i32 s62, s12, s8
	s_lshl_b32 s8, s18, 2
	v_bitop3_b32 v6, v3, v5, v1 bitop3:0xf6
	v_bitop3_b32 v1, v2, v5, v1 bitop3:0xf6
	v_bitop3_b32 v141, v2, 64, v4 bitop3:0x36
	v_add_u32_e32 v1, 0x10000, v1
	v_add_u32_e32 v141, 0x10000, v141
	v_bitop3_b32 v2, v3, 64, v4 bitop3:0x36
	s_add_i32 s70, s8, 0
	s_add_i32 s63, s70, 0x20400
	s_add_i32 s64, s70, 0x20600
	s_add_i32 s65, s70, 0x20800
	s_add_i32 s66, s70, 0x20a00
	s_add_i32 s67, s70, 0x21400
	s_add_i32 s68, s70, 0x21600
	s_add_i32 s69, s70, 0x21800
	s_add_i32 s70, s70, 0x21a00
	s_mov_b32 s71, 0
	v_add_u32_e32 v142, 0, v6
	v_add_u32_e32 v143, 0, v2
	s_lshl_b32 s92, s19, 1
	v_readlane_b32 s12, v254, 5
	v_readlane_b32 s46, v254, 20
	s_mov_b32 s24, 0
	s_barrier
	v_readlane_b32 s47, v254, 21
	s_branch .LBB0_157

.LBB0_161:
	s_ashr_i32 s23, s22, 31
	s_lshl_b64 s[8:9], s[22:23], 20
	v_readlane_b32 s20, v254, 38
	v_readlane_b32 s21, v254, 39
	s_add_u32 s8, s20, s8
	s_addc_u32 s9, s21, s9
	s_and_b64 s[20:21], s[40:41], exec
	s_cselect_b32 s13, s9, s43
	s_cselect_b32 s20, s8, s42
	s_ashr_i32 s19, s18, 31
	s_lshl_b64 s[28:29], s[18:19], 20
	v_readlane_b32 s30, v254, 22
	v_readlane_b32 s31, v254, 23
	s_add_u32 s28, s30, s28
	s_addc_u32 s29, s31, s29
	s_and_b64 s[30:31], s[40:41], exec
	s_cselect_b32 s19, s29, s45
	s_cselect_b32 s21, s28, s44
	s_add_u32 s42, s42, 0x80080
	s_addc_u32 s43, s43, 0
	s_add_u32 s23, s44, 0x100
	s_addc_u32 s25, s45, 0
	s_mov_b32 s30, -2
	v_readlane_b32 s52, v255, 20
	v_readlane_b32 s53, v255, 21
	v_readlane_b32 s72, v255, 22
	v_readlane_b32 s73, v255, 23
	s_mov_b64 s[74:75], 0x80
	s_add_u32 s31, s42, 0xfff80080
	s_addc_u32 s44, s43, -1
	s_add_i32 s47, 0, 0x10000
	s_cmp_eq_u32 s30, 28
	s_cselect_b32 s49, s13, s44
	s_cselect_b32 s48, s20, s31
	ds_read_b128 v[144:147], v1
	ds_read_b128 v[148:151], v141
	s_cselect_b32 s45, s19, s25
	s_cselect_b32 s44, s21, s23
	s_add_i32 s31, 0, 0x14000
	ds_read_b128 v[152:155], v1 offset:2048
	ds_read_b128 v[156:159], v141 offset:2048
	ds_read_b128 v[160:163], v1 offset:16384
	ds_read_b128 v[164:167], v141 offset:16384
	ds_read_b128 v[168:171], v1 offset:18432
	ds_read_b128 v[172:175], v141 offset:18432
	v_lshl_add_u64 v[212:213], s[42:43], 0, v[138:139]
	s_add_i32 m0, s34, 0xc000
	ds_read_b128 v[176:179], v142
	ds_read_b128 v[184:187], v142 offset:2048
	ds_read_b128 v[188:191], v143
	ds_read_b128 v[192:195], v143 offset:2048
	ds_read_b128 v[196:199], v142 offset:4096
	ds_read_b128 v[200:203], v142 offset:6144
	ds_read_b128 v[204:207], v143 offset:4096
	ds_read_b128 v[208:211], v143 offset:6144
	global_load_lds_dwordx4 v[212:213], off
	v_lshl_add_u64 v[212:213], s[42:43], 0, v[134:135]
	s_add_i32 m0, s34, 0xe000
	s_nop 0
	global_load_lds_dwordx4 v[212:213], off
	s_waitcnt vmcnt(8)
	s_waitcnt lgkmcnt(0)
	s_barrier
	s_setprio 1
	s_waitcnt lgkmcnt(0)
	v_mfma_f32_16x16x32_bf16 v[128:131], v[144:147], v[176:179], 0
	v_mfma_f32_16x16x32_bf16 v[124:127], v[152:155], v[176:179], 0
	v_mfma_f32_16x16x32_bf16 v[112:115], v[144:147], v[184:187], 0
	v_mfma_f32_16x16x32_bf16 v[108:111], v[152:155], v[184:187], 0
	v_mfma_f32_16x16x32_bf16 v[96:99], v[144:147], v[196:199], 0
	v_mfma_f32_16x16x32_bf16 v[92:95], v[152:155], v[196:199], 0
	v_mfma_f32_16x16x32_bf16 v[80:83], v[144:147], v[200:203], 0
	v_mfma_f32_16x16x32_bf16 v[76:79], v[152:155], v[200:203], 0
	v_mfma_f32_16x16x32_bf16 v[128:131], v[148:151], v[188:191], v[128:131]
	v_mfma_f32_16x16x32_bf16 v[124:127], v[156:159], v[188:191], v[124:127]
	v_mfma_f32_16x16x32_bf16 v[112:115], v[148:151], v[192:195], v[112:115]
	v_mfma_f32_16x16x32_bf16 v[108:111], v[156:159], v[192:195], v[108:111]
	v_mfma_f32_16x16x32_bf16 v[96:99], v[148:151], v[204:207], v[96:99]
	v_mfma_f32_16x16x32_bf16 v[92:95], v[156:159], v[204:207], v[92:95]
	v_mfma_f32_16x16x32_bf16 v[80:83], v[148:151], v[208:211], v[80:83]
	v_mfma_f32_16x16x32_bf16 v[76:79], v[156:159], v[208:211], v[76:79]
	s_setprio 0
	s_setprio 1
	v_mfma_f32_16x16x32_bf16 v[120:123], v[160:163], v[176:179], 0
	v_mfma_f32_16x16x32_bf16 v[116:119], v[168:171], v[176:179], 0
	v_mfma_f32_16x16x32_bf16 v[104:107], v[160:163], v[184:187], 0
	v_mfma_f32_16x16x32_bf16 v[100:103], v[168:171], v[184:187], 0
	v_mfma_f32_16x16x32_bf16 v[88:91], v[160:163], v[196:199], 0
	v_mfma_f32_16x16x32_bf16 v[84:87], v[168:171], v[196:199], 0
	v_mfma_f32_16x16x32_bf16 v[72:75], v[160:163], v[200:203], 0
	v_mfma_f32_16x16x32_bf16 v[68:71], v[168:171], v[200:203], 0
	v_mfma_f32_16x16x32_bf16 v[120:123], v[164:167], v[188:191], v[120:123]
	v_mfma_f32_16x16x32_bf16 v[116:119], v[172:175], v[188:191], v[116:119]
	v_mfma_f32_16x16x32_bf16 v[104:107], v[164:167], v[192:195], v[104:107]
	v_mfma_f32_16x16x32_bf16 v[100:103], v[172:175], v[192:195], v[100:103]
	v_mfma_f32_16x16x32_bf16 v[88:91], v[164:167], v[204:207], v[88:91]
	v_mfma_f32_16x16x32_bf16 v[84:87], v[172:175], v[204:207], v[84:87]
	v_mfma_f32_16x16x32_bf16 v[72:75], v[164:167], v[208:211], v[72:75]
	v_mfma_f32_16x16x32_bf16 v[68:71], v[172:175], v[208:211], v[68:71]
	s_setprio 0
	s_barrier
	s_add_i32 s47, s47, s33
	v_lshl_add_u64 v[212:213], s[44:45], 0, v[136:137]
	s_mov_b32 m0, s47
	ds_read_b128 v[176:179], v142 offset:16384
	ds_read_b128 v[184:187], v142 offset:18432
	ds_read_b128 v[188:191], v143 offset:16384
	ds_read_b128 v[192:195], v143 offset:18432
	ds_read_b128 v[196:199], v142 offset:20480
	ds_read_b128 v[200:203], v142 offset:22528
	ds_read_b128 v[204:207], v143 offset:20480
	ds_read_b128 v[208:211], v143 offset:22528
	global_load_lds_dwordx4 v[212:213], off
	s_add_i32 m0, s47, 0x2000
	s_add_u32 s50, s44, 0x80000
	v_lshl_add_u64 v[224:225], s[44:45], 0, v[132:133]
	s_addc_u32 s51, s45, 0
	s_add_i32 s31, s31, s33
	global_load_lds_dwordx4 v[224:225], off
	v_lshl_add_u64 v[226:227], s[50:51], 0, v[136:137]
	s_mov_b32 m0, s31
	v_lshl_add_u64 v[228:229], s[48:49], 0, v[134:135]
	global_load_lds_dwordx4 v[226:227], off
	v_lshl_add_u64 v[226:227], s[50:51], 0, v[132:133]
	s_add_i32 m0, s31, 0x2000
	s_nop 0
	global_load_lds_dwordx4 v[226:227], off
	v_lshl_add_u64 v[226:227], s[48:49], 0, v[138:139]
	s_mov_b32 m0, s34
	s_nop 0
	global_load_lds_dwordx4 v[226:227], off
	s_mov_b32 m0, s35
	s_nop 0
	global_load_lds_dwordx4 v[228:229], off
	s_waitcnt vmcnt(8)
	s_waitcnt lgkmcnt(0)
	s_barrier
	s_setprio 1
	s_waitcnt lgkmcnt(0)
	v_mfma_f32_16x16x32_bf16 v[64:67], v[144:147], v[176:179], 0
	v_mfma_f32_16x16x32_bf16 v[60:63], v[152:155], v[176:179], 0
	v_mfma_f32_16x16x32_bf16 v[48:51], v[144:147], v[184:187], 0
	v_mfma_f32_16x16x32_bf16 v[44:47], v[152:155], v[184:187], 0
	v_mfma_f32_16x16x32_bf16 v[30:33], v[144:147], v[196:199], 0
	v_mfma_f32_16x16x32_bf16 v[26:29], v[152:155], v[196:199], 0
	v_mfma_f32_16x16x32_bf16 v[14:17], v[144:147], v[200:203], 0
	v_mfma_f32_16x16x32_bf16 v[10:13], v[152:155], v[200:203], 0
	v_mfma_f32_16x16x32_bf16 v[64:67], v[148:151], v[188:191], v[64:67]
	v_mfma_f32_16x16x32_bf16 v[60:63], v[156:159], v[188:191], v[60:63]
	v_mfma_f32_16x16x32_bf16 v[48:51], v[148:151], v[192:195], v[48:51]
	v_mfma_f32_16x16x32_bf16 v[44:47], v[156:159], v[192:195], v[44:47]
	v_mfma_f32_16x16x32_bf16 v[30:33], v[148:151], v[204:207], v[30:33]
	v_mfma_f32_16x16x32_bf16 v[26:29], v[156:159], v[204:207], v[26:29]
	v_mfma_f32_16x16x32_bf16 v[14:17], v[148:151], v[208:211], v[14:17]
	v_mfma_f32_16x16x32_bf16 v[10:13], v[156:159], v[208:211], v[10:13]
	s_setprio 0
	s_setprio 1
	v_mfma_f32_16x16x32_bf16 v[56:59], v[160:163], v[176:179], 0
	v_mfma_f32_16x16x32_bf16 v[52:55], v[168:171], v[176:179], 0
	v_mfma_f32_16x16x32_bf16 v[40:43], v[160:163], v[184:187], 0
	v_mfma_f32_16x16x32_bf16 v[36:39], v[168:171], v[184:187], 0
	v_mfma_f32_16x16x32_bf16 v[22:25], v[160:163], v[196:199], 0
	v_mfma_f32_16x16x32_bf16 v[18:21], v[168:171], v[196:199], 0
	v_mfma_f32_16x16x32_bf16 v[6:9], v[160:163], v[200:203], 0
	v_mfma_f32_16x16x32_bf16 v[2:5], v[168:171], v[200:203], 0
	v_mfma_f32_16x16x32_bf16 v[56:59], v[164:167], v[188:191], v[56:59]
	v_mfma_f32_16x16x32_bf16 v[52:55], v[172:175], v[188:191], v[52:55]
	v_mfma_f32_16x16x32_bf16 v[40:43], v[164:167], v[192:195], v[40:43]
	v_mfma_f32_16x16x32_bf16 v[36:39], v[172:175], v[192:195], v[36:39]
	v_mfma_f32_16x16x32_bf16 v[22:25], v[164:167], v[204:207], v[22:25]
	v_mfma_f32_16x16x32_bf16 v[18:21], v[172:175], v[204:207], v[18:21]
	v_mfma_f32_16x16x32_bf16 v[6:9], v[164:167], v[208:211], v[6:9]
	v_mfma_f32_16x16x32_bf16 v[2:5], v[172:175], v[208:211], v[2:5]
	s_setprio 0
	s_barrier
	s_add_i32 s31, 0, 0x18000
	ds_read_b128 v[144:147], v1 offset:32768
	ds_read_b128 v[148:151], v141 offset:32768
	s_add_i32 s47, 0, 0x1c000
	ds_read_b128 v[152:155], v1 offset:34816
	ds_read_b128 v[156:159], v141 offset:34816
	ds_read_b128 v[160:163], v1 offset:49152
	ds_read_b128 v[164:167], v141 offset:49152
	ds_read_b128 v[168:171], v1 offset:51200
	ds_read_b128 v[172:175], v141 offset:51200
	s_add_u32 s48, s48, 0x80000
	s_addc_u32 s49, s49, 0
	s_mov_b32 m0, s54
	v_lshl_add_u64 v[230:231], s[48:49], 0, v[138:139]
	ds_read_b128 v[176:179], v142 offset:32768
	ds_read_b128 v[184:187], v142 offset:34816
	ds_read_b128 v[188:191], v143 offset:32768
	ds_read_b128 v[192:195], v143 offset:34816
	ds_read_b128 v[196:199], v142 offset:36864
	ds_read_b128 v[200:203], v142 offset:38912
	ds_read_b128 v[204:207], v143 offset:36864
	ds_read_b128 v[208:211], v143 offset:38912
	global_load_lds_dwordx4 v[230:231], off
	v_lshl_add_u64 v[230:231], s[48:49], 0, v[134:135]
	s_mov_b32 m0, s55
	s_nop 0
	global_load_lds_dwordx4 v[230:231], off
	s_waitcnt vmcnt(8)
	s_waitcnt lgkmcnt(0)
	s_barrier
	s_setprio 1
	s_waitcnt lgkmcnt(0)
	v_mfma_f32_16x16x32_bf16 v[128:131], v[144:147], v[176:179], v[128:131]
	v_mfma_f32_16x16x32_bf16 v[124:127], v[152:155], v[176:179], v[124:127]
	v_mfma_f32_16x16x32_bf16 v[112:115], v[144:147], v[184:187], v[112:115]
	v_mfma_f32_16x16x32_bf16 v[108:111], v[152:155], v[184:187], v[108:111]
	v_mfma_f32_16x16x32_bf16 v[96:99], v[144:147], v[196:199], v[96:99]
	v_mfma_f32_16x16x32_bf16 v[92:95], v[152:155], v[196:199], v[92:95]
	v_mfma_f32_16x16x32_bf16 v[80:83], v[144:147], v[200:203], v[80:83]
	v_mfma_f32_16x16x32_bf16 v[76:79], v[152:155], v[200:203], v[76:79]
	v_mfma_f32_16x16x32_bf16 v[128:131], v[148:151], v[188:191], v[128:131]
	v_mfma_f32_16x16x32_bf16 v[124:127], v[156:159], v[188:191], v[124:127]
	v_mfma_f32_16x16x32_bf16 v[112:115], v[148:151], v[192:195], v[112:115]
	v_mfma_f32_16x16x32_bf16 v[108:111], v[156:159], v[192:195], v[108:111]
	v_mfma_f32_16x16x32_bf16 v[96:99], v[148:151], v[204:207], v[96:99]
	v_mfma_f32_16x16x32_bf16 v[92:95], v[156:159], v[204:207], v[92:95]
	v_mfma_f32_16x16x32_bf16 v[80:83], v[148:151], v[208:211], v[80:83]
	v_mfma_f32_16x16x32_bf16 v[76:79], v[156:159], v[208:211], v[76:79]
	s_setprio 0
	s_setprio 1
	v_mfma_f32_16x16x32_bf16 v[120:123], v[160:163], v[176:179], v[120:123]
	v_mfma_f32_16x16x32_bf16 v[116:119], v[168:171], v[176:179], v[116:119]
	v_mfma_f32_16x16x32_bf16 v[104:107], v[160:163], v[184:187], v[104:107]
	v_mfma_f32_16x16x32_bf16 v[100:103], v[168:171], v[184:187], v[100:103]
	v_mfma_f32_16x16x32_bf16 v[88:91], v[160:163], v[196:199], v[88:91]
	v_mfma_f32_16x16x32_bf16 v[84:87], v[168:171], v[196:199], v[84:87]
	v_mfma_f32_16x16x32_bf16 v[72:75], v[160:163], v[200:203], v[72:75]
	v_mfma_f32_16x16x32_bf16 v[68:71], v[168:171], v[200:203], v[68:71]
	v_mfma_f32_16x16x32_bf16 v[120:123], v[164:167], v[188:191], v[120:123]
	v_mfma_f32_16x16x32_bf16 v[116:119], v[172:175], v[188:191], v[116:119]
	v_mfma_f32_16x16x32_bf16 v[104:107], v[164:167], v[192:195], v[104:107]
	v_mfma_f32_16x16x32_bf16 v[100:103], v[172:175], v[192:195], v[100:103]
	v_mfma_f32_16x16x32_bf16 v[88:91], v[164:167], v[204:207], v[88:91]
	v_mfma_f32_16x16x32_bf16 v[84:87], v[172:175], v[204:207], v[84:87]
	v_mfma_f32_16x16x32_bf16 v[72:75], v[164:167], v[208:211], v[72:75]
	v_mfma_f32_16x16x32_bf16 v[68:71], v[172:175], v[208:211], v[68:71]
	s_setprio 0
	s_barrier
	s_add_i32 s31, s31, s33
	v_lshl_add_u64 v[212:213], v[212:213], 0, s[74:75]
	s_mov_b32 m0, s31
	ds_read_b128 v[176:179], v142 offset:49152
	ds_read_b128 v[184:187], v142 offset:51200
	ds_read_b128 v[188:191], v143 offset:49152
	ds_read_b128 v[192:195], v143 offset:51200
	ds_read_b128 v[196:199], v142 offset:53248
	ds_read_b128 v[200:203], v142 offset:55296
	ds_read_b128 v[204:207], v143 offset:53248
	ds_read_b128 v[208:211], v143 offset:55296
	global_load_lds_dwordx4 v[212:213], off
	s_add_i32 m0, s31, 0x2000
	s_add_u32 s44, s44, 0x80080
	v_lshl_add_u64 v[212:213], v[224:225], 0, s[74:75]
	s_addc_u32 s45, s45, 0
	s_add_i32 s31, s47, s33
	global_load_lds_dwordx4 v[212:213], off
	v_lshl_add_u64 v[212:213], s[44:45], 0, v[136:137]
	s_mov_b32 m0, s31
	s_nop 0
	global_load_lds_dwordx4 v[212:213], off
	v_lshl_add_u64 v[212:213], s[44:45], 0, v[132:133]
	s_add_i32 m0, s31, 0x2000
	s_nop 0
	global_load_lds_dwordx4 v[212:213], off
	v_lshl_add_u64 v[212:213], v[226:227], 0, s[74:75]
	s_mov_b32 m0, s56
	s_nop 0
	global_load_lds_dwordx4 v[212:213], off
	v_lshl_add_u64 v[212:213], v[228:229], 0, s[74:75]
	s_mov_b32 m0, s57
	s_nop 0
	global_load_lds_dwordx4 v[212:213], off
	s_waitcnt vmcnt(8)
	s_waitcnt lgkmcnt(0)
	s_barrier
	s_setprio 1
	s_waitcnt lgkmcnt(0)
	v_mfma_f32_16x16x32_bf16 v[64:67], v[144:147], v[176:179], v[64:67]
	v_mfma_f32_16x16x32_bf16 v[60:63], v[152:155], v[176:179], v[60:63]
	v_mfma_f32_16x16x32_bf16 v[48:51], v[144:147], v[184:187], v[48:51]
	v_mfma_f32_16x16x32_bf16 v[44:47], v[152:155], v[184:187], v[44:47]
	v_mfma_f32_16x16x32_bf16 v[30:33], v[144:147], v[196:199], v[30:33]
	v_mfma_f32_16x16x32_bf16 v[26:29], v[152:155], v[196:199], v[26:29]
	v_mfma_f32_16x16x32_bf16 v[14:17], v[144:147], v[200:203], v[14:17]
	v_mfma_f32_16x16x32_bf16 v[10:13], v[152:155], v[200:203], v[10:13]
	v_mfma_f32_16x16x32_bf16 v[64:67], v[148:151], v[188:191], v[64:67]
	v_mfma_f32_16x16x32_bf16 v[60:63], v[156:159], v[188:191], v[60:63]
	v_mfma_f32_16x16x32_bf16 v[48:51], v[148:151], v[192:195], v[48:51]
	v_mfma_f32_16x16x32_bf16 v[44:47], v[156:159], v[192:195], v[44:47]
	v_mfma_f32_16x16x32_bf16 v[30:33], v[148:151], v[204:207], v[30:33]
	v_mfma_f32_16x16x32_bf16 v[26:29], v[156:159], v[204:207], v[26:29]
	v_mfma_f32_16x16x32_bf16 v[14:17], v[148:151], v[208:211], v[14:17]
	v_mfma_f32_16x16x32_bf16 v[10:13], v[156:159], v[208:211], v[10:13]
	s_setprio 0
	s_setprio 1
	v_mfma_f32_16x16x32_bf16 v[56:59], v[160:163], v[176:179], v[56:59]
	v_mfma_f32_16x16x32_bf16 v[52:55], v[168:171], v[176:179], v[52:55]
	v_mfma_f32_16x16x32_bf16 v[40:43], v[160:163], v[184:187], v[40:43]
	v_mfma_f32_16x16x32_bf16 v[36:39], v[168:171], v[184:187], v[36:39]
	v_mfma_f32_16x16x32_bf16 v[22:25], v[160:163], v[196:199], v[22:25]
	v_mfma_f32_16x16x32_bf16 v[18:21], v[168:171], v[196:199], v[18:21]
	v_mfma_f32_16x16x32_bf16 v[6:9], v[160:163], v[200:203], v[6:9]
	v_mfma_f32_16x16x32_bf16 v[2:5], v[168:171], v[200:203], v[2:5]
	v_mfma_f32_16x16x32_bf16 v[56:59], v[164:167], v[188:191], v[56:59]
	v_mfma_f32_16x16x32_bf16 v[52:55], v[172:175], v[188:191], v[52:55]
	v_mfma_f32_16x16x32_bf16 v[40:43], v[164:167], v[192:195], v[40:43]
	v_mfma_f32_16x16x32_bf16 v[36:39], v[172:175], v[192:195], v[36:39]
	v_mfma_f32_16x16x32_bf16 v[22:25], v[164:167], v[204:207], v[22:25]
	v_mfma_f32_16x16x32_bf16 v[18:21], v[172:175], v[204:207], v[18:21]
	v_mfma_f32_16x16x32_bf16 v[6:9], v[164:167], v[208:211], v[6:9]
	v_mfma_f32_16x16x32_bf16 v[2:5], v[172:175], v[208:211], v[2:5]
	s_setprio 0
	s_barrier
	s_add_i32 s30, s30, 2
	s_add_u32 s42, s42, 0x100
	s_addc_u32 s43, s43, 0
	s_add_u32 s23, s23, 0x100
	s_addc_u32 s25, s25, 0
	s_cmp_gt_u32 s30, 29
	s_cbranch_scc1 .Lpeel_done_P1
.LBB0_162:
	s_add_u32 s31, s42, 0xfff80080
	s_addc_u32 s44, s43, -1
	s_add_i32 s47, 0, 0x10000
	s_cmp_eq_u32 s30, 28
	s_cselect_b32 s49, s13, s44
	s_cselect_b32 s48, s20, s31
	ds_read_b128 v[144:147], v1
	ds_read_b128 v[148:151], v141
	s_cselect_b32 s45, s19, s25
	s_cselect_b32 s44, s21, s23
	s_add_i32 s31, 0, 0x14000
	ds_read_b128 v[152:155], v1 offset:2048
	ds_read_b128 v[156:159], v141 offset:2048
	ds_read_b128 v[160:163], v1 offset:16384
	ds_read_b128 v[164:167], v141 offset:16384
	ds_read_b128 v[168:171], v1 offset:18432
	ds_read_b128 v[172:175], v141 offset:18432
	v_lshl_add_u64 v[212:213], s[42:43], 0, v[138:139]
	s_add_i32 m0, s34, 0xc000
	ds_read_b128 v[176:179], v142
	ds_read_b128 v[184:187], v142 offset:2048
	ds_read_b128 v[188:191], v143
	ds_read_b128 v[192:195], v143 offset:2048
	ds_read_b128 v[196:199], v142 offset:4096
	ds_read_b128 v[200:203], v142 offset:6144
	ds_read_b128 v[204:207], v143 offset:4096
	ds_read_b128 v[208:211], v143 offset:6144
	global_load_lds_dwordx4 v[212:213], off
	v_lshl_add_u64 v[212:213], s[42:43], 0, v[134:135]
	s_add_i32 m0, s34, 0xe000
	s_nop 0
	global_load_lds_dwordx4 v[212:213], off
	s_waitcnt vmcnt(8)
	s_waitcnt lgkmcnt(0)
	s_barrier
	s_setprio 1
	s_waitcnt lgkmcnt(0)
	v_mfma_f32_16x16x32_bf16 v[128:131], v[144:147], v[176:179], v[128:131]
	v_mfma_f32_16x16x32_bf16 v[124:127], v[152:155], v[176:179], v[124:127]
	v_mfma_f32_16x16x32_bf16 v[112:115], v[144:147], v[184:187], v[112:115]
	v_mfma_f32_16x16x32_bf16 v[108:111], v[152:155], v[184:187], v[108:111]
	v_mfma_f32_16x16x32_bf16 v[96:99], v[144:147], v[196:199], v[96:99]
	v_mfma_f32_16x16x32_bf16 v[92:95], v[152:155], v[196:199], v[92:95]
	v_mfma_f32_16x16x32_bf16 v[80:83], v[144:147], v[200:203], v[80:83]
	v_mfma_f32_16x16x32_bf16 v[76:79], v[152:155], v[200:203], v[76:79]
	v_mfma_f32_16x16x32_bf16 v[128:131], v[148:151], v[188:191], v[128:131]
	v_mfma_f32_16x16x32_bf16 v[124:127], v[156:159], v[188:191], v[124:127]
	v_mfma_f32_16x16x32_bf16 v[112:115], v[148:151], v[192:195], v[112:115]
	v_mfma_f32_16x16x32_bf16 v[108:111], v[156:159], v[192:195], v[108:111]
	v_mfma_f32_16x16x32_bf16 v[96:99], v[148:151], v[204:207], v[96:99]
	v_mfma_f32_16x16x32_bf16 v[92:95], v[156:159], v[204:207], v[92:95]
	v_mfma_f32_16x16x32_bf16 v[80:83], v[148:151], v[208:211], v[80:83]
	v_mfma_f32_16x16x32_bf16 v[76:79], v[156:159], v[208:211], v[76:79]
	s_setprio 0
	s_setprio 1
	v_mfma_f32_16x16x32_bf16 v[120:123], v[160:163], v[176:179], v[120:123]
	v_mfma_f32_16x16x32_bf16 v[116:119], v[168:171], v[176:179], v[116:119]
	v_mfma_f32_16x16x32_bf16 v[104:107], v[160:163], v[184:187], v[104:107]
	v_mfma_f32_16x16x32_bf16 v[100:103], v[168:171], v[184:187], v[100:103]
	v_mfma_f32_16x16x32_bf16 v[88:91], v[160:163], v[196:199], v[88:91]
	v_mfma_f32_16x16x32_bf16 v[84:87], v[168:171], v[196:199], v[84:87]
	v_mfma_f32_16x16x32_bf16 v[72:75], v[160:163], v[200:203], v[72:75]
	v_mfma_f32_16x16x32_bf16 v[68:71], v[168:171], v[200:203], v[68:71]
	v_mfma_f32_16x16x32_bf16 v[120:123], v[164:167], v[188:191], v[120:123]
	v_mfma_f32_16x16x32_bf16 v[116:119], v[172:175], v[188:191], v[116:119]
	v_mfma_f32_16x16x32_bf16 v[104:107], v[164:167], v[192:195], v[104:107]
	v_mfma_f32_16x16x32_bf16 v[100:103], v[172:175], v[192:195], v[100:103]
	v_mfma_f32_16x16x32_bf16 v[88:91], v[164:167], v[204:207], v[88:91]
	v_mfma_f32_16x16x32_bf16 v[84:87], v[172:175], v[204:207], v[84:87]
	v_mfma_f32_16x16x32_bf16 v[72:75], v[164:167], v[208:211], v[72:75]
	v_mfma_f32_16x16x32_bf16 v[68:71], v[172:175], v[208:211], v[68:71]
	s_setprio 0
	s_barrier
	s_add_i32 s47, s47, s33
	v_lshl_add_u64 v[212:213], s[44:45], 0, v[136:137]
	s_mov_b32 m0, s47
	ds_read_b128 v[176:179], v142 offset:16384
	ds_read_b128 v[184:187], v142 offset:18432
	ds_read_b128 v[188:191], v143 offset:16384
	ds_read_b128 v[192:195], v143 offset:18432
	ds_read_b128 v[196:199], v142 offset:20480
	ds_read_b128 v[200:203], v142 offset:22528
	ds_read_b128 v[204:207], v143 offset:20480
	ds_read_b128 v[208:211], v143 offset:22528
	global_load_lds_dwordx4 v[212:213], off
	s_add_i32 m0, s47, 0x2000
	s_add_u32 s50, s44, 0x80000
	v_lshl_add_u64 v[224:225], s[44:45], 0, v[132:133]
	s_addc_u32 s51, s45, 0
	s_add_i32 s31, s31, s33
	global_load_lds_dwordx4 v[224:225], off
	v_lshl_add_u64 v[226:227], s[50:51], 0, v[136:137]
	s_mov_b32 m0, s31
	v_lshl_add_u64 v[228:229], s[48:49], 0, v[134:135]
	global_load_lds_dwordx4 v[226:227], off
	v_lshl_add_u64 v[226:227], s[50:51], 0, v[132:133]
	s_add_i32 m0, s31, 0x2000
	s_nop 0
	global_load_lds_dwordx4 v[226:227], off
	v_lshl_add_u64 v[226:227], s[48:49], 0, v[138:139]
	s_mov_b32 m0, s34
	s_nop 0
	global_load_lds_dwordx4 v[226:227], off
	s_mov_b32 m0, s35
	s_nop 0
	global_load_lds_dwordx4 v[228:229], off
	s_waitcnt vmcnt(8)
	s_waitcnt lgkmcnt(0)
	s_barrier
	s_setprio 1
	s_waitcnt lgkmcnt(0)
	v_mfma_f32_16x16x32_bf16 v[64:67], v[144:147], v[176:179], v[64:67]
	v_mfma_f32_16x16x32_bf16 v[60:63], v[152:155], v[176:179], v[60:63]
	v_mfma_f32_16x16x32_bf16 v[48:51], v[144:147], v[184:187], v[48:51]
	v_mfma_f32_16x16x32_bf16 v[44:47], v[152:155], v[184:187], v[44:47]
	v_mfma_f32_16x16x32_bf16 v[30:33], v[144:147], v[196:199], v[30:33]
	v_mfma_f32_16x16x32_bf16 v[26:29], v[152:155], v[196:199], v[26:29]
	v_mfma_f32_16x16x32_bf16 v[14:17], v[144:147], v[200:203], v[14:17]
	v_mfma_f32_16x16x32_bf16 v[10:13], v[152:155], v[200:203], v[10:13]
	v_mfma_f32_16x16x32_bf16 v[64:67], v[148:151], v[188:191], v[64:67]
	v_mfma_f32_16x16x32_bf16 v[60:63], v[156:159], v[188:191], v[60:63]
	v_mfma_f32_16x16x32_bf16 v[48:51], v[148:151], v[192:195], v[48:51]
	v_mfma_f32_16x16x32_bf16 v[44:47], v[156:159], v[192:195], v[44:47]
	v_mfma_f32_16x16x32_bf16 v[30:33], v[148:151], v[204:207], v[30:33]
	v_mfma_f32_16x16x32_bf16 v[26:29], v[156:159], v[204:207], v[26:29]
	v_mfma_f32_16x16x32_bf16 v[14:17], v[148:151], v[208:211], v[14:17]
	v_mfma_f32_16x16x32_bf16 v[10:13], v[156:159], v[208:211], v[10:13]
	s_setprio 0
	s_setprio 1
	v_mfma_f32_16x16x32_bf16 v[56:59], v[160:163], v[176:179], v[56:59]
	v_mfma_f32_16x16x32_bf16 v[52:55], v[168:171], v[176:179], v[52:55]
	v_mfma_f32_16x16x32_bf16 v[40:43], v[160:163], v[184:187], v[40:43]
	v_mfma_f32_16x16x32_bf16 v[36:39], v[168:171], v[184:187], v[36:39]
	v_mfma_f32_16x16x32_bf16 v[22:25], v[160:163], v[196:199], v[22:25]
	v_mfma_f32_16x16x32_bf16 v[18:21], v[168:171], v[196:199], v[18:21]
	v_mfma_f32_16x16x32_bf16 v[6:9], v[160:163], v[200:203], v[6:9]
	v_mfma_f32_16x16x32_bf16 v[2:5], v[168:171], v[200:203], v[2:5]
	v_mfma_f32_16x16x32_bf16 v[56:59], v[164:167], v[188:191], v[56:59]
	v_mfma_f32_16x16x32_bf16 v[52:55], v[172:175], v[188:191], v[52:55]
	v_mfma_f32_16x16x32_bf16 v[40:43], v[164:167], v[192:195], v[40:43]
	v_mfma_f32_16x16x32_bf16 v[36:39], v[172:175], v[192:195], v[36:39]
	v_mfma_f32_16x16x32_bf16 v[22:25], v[164:167], v[204:207], v[22:25]
	v_mfma_f32_16x16x32_bf16 v[18:21], v[172:175], v[204:207], v[18:21]
	v_mfma_f32_16x16x32_bf16 v[6:9], v[164:167], v[208:211], v[6:9]
	v_mfma_f32_16x16x32_bf16 v[2:5], v[172:175], v[208:211], v[2:5]
	s_setprio 0
	s_barrier
	s_add_i32 s31, 0, 0x18000
	ds_read_b128 v[144:147], v1 offset:32768
	ds_read_b128 v[148:151], v141 offset:32768
	s_add_i32 s47, 0, 0x1c000
	ds_read_b128 v[152:155], v1 offset:34816
	ds_read_b128 v[156:159], v141 offset:34816
	ds_read_b128 v[160:163], v1 offset:49152
	ds_read_b128 v[164:167], v141 offset:49152
	ds_read_b128 v[168:171], v1 offset:51200
	ds_read_b128 v[172:175], v141 offset:51200
	s_add_u32 s48, s48, 0x80000
	s_addc_u32 s49, s49, 0
	s_mov_b32 m0, s54
	v_lshl_add_u64 v[230:231], s[48:49], 0, v[138:139]
	ds_read_b128 v[176:179], v142 offset:32768
	ds_read_b128 v[184:187], v142 offset:34816
	ds_read_b128 v[188:191], v143 offset:32768
	ds_read_b128 v[192:195], v143 offset:34816
	ds_read_b128 v[196:199], v142 offset:36864
	ds_read_b128 v[200:203], v142 offset:38912
	ds_read_b128 v[204:207], v143 offset:36864
	ds_read_b128 v[208:211], v143 offset:38912
	global_load_lds_dwordx4 v[230:231], off
	v_lshl_add_u64 v[230:231], s[48:49], 0, v[134:135]
	s_mov_b32 m0, s55
	s_nop 0
	global_load_lds_dwordx4 v[230:231], off
	s_waitcnt vmcnt(8)
	s_waitcnt lgkmcnt(0)
	s_barrier
	s_setprio 1
	s_waitcnt lgkmcnt(0)
	v_mfma_f32_16x16x32_bf16 v[128:131], v[144:147], v[176:179], v[128:131]
	v_mfma_f32_16x16x32_bf16 v[124:127], v[152:155], v[176:179], v[124:127]
	v_mfma_f32_16x16x32_bf16 v[112:115], v[144:147], v[184:187], v[112:115]
	v_mfma_f32_16x16x32_bf16 v[108:111], v[152:155], v[184:187], v[108:111]
	v_mfma_f32_16x16x32_bf16 v[96:99], v[144:147], v[196:199], v[96:99]
	v_mfma_f32_16x16x32_bf16 v[92:95], v[152:155], v[196:199], v[92:95]
	v_mfma_f32_16x16x32_bf16 v[80:83], v[144:147], v[200:203], v[80:83]
	v_mfma_f32_16x16x32_bf16 v[76:79], v[152:155], v[200:203], v[76:79]
	v_mfma_f32_16x16x32_bf16 v[128:131], v[148:151], v[188:191], v[128:131]
	v_mfma_f32_16x16x32_bf16 v[124:127], v[156:159], v[188:191], v[124:127]
	v_mfma_f32_16x16x32_bf16 v[112:115], v[148:151], v[192:195], v[112:115]
	v_mfma_f32_16x16x32_bf16 v[108:111], v[156:159], v[192:195], v[108:111]
	v_mfma_f32_16x16x32_bf16 v[96:99], v[148:151], v[204:207], v[96:99]
	v_mfma_f32_16x16x32_bf16 v[92:95], v[156:159], v[204:207], v[92:95]
	v_mfma_f32_16x16x32_bf16 v[80:83], v[148:151], v[208:211], v[80:83]
	v_mfma_f32_16x16x32_bf16 v[76:79], v[156:159], v[208:211], v[76:79]
	s_setprio 0
	s_setprio 1
	v_mfma_f32_16x16x32_bf16 v[120:123], v[160:163], v[176:179], v[120:123]
	v_mfma_f32_16x16x32_bf16 v[116:119], v[168:171], v[176:179], v[116:119]
	v_mfma_f32_16x16x32_bf16 v[104:107], v[160:163], v[184:187], v[104:107]
	v_mfma_f32_16x16x32_bf16 v[100:103], v[168:171], v[184:187], v[100:103]
	v_mfma_f32_16x16x32_bf16 v[88:91], v[160:163], v[196:199], v[88:91]
	v_mfma_f32_16x16x32_bf16 v[84:87], v[168:171], v[196:199], v[84:87]
	v_mfma_f32_16x16x32_bf16 v[72:75], v[160:163], v[200:203], v[72:75]
	v_mfma_f32_16x16x32_bf16 v[68:71], v[168:171], v[200:203], v[68:71]
	v_mfma_f32_16x16x32_bf16 v[120:123], v[164:167], v[188:191], v[120:123]
	v_mfma_f32_16x16x32_bf16 v[116:119], v[172:175], v[188:191], v[116:119]
	v_mfma_f32_16x16x32_bf16 v[104:107], v[164:167], v[192:195], v[104:107]
	v_mfma_f32_16x16x32_bf16 v[100:103], v[172:175], v[192:195], v[100:103]
	v_mfma_f32_16x16x32_bf16 v[88:91], v[164:167], v[204:207], v[88:91]
	v_mfma_f32_16x16x32_bf16 v[84:87], v[172:175], v[204:207], v[84:87]
	v_mfma_f32_16x16x32_bf16 v[72:75], v[164:167], v[208:211], v[72:75]
	v_mfma_f32_16x16x32_bf16 v[68:71], v[172:175], v[208:211], v[68:71]
	s_setprio 0
	s_barrier
	s_add_i32 s31, s31, s33
	v_lshl_add_u64 v[212:213], v[212:213], 0, s[74:75]
	s_mov_b32 m0, s31
	ds_read_b128 v[176:179], v142 offset:49152
	ds_read_b128 v[184:187], v142 offset:51200
	ds_read_b128 v[188:191], v143 offset:49152
	ds_read_b128 v[192:195], v143 offset:51200
	ds_read_b128 v[196:199], v142 offset:53248
	ds_read_b128 v[200:203], v142 offset:55296
	ds_read_b128 v[204:207], v143 offset:53248
	ds_read_b128 v[208:211], v143 offset:55296
	global_load_lds_dwordx4 v[212:213], off
	s_add_i32 m0, s31, 0x2000
	s_add_u32 s44, s44, 0x80080
	v_lshl_add_u64 v[212:213], v[224:225], 0, s[74:75]
	s_addc_u32 s45, s45, 0
	s_add_i32 s31, s47, s33
	global_load_lds_dwordx4 v[212:213], off
	v_lshl_add_u64 v[212:213], s[44:45], 0, v[136:137]
	s_mov_b32 m0, s31
	s_nop 0
	global_load_lds_dwordx4 v[212:213], off
	v_lshl_add_u64 v[212:213], s[44:45], 0, v[132:133]
	s_add_i32 m0, s31, 0x2000
	s_nop 0
	global_load_lds_dwordx4 v[212:213], off
	v_lshl_add_u64 v[212:213], v[226:227], 0, s[74:75]
	s_mov_b32 m0, s56
	s_nop 0
	global_load_lds_dwordx4 v[212:213], off
	v_lshl_add_u64 v[212:213], v[228:229], 0, s[74:75]
	s_mov_b32 m0, s57
	s_nop 0
	global_load_lds_dwordx4 v[212:213], off
	s_waitcnt vmcnt(8)
	s_waitcnt lgkmcnt(0)
	s_barrier
	s_setprio 1
	s_waitcnt lgkmcnt(0)
	v_mfma_f32_16x16x32_bf16 v[64:67], v[144:147], v[176:179], v[64:67]
	v_mfma_f32_16x16x32_bf16 v[60:63], v[152:155], v[176:179], v[60:63]
	v_mfma_f32_16x16x32_bf16 v[48:51], v[144:147], v[184:187], v[48:51]
	v_mfma_f32_16x16x32_bf16 v[44:47], v[152:155], v[184:187], v[44:47]
	v_mfma_f32_16x16x32_bf16 v[30:33], v[144:147], v[196:199], v[30:33]
	v_mfma_f32_16x16x32_bf16 v[26:29], v[152:155], v[196:199], v[26:29]
	v_mfma_f32_16x16x32_bf16 v[14:17], v[144:147], v[200:203], v[14:17]
	v_mfma_f32_16x16x32_bf16 v[10:13], v[152:155], v[200:203], v[10:13]
	v_mfma_f32_16x16x32_bf16 v[64:67], v[148:151], v[188:191], v[64:67]
	v_mfma_f32_16x16x32_bf16 v[60:63], v[156:159], v[188:191], v[60:63]
	v_mfma_f32_16x16x32_bf16 v[48:51], v[148:151], v[192:195], v[48:51]
	v_mfma_f32_16x16x32_bf16 v[44:47], v[156:159], v[192:195], v[44:47]
	v_mfma_f32_16x16x32_bf16 v[30:33], v[148:151], v[204:207], v[30:33]
	v_mfma_f32_16x16x32_bf16 v[26:29], v[156:159], v[204:207], v[26:29]
	v_mfma_f32_16x16x32_bf16 v[14:17], v[148:151], v[208:211], v[14:17]
	v_mfma_f32_16x16x32_bf16 v[10:13], v[156:159], v[208:211], v[10:13]
	s_setprio 0
	s_setprio 1
	v_mfma_f32_16x16x32_bf16 v[56:59], v[160:163], v[176:179], v[56:59]
	v_mfma_f32_16x16x32_bf16 v[52:55], v[168:171], v[176:179], v[52:55]
	v_mfma_f32_16x16x32_bf16 v[40:43], v[160:163], v[184:187], v[40:43]
	v_mfma_f32_16x16x32_bf16 v[36:39], v[168:171], v[184:187], v[36:39]
	v_mfma_f32_16x16x32_bf16 v[22:25], v[160:163], v[196:199], v[22:25]
	v_mfma_f32_16x16x32_bf16 v[18:21], v[168:171], v[196:199], v[18:21]
	v_mfma_f32_16x16x32_bf16 v[6:9], v[160:163], v[200:203], v[6:9]
	v_mfma_f32_16x16x32_bf16 v[2:5], v[168:171], v[200:203], v[2:5]
	v_mfma_f32_16x16x32_bf16 v[56:59], v[164:167], v[188:191], v[56:59]
	v_mfma_f32_16x16x32_bf16 v[52:55], v[172:175], v[188:191], v[52:55]
	v_mfma_f32_16x16x32_bf16 v[40:43], v[164:167], v[192:195], v[40:43]
	v_mfma_f32_16x16x32_bf16 v[36:39], v[172:175], v[192:195], v[36:39]
	v_mfma_f32_16x16x32_bf16 v[22:25], v[164:167], v[204:207], v[22:25]
	v_mfma_f32_16x16x32_bf16 v[18:21], v[172:175], v[204:207], v[18:21]
	v_mfma_f32_16x16x32_bf16 v[6:9], v[164:167], v[208:211], v[6:9]
	v_mfma_f32_16x16x32_bf16 v[2:5], v[172:175], v[208:211], v[2:5]
	s_setprio 0
	s_barrier
	s_add_i32 s30, s30, 2
	s_add_u32 s42, s42, 0x100
	s_addc_u32 s43, s43, 0
	s_add_u32 s23, s23, 0x100
	s_addc_u32 s25, s25, 0
	s_cmp_gt_u32 s30, 29
	s_cbranch_scc0 .LBB0_162

.LBB0_890:
	v_readlane_b32 s28, v254, 44
	v_readlane_b32 s29, v254, 45
	v_mov_b32_e32 v185, v35
	v_readlane_b32 s22, v254, 40
	v_lshl_add_u64 v[2:3], s[28:29], 0, v[34:35]
	v_lshl_add_u64 v[4:5], s[28:29], 0, v[184:185]
	v_mov_b32_e32 v189, v35
	v_readlane_b32 s23, v254, 41
	s_add_i32 m0, s50, 0x18000
	v_lshl_add_u64 v[2:3], v[2:3], 0, s[10:11]
	v_lshl_add_u64 v[6:7], s[22:23], 0, v[188:189]
	v_mov_b32_e32 v187, v35
	s_waitcnt vmcnt(2)
	s_barrier
	global_load_lds_dwordx4 v[2:3], off
	v_lshl_add_u64 v[2:3], v[4:5], 0, s[10:11]
	s_add_i32 m0, s50, 0x1a000
	s_add_i32 s54, s50, 0x8000
	v_lshl_add_u64 v[8:9], s[22:23], 0, v[186:187]
	global_load_lds_dwordx4 v[2:3], off
	v_lshl_add_u64 v[2:3], v[6:7], 0, s[10:11]
	s_mov_b32 m0, s54
	s_add_i32 s55, s50, 0xa000
	global_load_lds_dwordx4 v[2:3], off
	v_lshl_add_u64 v[2:3], v[8:9], 0, s[10:11]
	v_readlane_b32 s10, v254, 46
	s_mov_b32 m0, s55
	v_readlane_b32 s11, v254, 47
	global_load_lds_dwordx4 v[2:3], off
	s_add_i32 m0, s50, 0x1c000
	v_lshl_add_u64 v[2:3], s[10:11], 0, v[34:35]
	global_load_lds_dwordx4 v[2:3], off
	v_lshl_add_u64 v[2:3], s[10:11], 0, v[184:185]
	s_add_i32 m0, s50, 0x1e000
	s_and_b32 s9, s6, 3
	global_load_lds_dwordx4 v[2:3], off
	v_and_b32_e32 v2, 15, v1
	v_lshlrev_b32_e32 v4, 3, v1
	v_and_b32_e32 v1, 48, v1
	s_movk_i32 s6, 0x70
	v_and_b32_e32 v5, 0x70, v4
	v_bitop3_b32 v4, v4, v1, s6 bitop3:0x6c
	s_lshl_b32 s6, s7, 2
	s_lshl_b32 s56, s7, 6
	s_lshl_b32 s57, s9, 5
	s_or_b32 s18, s6, s9
	s_cmp_lt_i32 s18, 4
	s_cselect_b64 s[6:7], -1, 0
	s_lshl_b32 s12, s18, 6
	s_ashr_i32 s13, s12, 31
	s_cmpk_lt_u32 s8, 0x100
	s_cselect_b64 s[10:11], -1, 0
	s_and_b32 s19, s8, 0xffffff00
	s_lshl_b32 s8, s9, 6
	s_or_b32 s58, s8, s19
	s_lshl_b64 s[8:9], s[12:13], 2
	s_add_u32 s59, s76, s8
	v_or_b32_e32 v3, s56, v2
	v_or_b32_e32 v2, s57, v2
	s_addc_u32 s60, s77, s9
	s_lshl_b32 s8, s18, 8
	v_readlane_b32 s9, v255, 19
	v_lshlrev_b32_e32 v3, 7, v3
	v_lshlrev_b32_e32 v2, 7, v2
	s_waitcnt vmcnt(6)
	s_add_i32 s61, s9, s8
	s_add_i32 s62, s9, s19
	v_readlane_b32 s8, v255, 3
	v_bitop3_b32 v6, v3, v5, v1 bitop3:0xf6
	v_bitop3_b32 v1, v2, v5, v1 bitop3:0xf6
	v_bitop3_b32 v204, v2, 64, v4 bitop3:0x36
	v_add_u32_e32 v1, 0x10000, v1
	v_add_u32_e32 v204, 0x10000, v204
	v_bitop3_b32 v2, v3, 64, v4 bitop3:0x36
	v_readlane_b32 s9, v255, 4
	s_mov_b32 s12, 0
	v_mov_b32_e32 v231, 0
	v_mov_b32_e32 v230, 0
	v_mov_b32_e32 v229, 0
	v_mov_b32_e32 v228, 0
	v_mov_b32_e32 v227, 0
	v_mov_b32_e32 v226, 0
	v_mov_b32_e32 v225, 0
	v_mov_b32_e32 v224, 0
	v_mov_b32_e32 v223, 0
	v_mov_b32_e32 v213, 0
	v_mov_b32_e32 v212, 0
	v_mov_b32_e32 v211, 0
	v_mov_b32_e32 v210, 0
	v_mov_b32_e32 v209, 0
	v_mov_b32_e32 v208, 0
	v_mov_b32_e32 v207, 0
	v_add_u32_e32 v205, 0, v6
	v_add_u32_e32 v206, 0, v2
	v_readlane_b32 s13, v254, 62
	s_mov_b32 s63, 0
	s_mov_b32 s9, 0
	s_barrier
	s_branch .LBB0_893

.LBB0_907:
	s_and_b32 s9, 1, s12
	s_cmp_gt_i32 s12, 1
	s_cselect_b32 s24, 10, 12
	s_cmp_eq_u32 s9, 1
	s_cselect_b64 s[18:19], -1, 0
	s_and_b64 s[20:21], s[18:19], exec
	s_cselect_b32 s9, s24, 32
	s_add_i32 s20, s9, -2
	s_add_u32 s22, s22, 0x80080
	s_addc_u32 s23, s23, 0
	s_add_u32 s21, s28, 0x100
	s_addc_u32 s24, s29, 0
	s_mov_b32 s25, 0
	s_waitcnt vmcnt(0)
	v_readlane_b32 s43, v255, 20
	v_readlane_b32 s45, v255, 21
	v_readlane_b32 s66, v255, 22
	v_readlane_b32 s67, v255, 23
	s_mov_b64 s[68:69], 0x80
	s_add_i32 s30, s25, 2
	s_add_u32 s28, s22, 0xfff80080
	s_addc_u32 s29, s23, -1
	s_add_i32 s31, 0, 0x10000
	s_cmp_eq_u32 s20, s25
	s_cselect_b32 s41, s47, s29
	s_cselect_b32 s40, s46, s28
	s_cselect_b32 s29, s49, s24
	s_cselect_b32 s28, s48, s21
	s_add_i32 s25, 0, 0x14000
	ds_read_b128 v[132:135], v1
	ds_read_b128 v[136:139], v204
	ds_read_b128 v[140:143], v1 offset:2048
	ds_read_b128 v[144:147], v204 offset:2048
	ds_read_b128 v[148:151], v1 offset:16384
	ds_read_b128 v[152:155], v204 offset:16384
	ds_read_b128 v[156:159], v1 offset:18432
	ds_read_b128 v[160:163], v204 offset:18432
	v_lshl_add_u64 v[180:181], s[22:23], 0, v[188:189]
	s_add_i32 m0, s50, 0xc000
	ds_read_b128 v[164:167], v205
	ds_read_b128 v[168:171], v205 offset:2048
	ds_read_b128 v[172:175], v206
	ds_read_b128 v[176:179], v206 offset:2048
	ds_read_b128 v[190:193], v205 offset:4096
	ds_read_b128 v[194:197], v205 offset:6144
	ds_read_b128 v[198:201], v206 offset:4096
	ds_read_b128 v[232:235], v206 offset:6144
	global_load_lds_dwordx4 v[180:181], off
	v_lshl_add_u64 v[180:181], s[22:23], 0, v[186:187]
	s_add_i32 m0, s50, 0xe000
	s_nop 0
	global_load_lds_dwordx4 v[180:181], off
	s_waitcnt vmcnt(8)
	s_waitcnt lgkmcnt(0)
	s_barrier
	s_setprio 1
	s_waitcnt lgkmcnt(0)
	v_mfma_f32_16x16x32_bf16 v[68:71], v[132:135], v[164:167], 0
	v_mfma_f32_16x16x32_bf16 v[72:75], v[140:143], v[164:167], 0
	v_mfma_f32_16x16x32_bf16 v[84:87], v[132:135], v[168:171], 0
	v_mfma_f32_16x16x32_bf16 v[88:91], v[140:143], v[168:171], 0
	v_mfma_f32_16x16x32_bf16 v[100:103], v[132:135], v[190:193], 0
	v_mfma_f32_16x16x32_bf16 v[104:107], v[140:143], v[190:193], 0
	v_mfma_f32_16x16x32_bf16 v[116:119], v[132:135], v[194:197], 0
	v_mfma_f32_16x16x32_bf16 v[120:123], v[140:143], v[194:197], 0
	v_mfma_f32_16x16x32_bf16 v[68:71], v[136:139], v[172:175], v[68:71]
	v_mfma_f32_16x16x32_bf16 v[72:75], v[144:147], v[172:175], v[72:75]
	v_mfma_f32_16x16x32_bf16 v[84:87], v[136:139], v[176:179], v[84:87]
	v_mfma_f32_16x16x32_bf16 v[88:91], v[144:147], v[176:179], v[88:91]
	v_mfma_f32_16x16x32_bf16 v[100:103], v[136:139], v[198:201], v[100:103]
	v_mfma_f32_16x16x32_bf16 v[104:107], v[144:147], v[198:201], v[104:107]
	v_mfma_f32_16x16x32_bf16 v[116:119], v[136:139], v[232:235], v[116:119]
	v_mfma_f32_16x16x32_bf16 v[120:123], v[144:147], v[232:235], v[120:123]
	s_setprio 0
	s_setprio 1
	v_mfma_f32_16x16x32_bf16 v[76:79], v[148:151], v[164:167], 0
	v_mfma_f32_16x16x32_bf16 v[80:83], v[156:159], v[164:167], 0
	v_mfma_f32_16x16x32_bf16 v[92:95], v[148:151], v[168:171], 0
	v_mfma_f32_16x16x32_bf16 v[96:99], v[156:159], v[168:171], 0
	v_mfma_f32_16x16x32_bf16 v[108:111], v[148:151], v[190:193], 0
	v_mfma_f32_16x16x32_bf16 v[112:115], v[156:159], v[190:193], 0
	v_mfma_f32_16x16x32_bf16 v[124:127], v[148:151], v[194:197], 0
	v_mfma_f32_16x16x32_bf16 v[128:131], v[156:159], v[194:197], 0
	v_mfma_f32_16x16x32_bf16 v[76:79], v[152:155], v[172:175], v[76:79]
	v_mfma_f32_16x16x32_bf16 v[80:83], v[160:163], v[172:175], v[80:83]
	v_mfma_f32_16x16x32_bf16 v[92:95], v[152:155], v[176:179], v[92:95]
	v_mfma_f32_16x16x32_bf16 v[96:99], v[160:163], v[176:179], v[96:99]
	v_mfma_f32_16x16x32_bf16 v[108:111], v[152:155], v[198:201], v[108:111]
	v_mfma_f32_16x16x32_bf16 v[112:115], v[160:163], v[198:201], v[112:115]
	v_mfma_f32_16x16x32_bf16 v[124:127], v[152:155], v[232:235], v[124:127]
	v_mfma_f32_16x16x32_bf16 v[128:131], v[160:163], v[232:235], v[128:131]
	s_setprio 0
	s_barrier
	s_add_i32 s31, s31, s33
	v_lshl_add_u64 v[180:181], s[28:29], 0, v[34:35]
	s_mov_b32 m0, s31
	ds_read_b128 v[164:167], v205 offset:16384
	ds_read_b128 v[168:171], v205 offset:18432
	ds_read_b128 v[172:175], v206 offset:16384
	ds_read_b128 v[176:179], v206 offset:18432
	ds_read_b128 v[190:193], v205 offset:20480
	ds_read_b128 v[194:197], v205 offset:22528
	ds_read_b128 v[198:201], v206 offset:20480
	ds_read_b128 v[232:235], v206 offset:22528
	global_load_lds_dwordx4 v[180:181], off
	s_add_i32 m0, s31, 0x2000
	s_add_u32 s34, s28, 0x80000
	v_lshl_add_u64 v[182:183], s[28:29], 0, v[184:185]
	s_addc_u32 s35, s29, 0
	s_add_i32 s25, s25, s33
	global_load_lds_dwordx4 v[182:183], off
	v_lshl_add_u64 v[202:203], s[34:35], 0, v[34:35]
	s_mov_b32 m0, s25
	v_lshl_add_u64 v[218:219], s[40:41], 0, v[186:187]
	global_load_lds_dwordx4 v[202:203], off
	v_lshl_add_u64 v[202:203], s[34:35], 0, v[184:185]
	s_add_i32 m0, s25, 0x2000
	s_nop 0
	global_load_lds_dwordx4 v[202:203], off
	v_lshl_add_u64 v[202:203], s[40:41], 0, v[188:189]
	s_mov_b32 m0, s50
	s_nop 0
	global_load_lds_dwordx4 v[202:203], off
	s_mov_b32 m0, s51
	s_nop 0
	global_load_lds_dwordx4 v[218:219], off
	s_waitcnt vmcnt(8)
	s_waitcnt lgkmcnt(0)
	s_barrier
	s_setprio 1
	s_waitcnt lgkmcnt(0)
	v_mfma_f32_16x16x32_bf16 v[2:5], v[132:135], v[164:167], 0
	v_mfma_f32_16x16x32_bf16 v[6:9], v[140:143], v[164:167], 0
	v_mfma_f32_16x16x32_bf16 v[18:21], v[132:135], v[168:171], 0
	v_mfma_f32_16x16x32_bf16 v[22:25], v[140:143], v[168:171], 0
	v_mfma_f32_16x16x32_bf16 v[36:39], v[132:135], v[190:193], 0
	v_mfma_f32_16x16x32_bf16 v[40:43], v[140:143], v[190:193], 0
	v_mfma_f32_16x16x32_bf16 v[52:55], v[132:135], v[194:197], 0
	v_mfma_f32_16x16x32_bf16 v[56:59], v[140:143], v[194:197], 0
	v_mfma_f32_16x16x32_bf16 v[2:5], v[136:139], v[172:175], v[2:5]
	v_mfma_f32_16x16x32_bf16 v[6:9], v[144:147], v[172:175], v[6:9]
	v_mfma_f32_16x16x32_bf16 v[18:21], v[136:139], v[176:179], v[18:21]
	v_mfma_f32_16x16x32_bf16 v[22:25], v[144:147], v[176:179], v[22:25]
	v_mfma_f32_16x16x32_bf16 v[36:39], v[136:139], v[198:201], v[36:39]
	v_mfma_f32_16x16x32_bf16 v[40:43], v[144:147], v[198:201], v[40:43]
	v_mfma_f32_16x16x32_bf16 v[52:55], v[136:139], v[232:235], v[52:55]
	v_mfma_f32_16x16x32_bf16 v[56:59], v[144:147], v[232:235], v[56:59]
	s_setprio 0
	s_setprio 1
	v_mfma_f32_16x16x32_bf16 v[10:13], v[148:151], v[164:167], 0
	v_mfma_f32_16x16x32_bf16 v[14:17], v[156:159], v[164:167], 0
	v_mfma_f32_16x16x32_bf16 v[26:29], v[148:151], v[168:171], 0
	v_mfma_f32_16x16x32_bf16 v[30:33], v[156:159], v[168:171], 0
	v_mfma_f32_16x16x32_bf16 v[44:47], v[148:151], v[190:193], 0
	v_mfma_f32_16x16x32_bf16 v[48:51], v[156:159], v[190:193], 0
	v_mfma_f32_16x16x32_bf16 v[60:63], v[148:151], v[194:197], 0
	v_mfma_f32_16x16x32_bf16 v[64:67], v[156:159], v[194:197], 0
	v_mfma_f32_16x16x32_bf16 v[10:13], v[152:155], v[172:175], v[10:13]
	v_mfma_f32_16x16x32_bf16 v[14:17], v[160:163], v[172:175], v[14:17]
	v_mfma_f32_16x16x32_bf16 v[26:29], v[152:155], v[176:179], v[26:29]
	v_mfma_f32_16x16x32_bf16 v[30:33], v[160:163], v[176:179], v[30:33]
	v_mfma_f32_16x16x32_bf16 v[44:47], v[152:155], v[198:201], v[44:47]
	v_mfma_f32_16x16x32_bf16 v[48:51], v[160:163], v[198:201], v[48:51]
	v_mfma_f32_16x16x32_bf16 v[60:63], v[152:155], v[232:235], v[60:63]
	v_mfma_f32_16x16x32_bf16 v[64:67], v[160:163], v[232:235], v[64:67]
	s_setprio 0
	s_barrier
	s_add_i32 s25, 0, 0x18000
	s_add_i32 s31, 0, 0x1c000
	ds_read_b128 v[132:135], v1 offset:32768
	ds_read_b128 v[136:139], v204 offset:32768
	ds_read_b128 v[140:143], v1 offset:34816
	ds_read_b128 v[144:147], v204 offset:34816
	ds_read_b128 v[148:151], v1 offset:49152
	ds_read_b128 v[152:155], v204 offset:49152
	ds_read_b128 v[156:159], v1 offset:51200
	ds_read_b128 v[160:163], v204 offset:51200
	s_add_u32 s34, s40, 0x80000
	s_addc_u32 s35, s41, 0
	s_mov_b32 m0, s52
	v_lshl_add_u64 v[236:237], s[34:35], 0, v[188:189]
	ds_read_b128 v[164:167], v205 offset:32768
	ds_read_b128 v[168:171], v205 offset:34816
	ds_read_b128 v[172:175], v206 offset:32768
	ds_read_b128 v[176:179], v206 offset:34816
	ds_read_b128 v[190:193], v205 offset:36864
	ds_read_b128 v[194:197], v205 offset:38912
	ds_read_b128 v[198:201], v206 offset:36864
	ds_read_b128 v[232:235], v206 offset:38912
	global_load_lds_dwordx4 v[236:237], off
	v_lshl_add_u64 v[236:237], s[34:35], 0, v[186:187]
	s_mov_b32 m0, s53
	s_nop 0
	global_load_lds_dwordx4 v[236:237], off
	s_waitcnt vmcnt(8)
	s_waitcnt lgkmcnt(0)
	s_barrier
	s_setprio 1
	s_waitcnt lgkmcnt(0)
	v_mfma_f32_16x16x32_bf16 v[68:71], v[132:135], v[164:167], v[68:71]
	v_mfma_f32_16x16x32_bf16 v[72:75], v[140:143], v[164:167], v[72:75]
	v_mfma_f32_16x16x32_bf16 v[84:87], v[132:135], v[168:171], v[84:87]
	v_mfma_f32_16x16x32_bf16 v[88:91], v[140:143], v[168:171], v[88:91]
	v_mfma_f32_16x16x32_bf16 v[100:103], v[132:135], v[190:193], v[100:103]
	v_mfma_f32_16x16x32_bf16 v[104:107], v[140:143], v[190:193], v[104:107]
	v_mfma_f32_16x16x32_bf16 v[116:119], v[132:135], v[194:197], v[116:119]
	v_mfma_f32_16x16x32_bf16 v[120:123], v[140:143], v[194:197], v[120:123]
	v_mfma_f32_16x16x32_bf16 v[68:71], v[136:139], v[172:175], v[68:71]
	v_mfma_f32_16x16x32_bf16 v[72:75], v[144:147], v[172:175], v[72:75]
	v_mfma_f32_16x16x32_bf16 v[84:87], v[136:139], v[176:179], v[84:87]
	v_mfma_f32_16x16x32_bf16 v[88:91], v[144:147], v[176:179], v[88:91]
	v_mfma_f32_16x16x32_bf16 v[100:103], v[136:139], v[198:201], v[100:103]
	v_mfma_f32_16x16x32_bf16 v[104:107], v[144:147], v[198:201], v[104:107]
	v_mfma_f32_16x16x32_bf16 v[116:119], v[136:139], v[232:235], v[116:119]
	v_mfma_f32_16x16x32_bf16 v[120:123], v[144:147], v[232:235], v[120:123]
	s_setprio 0
	s_setprio 1
	v_mfma_f32_16x16x32_bf16 v[76:79], v[148:151], v[164:167], v[76:79]
	v_mfma_f32_16x16x32_bf16 v[80:83], v[156:159], v[164:167], v[80:83]
	v_mfma_f32_16x16x32_bf16 v[92:95], v[148:151], v[168:171], v[92:95]
	v_mfma_f32_16x16x32_bf16 v[96:99], v[156:159], v[168:171], v[96:99]
	v_mfma_f32_16x16x32_bf16 v[108:111], v[148:151], v[190:193], v[108:111]
	v_mfma_f32_16x16x32_bf16 v[112:115], v[156:159], v[190:193], v[112:115]
	v_mfma_f32_16x16x32_bf16 v[124:127], v[148:151], v[194:197], v[124:127]
	v_mfma_f32_16x16x32_bf16 v[128:131], v[156:159], v[194:197], v[128:131]
	v_mfma_f32_16x16x32_bf16 v[76:79], v[152:155], v[172:175], v[76:79]
	v_mfma_f32_16x16x32_bf16 v[80:83], v[160:163], v[172:175], v[80:83]
	v_mfma_f32_16x16x32_bf16 v[92:95], v[152:155], v[176:179], v[92:95]
	v_mfma_f32_16x16x32_bf16 v[96:99], v[160:163], v[176:179], v[96:99]
	v_mfma_f32_16x16x32_bf16 v[108:111], v[152:155], v[198:201], v[108:111]
	v_mfma_f32_16x16x32_bf16 v[112:115], v[160:163], v[198:201], v[112:115]
	v_mfma_f32_16x16x32_bf16 v[124:127], v[152:155], v[232:235], v[124:127]
	v_mfma_f32_16x16x32_bf16 v[128:131], v[160:163], v[232:235], v[128:131]
	s_setprio 0
	s_barrier
	s_add_i32 s25, s25, s33
	v_lshl_add_u64 v[180:181], v[180:181], 0, s[68:69]
	s_mov_b32 m0, s25
	ds_read_b128 v[164:167], v205 offset:49152
	ds_read_b128 v[168:171], v205 offset:51200
	ds_read_b128 v[172:175], v206 offset:49152
	ds_read_b128 v[176:179], v206 offset:51200
	ds_read_b128 v[190:193], v205 offset:53248
	ds_read_b128 v[194:197], v205 offset:55296
	ds_read_b128 v[198:201], v206 offset:53248
	ds_read_b128 v[232:235], v206 offset:55296
	global_load_lds_dwordx4 v[180:181], off
	s_add_i32 m0, s25, 0x2000
	s_add_u32 s28, s28, 0x80080
	v_lshl_add_u64 v[180:181], v[182:183], 0, s[68:69]
	s_addc_u32 s29, s29, 0
	s_add_i32 s25, s31, s33
	global_load_lds_dwordx4 v[180:181], off
	v_lshl_add_u64 v[180:181], s[28:29], 0, v[34:35]
	s_mov_b32 m0, s25
	s_nop 0
	global_load_lds_dwordx4 v[180:181], off
	v_lshl_add_u64 v[180:181], s[28:29], 0, v[184:185]
	s_add_i32 m0, s25, 0x2000
	s_nop 0
	global_load_lds_dwordx4 v[180:181], off
	v_lshl_add_u64 v[180:181], v[202:203], 0, s[68:69]
	s_mov_b32 m0, s54
	s_nop 0
	global_load_lds_dwordx4 v[180:181], off
	v_lshl_add_u64 v[180:181], v[218:219], 0, s[68:69]
	s_mov_b32 m0, s55
	s_nop 0
	global_load_lds_dwordx4 v[180:181], off
	s_waitcnt vmcnt(8)
	s_waitcnt lgkmcnt(0)
	s_barrier
	s_setprio 1
	s_waitcnt lgkmcnt(0)
	v_mfma_f32_16x16x32_bf16 v[2:5], v[132:135], v[164:167], v[2:5]
	v_mfma_f32_16x16x32_bf16 v[6:9], v[140:143], v[164:167], v[6:9]
	v_mfma_f32_16x16x32_bf16 v[18:21], v[132:135], v[168:171], v[18:21]
	v_mfma_f32_16x16x32_bf16 v[22:25], v[140:143], v[168:171], v[22:25]
	v_mfma_f32_16x16x32_bf16 v[36:39], v[132:135], v[190:193], v[36:39]
	v_mfma_f32_16x16x32_bf16 v[40:43], v[140:143], v[190:193], v[40:43]
	v_mfma_f32_16x16x32_bf16 v[52:55], v[132:135], v[194:197], v[52:55]
	v_mfma_f32_16x16x32_bf16 v[56:59], v[140:143], v[194:197], v[56:59]
	v_mfma_f32_16x16x32_bf16 v[2:5], v[136:139], v[172:175], v[2:5]
	v_mfma_f32_16x16x32_bf16 v[6:9], v[144:147], v[172:175], v[6:9]
	v_mfma_f32_16x16x32_bf16 v[18:21], v[136:139], v[176:179], v[18:21]
	v_mfma_f32_16x16x32_bf16 v[22:25], v[144:147], v[176:179], v[22:25]
	v_mfma_f32_16x16x32_bf16 v[36:39], v[136:139], v[198:201], v[36:39]
	v_mfma_f32_16x16x32_bf16 v[40:43], v[144:147], v[198:201], v[40:43]
	v_mfma_f32_16x16x32_bf16 v[52:55], v[136:139], v[232:235], v[52:55]
	v_mfma_f32_16x16x32_bf16 v[56:59], v[144:147], v[232:235], v[56:59]
	s_setprio 0
	s_setprio 1
	v_mfma_f32_16x16x32_bf16 v[10:13], v[148:151], v[164:167], v[10:13]
	v_mfma_f32_16x16x32_bf16 v[14:17], v[156:159], v[164:167], v[14:17]
	v_mfma_f32_16x16x32_bf16 v[26:29], v[148:151], v[168:171], v[26:29]
	v_mfma_f32_16x16x32_bf16 v[30:33], v[156:159], v[168:171], v[30:33]
	v_mfma_f32_16x16x32_bf16 v[44:47], v[148:151], v[190:193], v[44:47]
	v_mfma_f32_16x16x32_bf16 v[48:51], v[156:159], v[190:193], v[48:51]
	v_mfma_f32_16x16x32_bf16 v[60:63], v[148:151], v[194:197], v[60:63]
	v_mfma_f32_16x16x32_bf16 v[64:67], v[156:159], v[194:197], v[64:67]
	v_mfma_f32_16x16x32_bf16 v[10:13], v[152:155], v[172:175], v[10:13]
	v_mfma_f32_16x16x32_bf16 v[14:17], v[160:163], v[172:175], v[14:17]
	v_mfma_f32_16x16x32_bf16 v[26:29], v[152:155], v[176:179], v[26:29]
	v_mfma_f32_16x16x32_bf16 v[30:33], v[160:163], v[176:179], v[30:33]
	v_mfma_f32_16x16x32_bf16 v[44:47], v[152:155], v[198:201], v[44:47]
	v_mfma_f32_16x16x32_bf16 v[48:51], v[160:163], v[198:201], v[48:51]
	v_mfma_f32_16x16x32_bf16 v[60:63], v[152:155], v[232:235], v[60:63]
	v_mfma_f32_16x16x32_bf16 v[64:67], v[160:163], v[232:235], v[64:67]
	s_setprio 0
	s_barrier
	s_add_u32 s22, s22, 0x100
	s_addc_u32 s23, s23, 0
	s_add_u32 s21, s21, 0x100
	s_addc_u32 s24, s24, 0
	s_cmp_ge_u32 s30, s9
	s_mov_b32 s25, s30
	s_cbranch_scc1 .Lpeel_done_P3
.LBB0_908:
	s_add_i32 s30, s25, 2
	s_add_u32 s28, s22, 0xfff80080
	s_addc_u32 s29, s23, -1
	s_add_i32 s31, 0, 0x10000
	s_cmp_eq_u32 s20, s25
	s_cselect_b32 s41, s47, s29
	s_cselect_b32 s40, s46, s28
	s_cselect_b32 s29, s49, s24
	s_cselect_b32 s28, s48, s21
	s_add_i32 s25, 0, 0x14000
	ds_read_b128 v[132:135], v1
	ds_read_b128 v[136:139], v204
	ds_read_b128 v[140:143], v1 offset:2048
	ds_read_b128 v[144:147], v204 offset:2048
	ds_read_b128 v[148:151], v1 offset:16384
	ds_read_b128 v[152:155], v204 offset:16384
	ds_read_b128 v[156:159], v1 offset:18432
	ds_read_b128 v[160:163], v204 offset:18432
	v_lshl_add_u64 v[180:181], s[22:23], 0, v[188:189]
	s_add_i32 m0, s50, 0xc000
	ds_read_b128 v[164:167], v205
	ds_read_b128 v[168:171], v205 offset:2048
	ds_read_b128 v[172:175], v206
	ds_read_b128 v[176:179], v206 offset:2048
	ds_read_b128 v[190:193], v205 offset:4096
	ds_read_b128 v[194:197], v205 offset:6144
	ds_read_b128 v[198:201], v206 offset:4096
	ds_read_b128 v[232:235], v206 offset:6144
	global_load_lds_dwordx4 v[180:181], off
	v_lshl_add_u64 v[180:181], s[22:23], 0, v[186:187]
	s_add_i32 m0, s50, 0xe000
	s_nop 0
	global_load_lds_dwordx4 v[180:181], off
	s_waitcnt vmcnt(8)
	s_waitcnt lgkmcnt(0)
	s_barrier
	s_setprio 1
	s_waitcnt lgkmcnt(0)
	v_mfma_f32_16x16x32_bf16 v[68:71], v[132:135], v[164:167], v[68:71]
	v_mfma_f32_16x16x32_bf16 v[72:75], v[140:143], v[164:167], v[72:75]
	v_mfma_f32_16x16x32_bf16 v[84:87], v[132:135], v[168:171], v[84:87]
	v_mfma_f32_16x16x32_bf16 v[88:91], v[140:143], v[168:171], v[88:91]
	v_mfma_f32_16x16x32_bf16 v[100:103], v[132:135], v[190:193], v[100:103]
	v_mfma_f32_16x16x32_bf16 v[104:107], v[140:143], v[190:193], v[104:107]
	v_mfma_f32_16x16x32_bf16 v[116:119], v[132:135], v[194:197], v[116:119]
	v_mfma_f32_16x16x32_bf16 v[120:123], v[140:143], v[194:197], v[120:123]
	v_mfma_f32_16x16x32_bf16 v[68:71], v[136:139], v[172:175], v[68:71]
	v_mfma_f32_16x16x32_bf16 v[72:75], v[144:147], v[172:175], v[72:75]
	v_mfma_f32_16x16x32_bf16 v[84:87], v[136:139], v[176:179], v[84:87]
	v_mfma_f32_16x16x32_bf16 v[88:91], v[144:147], v[176:179], v[88:91]
	v_mfma_f32_16x16x32_bf16 v[100:103], v[136:139], v[198:201], v[100:103]
	v_mfma_f32_16x16x32_bf16 v[104:107], v[144:147], v[198:201], v[104:107]
	v_mfma_f32_16x16x32_bf16 v[116:119], v[136:139], v[232:235], v[116:119]
	v_mfma_f32_16x16x32_bf16 v[120:123], v[144:147], v[232:235], v[120:123]
	s_setprio 0
	s_setprio 1
	v_mfma_f32_16x16x32_bf16 v[76:79], v[148:151], v[164:167], v[76:79]
	v_mfma_f32_16x16x32_bf16 v[80:83], v[156:159], v[164:167], v[80:83]
	v_mfma_f32_16x16x32_bf16 v[92:95], v[148:151], v[168:171], v[92:95]
	v_mfma_f32_16x16x32_bf16 v[96:99], v[156:159], v[168:171], v[96:99]
	v_mfma_f32_16x16x32_bf16 v[108:111], v[148:151], v[190:193], v[108:111]
	v_mfma_f32_16x16x32_bf16 v[112:115], v[156:159], v[190:193], v[112:115]
	v_mfma_f32_16x16x32_bf16 v[124:127], v[148:151], v[194:197], v[124:127]
	v_mfma_f32_16x16x32_bf16 v[128:131], v[156:159], v[194:197], v[128:131]
	v_mfma_f32_16x16x32_bf16 v[76:79], v[152:155], v[172:175], v[76:79]
	v_mfma_f32_16x16x32_bf16 v[80:83], v[160:163], v[172:175], v[80:83]
	v_mfma_f32_16x16x32_bf16 v[92:95], v[152:155], v[176:179], v[92:95]
	v_mfma_f32_16x16x32_bf16 v[96:99], v[160:163], v[176:179], v[96:99]
	v_mfma_f32_16x16x32_bf16 v[108:111], v[152:155], v[198:201], v[108:111]
	v_mfma_f32_16x16x32_bf16 v[112:115], v[160:163], v[198:201], v[112:115]
	v_mfma_f32_16x16x32_bf16 v[124:127], v[152:155], v[232:235], v[124:127]
	v_mfma_f32_16x16x32_bf16 v[128:131], v[160:163], v[232:235], v[128:131]
	s_setprio 0
	s_barrier
	s_add_i32 s31, s31, s33
	v_lshl_add_u64 v[180:181], s[28:29], 0, v[34:35]
	s_mov_b32 m0, s31
	ds_read_b128 v[164:167], v205 offset:16384
	ds_read_b128 v[168:171], v205 offset:18432
	ds_read_b128 v[172:175], v206 offset:16384
	ds_read_b128 v[176:179], v206 offset:18432
	ds_read_b128 v[190:193], v205 offset:20480
	ds_read_b128 v[194:197], v205 offset:22528
	ds_read_b128 v[198:201], v206 offset:20480
	ds_read_b128 v[232:235], v206 offset:22528
	global_load_lds_dwordx4 v[180:181], off
	s_add_i32 m0, s31, 0x2000
	s_add_u32 s34, s28, 0x80000
	v_lshl_add_u64 v[182:183], s[28:29], 0, v[184:185]
	s_addc_u32 s35, s29, 0
	s_add_i32 s25, s25, s33
	global_load_lds_dwordx4 v[182:183], off
	v_lshl_add_u64 v[202:203], s[34:35], 0, v[34:35]
	s_mov_b32 m0, s25
	v_lshl_add_u64 v[218:219], s[40:41], 0, v[186:187]
	global_load_lds_dwordx4 v[202:203], off
	v_lshl_add_u64 v[202:203], s[34:35], 0, v[184:185]
	s_add_i32 m0, s25, 0x2000
	s_nop 0
	global_load_lds_dwordx4 v[202:203], off
	v_lshl_add_u64 v[202:203], s[40:41], 0, v[188:189]
	s_mov_b32 m0, s50
	s_nop 0
	global_load_lds_dwordx4 v[202:203], off
	s_mov_b32 m0, s51
	s_nop 0
	global_load_lds_dwordx4 v[218:219], off
	s_waitcnt vmcnt(8)
	s_waitcnt lgkmcnt(0)
	s_barrier
	s_setprio 1
	s_waitcnt lgkmcnt(0)
	v_mfma_f32_16x16x32_bf16 v[2:5], v[132:135], v[164:167], v[2:5]
	v_mfma_f32_16x16x32_bf16 v[6:9], v[140:143], v[164:167], v[6:9]
	v_mfma_f32_16x16x32_bf16 v[18:21], v[132:135], v[168:171], v[18:21]
	v_mfma_f32_16x16x32_bf16 v[22:25], v[140:143], v[168:171], v[22:25]
	v_mfma_f32_16x16x32_bf16 v[36:39], v[132:135], v[190:193], v[36:39]
	v_mfma_f32_16x16x32_bf16 v[40:43], v[140:143], v[190:193], v[40:43]
	v_mfma_f32_16x16x32_bf16 v[52:55], v[132:135], v[194:197], v[52:55]
	v_mfma_f32_16x16x32_bf16 v[56:59], v[140:143], v[194:197], v[56:59]
	v_mfma_f32_16x16x32_bf16 v[2:5], v[136:139], v[172:175], v[2:5]
	v_mfma_f32_16x16x32_bf16 v[6:9], v[144:147], v[172:175], v[6:9]
	v_mfma_f32_16x16x32_bf16 v[18:21], v[136:139], v[176:179], v[18:21]
	v_mfma_f32_16x16x32_bf16 v[22:25], v[144:147], v[176:179], v[22:25]
	v_mfma_f32_16x16x32_bf16 v[36:39], v[136:139], v[198:201], v[36:39]
	v_mfma_f32_16x16x32_bf16 v[40:43], v[144:147], v[198:201], v[40:43]
	v_mfma_f32_16x16x32_bf16 v[52:55], v[136:139], v[232:235], v[52:55]
	v_mfma_f32_16x16x32_bf16 v[56:59], v[144:147], v[232:235], v[56:59]
	s_setprio 0
	s_setprio 1
	v_mfma_f32_16x16x32_bf16 v[10:13], v[148:151], v[164:167], v[10:13]
	v_mfma_f32_16x16x32_bf16 v[14:17], v[156:159], v[164:167], v[14:17]
	v_mfma_f32_16x16x32_bf16 v[26:29], v[148:151], v[168:171], v[26:29]
	v_mfma_f32_16x16x32_bf16 v[30:33], v[156:159], v[168:171], v[30:33]
	v_mfma_f32_16x16x32_bf16 v[44:47], v[148:151], v[190:193], v[44:47]
	v_mfma_f32_16x16x32_bf16 v[48:51], v[156:159], v[190:193], v[48:51]
	v_mfma_f32_16x16x32_bf16 v[60:63], v[148:151], v[194:197], v[60:63]
	v_mfma_f32_16x16x32_bf16 v[64:67], v[156:159], v[194:197], v[64:67]
	v_mfma_f32_16x16x32_bf16 v[10:13], v[152:155], v[172:175], v[10:13]
	v_mfma_f32_16x16x32_bf16 v[14:17], v[160:163], v[172:175], v[14:17]
	v_mfma_f32_16x16x32_bf16 v[26:29], v[152:155], v[176:179], v[26:29]
	v_mfma_f32_16x16x32_bf16 v[30:33], v[160:163], v[176:179], v[30:33]
	v_mfma_f32_16x16x32_bf16 v[44:47], v[152:155], v[198:201], v[44:47]
	v_mfma_f32_16x16x32_bf16 v[48:51], v[160:163], v[198:201], v[48:51]
	v_mfma_f32_16x16x32_bf16 v[60:63], v[152:155], v[232:235], v[60:63]
	v_mfma_f32_16x16x32_bf16 v[64:67], v[160:163], v[232:235], v[64:67]
	s_setprio 0
	s_barrier
	s_add_i32 s25, 0, 0x18000
	s_add_i32 s31, 0, 0x1c000
	ds_read_b128 v[132:135], v1 offset:32768
	ds_read_b128 v[136:139], v204 offset:32768
	ds_read_b128 v[140:143], v1 offset:34816
	ds_read_b128 v[144:147], v204 offset:34816
	ds_read_b128 v[148:151], v1 offset:49152
	ds_read_b128 v[152:155], v204 offset:49152
	ds_read_b128 v[156:159], v1 offset:51200
	ds_read_b128 v[160:163], v204 offset:51200
	s_add_u32 s34, s40, 0x80000
	s_addc_u32 s35, s41, 0
	s_mov_b32 m0, s52
	v_lshl_add_u64 v[236:237], s[34:35], 0, v[188:189]
	ds_read_b128 v[164:167], v205 offset:32768
	ds_read_b128 v[168:171], v205 offset:34816
	ds_read_b128 v[172:175], v206 offset:32768
	ds_read_b128 v[176:179], v206 offset:34816
	ds_read_b128 v[190:193], v205 offset:36864
	ds_read_b128 v[194:197], v205 offset:38912
	ds_read_b128 v[198:201], v206 offset:36864
	ds_read_b128 v[232:235], v206 offset:38912
	global_load_lds_dwordx4 v[236:237], off
	v_lshl_add_u64 v[236:237], s[34:35], 0, v[186:187]
	s_mov_b32 m0, s53
	s_nop 0
	global_load_lds_dwordx4 v[236:237], off
	s_waitcnt vmcnt(8)
	s_waitcnt lgkmcnt(0)
	s_barrier
	s_setprio 1
	s_waitcnt lgkmcnt(0)
	v_mfma_f32_16x16x32_bf16 v[68:71], v[132:135], v[164:167], v[68:71]
	v_mfma_f32_16x16x32_bf16 v[72:75], v[140:143], v[164:167], v[72:75]
	v_mfma_f32_16x16x32_bf16 v[84:87], v[132:135], v[168:171], v[84:87]
	v_mfma_f32_16x16x32_bf16 v[88:91], v[140:143], v[168:171], v[88:91]
	v_mfma_f32_16x16x32_bf16 v[100:103], v[132:135], v[190:193], v[100:103]
	v_mfma_f32_16x16x32_bf16 v[104:107], v[140:143], v[190:193], v[104:107]
	v_mfma_f32_16x16x32_bf16 v[116:119], v[132:135], v[194:197], v[116:119]
	v_mfma_f32_16x16x32_bf16 v[120:123], v[140:143], v[194:197], v[120:123]
	v_mfma_f32_16x16x32_bf16 v[68:71], v[136:139], v[172:175], v[68:71]
	v_mfma_f32_16x16x32_bf16 v[72:75], v[144:147], v[172:175], v[72:75]
	v_mfma_f32_16x16x32_bf16 v[84:87], v[136:139], v[176:179], v[84:87]
	v_mfma_f32_16x16x32_bf16 v[88:91], v[144:147], v[176:179], v[88:91]
	v_mfma_f32_16x16x32_bf16 v[100:103], v[136:139], v[198:201], v[100:103]
	v_mfma_f32_16x16x32_bf16 v[104:107], v[144:147], v[198:201], v[104:107]
	v_mfma_f32_16x16x32_bf16 v[116:119], v[136:139], v[232:235], v[116:119]
	v_mfma_f32_16x16x32_bf16 v[120:123], v[144:147], v[232:235], v[120:123]
	s_setprio 0
	s_setprio 1
	v_mfma_f32_16x16x32_bf16 v[76:79], v[148:151], v[164:167], v[76:79]
	v_mfma_f32_16x16x32_bf16 v[80:83], v[156:159], v[164:167], v[80:83]
	v_mfma_f32_16x16x32_bf16 v[92:95], v[148:151], v[168:171], v[92:95]
	v_mfma_f32_16x16x32_bf16 v[96:99], v[156:159], v[168:171], v[96:99]
	v_mfma_f32_16x16x32_bf16 v[108:111], v[148:151], v[190:193], v[108:111]
	v_mfma_f32_16x16x32_bf16 v[112:115], v[156:159], v[190:193], v[112:115]
	v_mfma_f32_16x16x32_bf16 v[124:127], v[148:151], v[194:197], v[124:127]
	v_mfma_f32_16x16x32_bf16 v[128:131], v[156:159], v[194:197], v[128:131]
	v_mfma_f32_16x16x32_bf16 v[76:79], v[152:155], v[172:175], v[76:79]
	v_mfma_f32_16x16x32_bf16 v[80:83], v[160:163], v[172:175], v[80:83]
	v_mfma_f32_16x16x32_bf16 v[92:95], v[152:155], v[176:179], v[92:95]
	v_mfma_f32_16x16x32_bf16 v[96:99], v[160:163], v[176:179], v[96:99]
	v_mfma_f32_16x16x32_bf16 v[108:111], v[152:155], v[198:201], v[108:111]
	v_mfma_f32_16x16x32_bf16 v[112:115], v[160:163], v[198:201], v[112:115]
	v_mfma_f32_16x16x32_bf16 v[124:127], v[152:155], v[232:235], v[124:127]
	v_mfma_f32_16x16x32_bf16 v[128:131], v[160:163], v[232:235], v[128:131]
	s_setprio 0
	s_barrier
	s_add_i32 s25, s25, s33
	v_lshl_add_u64 v[180:181], v[180:181], 0, s[68:69]
	s_mov_b32 m0, s25
	ds_read_b128 v[164:167], v205 offset:49152
	ds_read_b128 v[168:171], v205 offset:51200
	ds_read_b128 v[172:175], v206 offset:49152
	ds_read_b128 v[176:179], v206 offset:51200
	ds_read_b128 v[190:193], v205 offset:53248
	ds_read_b128 v[194:197], v205 offset:55296
	ds_read_b128 v[198:201], v206 offset:53248
	ds_read_b128 v[232:235], v206 offset:55296
	global_load_lds_dwordx4 v[180:181], off
	s_add_i32 m0, s25, 0x2000
	s_add_u32 s28, s28, 0x80080
	v_lshl_add_u64 v[180:181], v[182:183], 0, s[68:69]
	s_addc_u32 s29, s29, 0
	s_add_i32 s25, s31, s33
	global_load_lds_dwordx4 v[180:181], off
	v_lshl_add_u64 v[180:181], s[28:29], 0, v[34:35]
	s_mov_b32 m0, s25
	s_nop 0
	global_load_lds_dwordx4 v[180:181], off
	v_lshl_add_u64 v[180:181], s[28:29], 0, v[184:185]
	s_add_i32 m0, s25, 0x2000
	s_nop 0
	global_load_lds_dwordx4 v[180:181], off
	v_lshl_add_u64 v[180:181], v[202:203], 0, s[68:69]
	s_mov_b32 m0, s54
	s_nop 0
	global_load_lds_dwordx4 v[180:181], off
	v_lshl_add_u64 v[180:181], v[218:219], 0, s[68:69]
	s_mov_b32 m0, s55
	s_nop 0
	global_load_lds_dwordx4 v[180:181], off
	s_waitcnt vmcnt(8)
	s_waitcnt lgkmcnt(0)
	s_barrier
	s_setprio 1
	s_waitcnt lgkmcnt(0)
	v_mfma_f32_16x16x32_bf16 v[2:5], v[132:135], v[164:167], v[2:5]
	v_mfma_f32_16x16x32_bf16 v[6:9], v[140:143], v[164:167], v[6:9]
	v_mfma_f32_16x16x32_bf16 v[18:21], v[132:135], v[168:171], v[18:21]
	v_mfma_f32_16x16x32_bf16 v[22:25], v[140:143], v[168:171], v[22:25]
	v_mfma_f32_16x16x32_bf16 v[36:39], v[132:135], v[190:193], v[36:39]
	v_mfma_f32_16x16x32_bf16 v[40:43], v[140:143], v[190:193], v[40:43]
	v_mfma_f32_16x16x32_bf16 v[52:55], v[132:135], v[194:197], v[52:55]
	v_mfma_f32_16x16x32_bf16 v[56:59], v[140:143], v[194:197], v[56:59]
	v_mfma_f32_16x16x32_bf16 v[2:5], v[136:139], v[172:175], v[2:5]
	v_mfma_f32_16x16x32_bf16 v[6:9], v[144:147], v[172:175], v[6:9]
	v_mfma_f32_16x16x32_bf16 v[18:21], v[136:139], v[176:179], v[18:21]
	v_mfma_f32_16x16x32_bf16 v[22:25], v[144:147], v[176:179], v[22:25]
	v_mfma_f32_16x16x32_bf16 v[36:39], v[136:139], v[198:201], v[36:39]
	v_mfma_f32_16x16x32_bf16 v[40:43], v[144:147], v[198:201], v[40:43]
	v_mfma_f32_16x16x32_bf16 v[52:55], v[136:139], v[232:235], v[52:55]
	v_mfma_f32_16x16x32_bf16 v[56:59], v[144:147], v[232:235], v[56:59]
	s_setprio 0
	s_setprio 1
	v_mfma_f32_16x16x32_bf16 v[10:13], v[148:151], v[164:167], v[10:13]
	v_mfma_f32_16x16x32_bf16 v[14:17], v[156:159], v[164:167], v[14:17]
	v_mfma_f32_16x16x32_bf16 v[26:29], v[148:151], v[168:171], v[26:29]
	v_mfma_f32_16x16x32_bf16 v[30:33], v[156:159], v[168:171], v[30:33]
	v_mfma_f32_16x16x32_bf16 v[44:47], v[148:151], v[190:193], v[44:47]
	v_mfma_f32_16x16x32_bf16 v[48:51], v[156:159], v[190:193], v[48:51]
	v_mfma_f32_16x16x32_bf16 v[60:63], v[148:151], v[194:197], v[60:63]
	v_mfma_f32_16x16x32_bf16 v[64:67], v[156:159], v[194:197], v[64:67]
	v_mfma_f32_16x16x32_bf16 v[10:13], v[152:155], v[172:175], v[10:13]
	v_mfma_f32_16x16x32_bf16 v[14:17], v[160:163], v[172:175], v[14:17]
	v_mfma_f32_16x16x32_bf16 v[26:29], v[152:155], v[176:179], v[26:29]
	v_mfma_f32_16x16x32_bf16 v[30:33], v[160:163], v[176:179], v[30:33]
	v_mfma_f32_16x16x32_bf16 v[44:47], v[152:155], v[198:201], v[44:47]
	v_mfma_f32_16x16x32_bf16 v[48:51], v[160:163], v[198:201], v[48:51]
	v_mfma_f32_16x16x32_bf16 v[60:63], v[152:155], v[232:235], v[60:63]
	v_mfma_f32_16x16x32_bf16 v[64:67], v[160:163], v[232:235], v[64:67]
	s_setprio 0
	s_barrier
	s_add_u32 s22, s22, 0x100
	s_addc_u32 s23, s23, 0
	s_add_u32 s21, s21, 0x100
	s_addc_u32 s24, s24, 0
	s_cmp_ge_u32 s30, s9
	s_mov_b32 s25, s30
	s_cbranch_scc0 .LBB0_908

.LBB0_1013:
	v_readlane_b32 s28, v254, 58
	v_readlane_b32 s29, v254, 59
	v_mov_b32_e32 v133, v35
	v_readlane_b32 s12, v254, 54
	v_lshl_add_u64 v[2:3], s[28:29], 0, v[34:35]
	v_lshl_add_u64 v[4:5], s[28:29], 0, v[132:133]
	v_mov_b32_e32 v137, v35
	v_readlane_b32 s13, v254, 55
	s_add_i32 m0, s46, 0x18000
	v_lshl_add_u64 v[2:3], v[2:3], 0, s[10:11]
	v_lshl_add_u64 v[6:7], s[12:13], 0, v[136:137]
	v_mov_b32_e32 v135, v35
	s_and_b32 s9, s6, 3
	v_and_b32_e32 v10, 15, v1
	v_lshlrev_b32_e32 v12, 3, v1
	v_and_b32_e32 v1, 48, v1
	s_movk_i32 s6, 0x70
	s_waitcnt vmcnt(2)
	s_barrier
	global_load_lds_dwordx4 v[2:3], off
	v_lshl_add_u64 v[2:3], v[4:5], 0, s[10:11]
	s_add_i32 m0, s46, 0x1a000
	s_add_i32 s52, s46, 0x8000
	v_lshl_add_u64 v[8:9], s[12:13], 0, v[134:135]
	s_lshl_b32 s50, s7, 6
	v_and_b32_e32 v13, 0x70, v12
	v_bitop3_b32 v12, v12, v1, s6 bitop3:0x6c
	global_load_lds_dwordx4 v[2:3], off
	v_lshl_add_u64 v[2:3], v[6:7], 0, s[10:11]
	s_mov_b32 m0, s52
	s_add_i32 s53, s46, 0xa000
	v_readlane_b32 s6, v254, 60
	global_load_lds_dwordx4 v[2:3], off
	v_lshl_add_u64 v[2:3], v[8:9], 0, s[10:11]
	s_mov_b32 m0, s53
	v_readlane_b32 s7, v254, 61
	global_load_lds_dwordx4 v[2:3], off
	s_add_i32 m0, s46, 0x1c000
	v_lshl_add_u64 v[2:3], s[6:7], 0, v[34:35]
	global_load_lds_dwordx4 v[2:3], off
	v_lshl_add_u64 v[2:3], s[6:7], 0, v[132:133]
	s_add_i32 m0, s46, 0x1e000
	s_lshl_b32 s51, s9, 5
	global_load_lds_dwordx4 v[2:3], off
	s_cmpk_lt_u32 s8, 0x100
	s_cselect_b64 s[6:7], -1, 0
	s_and_b32 s8, s8, 0xffffff00
	s_lshl_b32 s10, s9, 6
	s_or_b32 s54, s10, s8
	s_lshl_b32 s8, s9, 2
	v_or_b32_e32 v11, s50, v10
	s_add_i32 s55, s8, 0
	v_readlane_b32 s8, v254, 62
	v_lshlrev_b32_e32 v11, 7, v11
	v_or_b32_e32 v10, s51, v10
	s_waitcnt vmcnt(6)
	s_mov_b32 s10, s8
	v_readlane_b32 s8, v255, 3
	v_bitop3_b32 v14, v11, v13, v1 bitop3:0xf6
	v_lshlrev_b32_e32 v10, 7, v10
	v_bitop3_b32 v2, v11, 64, v12 bitop3:0x36
	v_readlane_b32 s9, v255, 4
	v_bitop3_b32 v1, v10, v13, v1 bitop3:0xf6
	v_bitop3_b32 v150, v10, 64, v12 bitop3:0x36
	v_add_u32_e32 v1, 0x10000, v1
	v_add_u32_e32 v150, 0x10000, v150
	s_add_i32 s55, s55, 0x20400
	s_mov_b32 s56, 0
	v_add_u32_e32 v151, 0, v14
	v_add_u32_e32 v152, 0, v2
	s_mov_b32 s11, s8
	s_mov_b64 s[8:9], s[12:13]
	s_barrier
	s_branch .LBB0_1016

.LBB0_1022:
	s_ashr_i32 s23, s22, 31
	s_lshl_b64 s[12:13], s[22:23], 20
	v_readlane_b32 s20, v254, 52
	v_readlane_b32 s21, v254, 53
	s_add_u32 s40, s20, s12
	s_addc_u32 s41, s21, s13
	s_and_b64 s[12:13], s[38:39], exec
	s_cselect_b32 s12, s41, s9
	s_cselect_b32 s13, s40, s8
	s_ashr_i32 s19, s18, 31
	s_lshl_b64 s[20:21], s[18:19], 20
	v_readlane_b32 s24, v254, 48
	v_readlane_b32 s25, v254, 49
	s_add_u32 s42, s24, s20
	s_addc_u32 s43, s25, s21
	s_and_b64 s[20:21], s[38:39], exec
	s_cselect_b32 s19, s43, s29
	s_cselect_b32 s20, s42, s28
	s_add_u32 s8, s8, 0x80080
	s_addc_u32 s9, s9, 0
	s_add_u32 s21, s28, 0x100
	s_addc_u32 s23, s29, 0
	s_mov_b32 s24, -2
	v_readlane_b32 s35, v255, 20
	v_readlane_b32 s57, v255, 21
	v_readlane_b32 s58, v255, 22
	v_readlane_b32 s59, v255, 23
	s_mov_b64 s[60:61], 0x80
	s_add_u32 s25, s8, 0xfff80080
	s_addc_u32 s28, s9, -1
	s_add_i32 s30, 0, 0x10000
	s_cmp_eq_u32 s24, 28
	s_cselect_b32 s45, s12, s28
	s_cselect_b32 s44, s13, s25
	s_cselect_b32 s29, s19, s23
	s_cselect_b32 s28, s20, s21
	s_add_i32 s25, 0, 0x14000
	ds_read_b128 v[138:141], v1
	ds_read_b128 v[142:145], v150
	ds_read_b128 v[146:149], v1 offset:2048
	ds_read_b128 v[154:157], v150 offset:2048
	ds_read_b128 v[158:161], v1 offset:16384
	ds_read_b128 v[162:165], v150 offset:16384
	ds_read_b128 v[166:169], v1 offset:18432
	ds_read_b128 v[170:173], v150 offset:18432
	v_lshl_add_u64 v[178:179], s[8:9], 0, v[136:137]
	s_add_i32 m0, s46, 0xc000
	ds_read_b128 v[174:177], v151
	ds_read_b128 v[184:187], v151 offset:2048
	ds_read_b128 v[188:191], v152
	ds_read_b128 v[192:195], v152 offset:2048
	ds_read_b128 v[196:199], v151 offset:4096
	ds_read_b128 v[200:203], v151 offset:6144
	ds_read_b128 v[204:207], v152 offset:4096
	ds_read_b128 v[208:211], v152 offset:6144
	global_load_lds_dwordx4 v[178:179], off
	v_lshl_add_u64 v[178:179], s[8:9], 0, v[134:135]
	s_add_i32 m0, s46, 0xe000
	s_nop 0
	global_load_lds_dwordx4 v[178:179], off
	s_waitcnt vmcnt(8)
	s_waitcnt lgkmcnt(0)
	s_barrier
	s_setprio 1
	s_waitcnt lgkmcnt(0)
	v_mfma_f32_16x16x32_bf16 v[128:131], v[138:141], v[174:177], 0
	v_mfma_f32_16x16x32_bf16 v[124:127], v[146:149], v[174:177], 0
	v_mfma_f32_16x16x32_bf16 v[112:115], v[138:141], v[184:187], 0
	v_mfma_f32_16x16x32_bf16 v[108:111], v[146:149], v[184:187], 0
	v_mfma_f32_16x16x32_bf16 v[96:99], v[138:141], v[196:199], 0
	v_mfma_f32_16x16x32_bf16 v[92:95], v[146:149], v[196:199], 0
	v_mfma_f32_16x16x32_bf16 v[80:83], v[138:141], v[200:203], 0
	v_mfma_f32_16x16x32_bf16 v[76:79], v[146:149], v[200:203], 0
	v_mfma_f32_16x16x32_bf16 v[128:131], v[142:145], v[188:191], v[128:131]
	v_mfma_f32_16x16x32_bf16 v[124:127], v[154:157], v[188:191], v[124:127]
	v_mfma_f32_16x16x32_bf16 v[112:115], v[142:145], v[192:195], v[112:115]
	v_mfma_f32_16x16x32_bf16 v[108:111], v[154:157], v[192:195], v[108:111]
	v_mfma_f32_16x16x32_bf16 v[96:99], v[142:145], v[204:207], v[96:99]
	v_mfma_f32_16x16x32_bf16 v[92:95], v[154:157], v[204:207], v[92:95]
	v_mfma_f32_16x16x32_bf16 v[80:83], v[142:145], v[208:211], v[80:83]
	v_mfma_f32_16x16x32_bf16 v[76:79], v[154:157], v[208:211], v[76:79]
	s_setprio 0
	s_setprio 1
	v_mfma_f32_16x16x32_bf16 v[120:123], v[158:161], v[174:177], 0
	v_mfma_f32_16x16x32_bf16 v[116:119], v[166:169], v[174:177], 0
	v_mfma_f32_16x16x32_bf16 v[104:107], v[158:161], v[184:187], 0
	v_mfma_f32_16x16x32_bf16 v[100:103], v[166:169], v[184:187], 0
	v_mfma_f32_16x16x32_bf16 v[88:91], v[158:161], v[196:199], 0
	v_mfma_f32_16x16x32_bf16 v[84:87], v[166:169], v[196:199], 0
	v_mfma_f32_16x16x32_bf16 v[72:75], v[158:161], v[200:203], 0
	v_mfma_f32_16x16x32_bf16 v[68:71], v[166:169], v[200:203], 0
	v_mfma_f32_16x16x32_bf16 v[120:123], v[162:165], v[188:191], v[120:123]
	v_mfma_f32_16x16x32_bf16 v[116:119], v[170:173], v[188:191], v[116:119]
	v_mfma_f32_16x16x32_bf16 v[104:107], v[162:165], v[192:195], v[104:107]
	v_mfma_f32_16x16x32_bf16 v[100:103], v[170:173], v[192:195], v[100:103]
	v_mfma_f32_16x16x32_bf16 v[88:91], v[162:165], v[204:207], v[88:91]
	v_mfma_f32_16x16x32_bf16 v[84:87], v[170:173], v[204:207], v[84:87]
	v_mfma_f32_16x16x32_bf16 v[72:75], v[162:165], v[208:211], v[72:75]
	v_mfma_f32_16x16x32_bf16 v[68:71], v[170:173], v[208:211], v[68:71]
	s_setprio 0
	s_barrier
	s_add_i32 s30, s30, s33
	v_lshl_add_u64 v[178:179], s[28:29], 0, v[34:35]
	s_mov_b32 m0, s30
	ds_read_b128 v[174:177], v151 offset:16384
	ds_read_b128 v[184:187], v151 offset:18432
	ds_read_b128 v[188:191], v152 offset:16384
	ds_read_b128 v[192:195], v152 offset:18432
	ds_read_b128 v[196:199], v151 offset:20480
	ds_read_b128 v[200:203], v151 offset:22528
	ds_read_b128 v[204:207], v152 offset:20480
	ds_read_b128 v[208:211], v152 offset:22528
	global_load_lds_dwordx4 v[178:179], off
	s_add_i32 m0, s30, 0x2000
	s_add_u32 s30, s28, 0x80000
	v_lshl_add_u64 v[180:181], s[28:29], 0, v[132:133]
	s_addc_u32 s31, s29, 0
	s_add_i32 s25, s25, s33
	global_load_lds_dwordx4 v[180:181], off
	v_lshl_add_u64 v[182:183], s[30:31], 0, v[34:35]
	s_mov_b32 m0, s25
	v_lshl_add_u64 v[212:213], s[44:45], 0, v[134:135]
	global_load_lds_dwordx4 v[182:183], off
	v_lshl_add_u64 v[182:183], s[30:31], 0, v[132:133]
	s_add_i32 m0, s25, 0x2000
	s_nop 0
	global_load_lds_dwordx4 v[182:183], off
	v_lshl_add_u64 v[182:183], s[44:45], 0, v[136:137]
	s_mov_b32 m0, s46
	s_nop 0
	global_load_lds_dwordx4 v[182:183], off
	s_mov_b32 m0, s47
	s_nop 0
	global_load_lds_dwordx4 v[212:213], off
	s_waitcnt vmcnt(8)
	s_waitcnt lgkmcnt(0)
	s_barrier
	s_setprio 1
	s_waitcnt lgkmcnt(0)
	v_mfma_f32_16x16x32_bf16 v[64:67], v[138:141], v[174:177], 0
	v_mfma_f32_16x16x32_bf16 v[60:63], v[146:149], v[174:177], 0
	v_mfma_f32_16x16x32_bf16 v[48:51], v[138:141], v[184:187], 0
	v_mfma_f32_16x16x32_bf16 v[44:47], v[146:149], v[184:187], 0
	v_mfma_f32_16x16x32_bf16 v[30:33], v[138:141], v[196:199], 0
	v_mfma_f32_16x16x32_bf16 v[26:29], v[146:149], v[196:199], 0
	v_mfma_f32_16x16x32_bf16 v[14:17], v[138:141], v[200:203], 0
	v_mfma_f32_16x16x32_bf16 v[10:13], v[146:149], v[200:203], 0
	v_mfma_f32_16x16x32_bf16 v[64:67], v[142:145], v[188:191], v[64:67]
	v_mfma_f32_16x16x32_bf16 v[60:63], v[154:157], v[188:191], v[60:63]
	v_mfma_f32_16x16x32_bf16 v[48:51], v[142:145], v[192:195], v[48:51]
	v_mfma_f32_16x16x32_bf16 v[44:47], v[154:157], v[192:195], v[44:47]
	v_mfma_f32_16x16x32_bf16 v[30:33], v[142:145], v[204:207], v[30:33]
	v_mfma_f32_16x16x32_bf16 v[26:29], v[154:157], v[204:207], v[26:29]
	v_mfma_f32_16x16x32_bf16 v[14:17], v[142:145], v[208:211], v[14:17]
	v_mfma_f32_16x16x32_bf16 v[10:13], v[154:157], v[208:211], v[10:13]
	s_setprio 0
	s_setprio 1
	v_mfma_f32_16x16x32_bf16 v[56:59], v[158:161], v[174:177], 0
	v_mfma_f32_16x16x32_bf16 v[52:55], v[166:169], v[174:177], 0
	v_mfma_f32_16x16x32_bf16 v[40:43], v[158:161], v[184:187], 0
	v_mfma_f32_16x16x32_bf16 v[36:39], v[166:169], v[184:187], 0
	v_mfma_f32_16x16x32_bf16 v[22:25], v[158:161], v[196:199], 0
	v_mfma_f32_16x16x32_bf16 v[18:21], v[166:169], v[196:199], 0
	v_mfma_f32_16x16x32_bf16 v[6:9], v[158:161], v[200:203], 0
	v_mfma_f32_16x16x32_bf16 v[2:5], v[166:169], v[200:203], 0
	v_mfma_f32_16x16x32_bf16 v[56:59], v[162:165], v[188:191], v[56:59]
	v_mfma_f32_16x16x32_bf16 v[52:55], v[170:173], v[188:191], v[52:55]
	v_mfma_f32_16x16x32_bf16 v[40:43], v[162:165], v[192:195], v[40:43]
	v_mfma_f32_16x16x32_bf16 v[36:39], v[170:173], v[192:195], v[36:39]
	v_mfma_f32_16x16x32_bf16 v[22:25], v[162:165], v[204:207], v[22:25]
	v_mfma_f32_16x16x32_bf16 v[18:21], v[170:173], v[204:207], v[18:21]
	v_mfma_f32_16x16x32_bf16 v[6:9], v[162:165], v[208:211], v[6:9]
	v_mfma_f32_16x16x32_bf16 v[2:5], v[170:173], v[208:211], v[2:5]
	s_setprio 0
	s_barrier
	s_add_i32 s25, 0, 0x18000
	s_add_i32 s34, 0, 0x1c000
	ds_read_b128 v[138:141], v1 offset:32768
	ds_read_b128 v[142:145], v150 offset:32768
	ds_read_b128 v[146:149], v1 offset:34816
	ds_read_b128 v[154:157], v150 offset:34816
	ds_read_b128 v[158:161], v1 offset:49152
	ds_read_b128 v[162:165], v150 offset:49152
	ds_read_b128 v[166:169], v1 offset:51200
	ds_read_b128 v[170:173], v150 offset:51200
	s_add_u32 s30, s44, 0x80000
	s_addc_u32 s31, s45, 0
	s_mov_b32 m0, s48
	v_lshl_add_u64 v[218:219], s[30:31], 0, v[136:137]
	ds_read_b128 v[174:177], v151 offset:32768
	ds_read_b128 v[184:187], v151 offset:34816
	ds_read_b128 v[188:191], v152 offset:32768
	ds_read_b128 v[192:195], v152 offset:34816
	ds_read_b128 v[196:199], v151 offset:36864
	ds_read_b128 v[200:203], v151 offset:38912
	ds_read_b128 v[204:207], v152 offset:36864
	ds_read_b128 v[208:211], v152 offset:38912
	global_load_lds_dwordx4 v[218:219], off
	v_lshl_add_u64 v[218:219], s[30:31], 0, v[134:135]
	s_mov_b32 m0, s49
	s_nop 0
	global_load_lds_dwordx4 v[218:219], off
	s_waitcnt vmcnt(8)
	s_waitcnt lgkmcnt(0)
	s_barrier
	s_setprio 1
	s_waitcnt lgkmcnt(0)
	v_mfma_f32_16x16x32_bf16 v[128:131], v[138:141], v[174:177], v[128:131]
	v_mfma_f32_16x16x32_bf16 v[124:127], v[146:149], v[174:177], v[124:127]
	v_mfma_f32_16x16x32_bf16 v[112:115], v[138:141], v[184:187], v[112:115]
	v_mfma_f32_16x16x32_bf16 v[108:111], v[146:149], v[184:187], v[108:111]
	v_mfma_f32_16x16x32_bf16 v[96:99], v[138:141], v[196:199], v[96:99]
	v_mfma_f32_16x16x32_bf16 v[92:95], v[146:149], v[196:199], v[92:95]
	v_mfma_f32_16x16x32_bf16 v[80:83], v[138:141], v[200:203], v[80:83]
	v_mfma_f32_16x16x32_bf16 v[76:79], v[146:149], v[200:203], v[76:79]
	v_mfma_f32_16x16x32_bf16 v[128:131], v[142:145], v[188:191], v[128:131]
	v_mfma_f32_16x16x32_bf16 v[124:127], v[154:157], v[188:191], v[124:127]
	v_mfma_f32_16x16x32_bf16 v[112:115], v[142:145], v[192:195], v[112:115]
	v_mfma_f32_16x16x32_bf16 v[108:111], v[154:157], v[192:195], v[108:111]
	v_mfma_f32_16x16x32_bf16 v[96:99], v[142:145], v[204:207], v[96:99]
	v_mfma_f32_16x16x32_bf16 v[92:95], v[154:157], v[204:207], v[92:95]
	v_mfma_f32_16x16x32_bf16 v[80:83], v[142:145], v[208:211], v[80:83]
	v_mfma_f32_16x16x32_bf16 v[76:79], v[154:157], v[208:211], v[76:79]
	s_setprio 0
	s_setprio 1
	v_mfma_f32_16x16x32_bf16 v[120:123], v[158:161], v[174:177], v[120:123]
	v_mfma_f32_16x16x32_bf16 v[116:119], v[166:169], v[174:177], v[116:119]
	v_mfma_f32_16x16x32_bf16 v[104:107], v[158:161], v[184:187], v[104:107]
	v_mfma_f32_16x16x32_bf16 v[100:103], v[166:169], v[184:187], v[100:103]
	v_mfma_f32_16x16x32_bf16 v[88:91], v[158:161], v[196:199], v[88:91]
	v_mfma_f32_16x16x32_bf16 v[84:87], v[166:169], v[196:199], v[84:87]
	v_mfma_f32_16x16x32_bf16 v[72:75], v[158:161], v[200:203], v[72:75]
	v_mfma_f32_16x16x32_bf16 v[68:71], v[166:169], v[200:203], v[68:71]
	v_mfma_f32_16x16x32_bf16 v[120:123], v[162:165], v[188:191], v[120:123]
	v_mfma_f32_16x16x32_bf16 v[116:119], v[170:173], v[188:191], v[116:119]
	v_mfma_f32_16x16x32_bf16 v[104:107], v[162:165], v[192:195], v[104:107]
	v_mfma_f32_16x16x32_bf16 v[100:103], v[170:173], v[192:195], v[100:103]
	v_mfma_f32_16x16x32_bf16 v[88:91], v[162:165], v[204:207], v[88:91]
	v_mfma_f32_16x16x32_bf16 v[84:87], v[170:173], v[204:207], v[84:87]
	v_mfma_f32_16x16x32_bf16 v[72:75], v[162:165], v[208:211], v[72:75]
	v_mfma_f32_16x16x32_bf16 v[68:71], v[170:173], v[208:211], v[68:71]
	s_setprio 0
	s_barrier
	s_add_i32 s25, s25, s33
	v_lshl_add_u64 v[178:179], v[178:179], 0, s[60:61]
	s_mov_b32 m0, s25
	ds_read_b128 v[174:177], v151 offset:49152
	ds_read_b128 v[184:187], v151 offset:51200
	ds_read_b128 v[188:191], v152 offset:49152
	ds_read_b128 v[192:195], v152 offset:51200
	ds_read_b128 v[196:199], v151 offset:53248
	ds_read_b128 v[200:203], v151 offset:55296
	ds_read_b128 v[204:207], v152 offset:53248
	ds_read_b128 v[208:211], v152 offset:55296
	global_load_lds_dwordx4 v[178:179], off
	s_add_i32 m0, s25, 0x2000
	s_add_u32 s28, s28, 0x80080
	v_lshl_add_u64 v[178:179], v[180:181], 0, s[60:61]
	s_addc_u32 s29, s29, 0
	s_add_i32 s25, s34, s33
	global_load_lds_dwordx4 v[178:179], off
	v_lshl_add_u64 v[178:179], s[28:29], 0, v[34:35]
	s_mov_b32 m0, s25
	s_nop 0
	global_load_lds_dwordx4 v[178:179], off
	v_lshl_add_u64 v[178:179], s[28:29], 0, v[132:133]
	s_add_i32 m0, s25, 0x2000
	s_nop 0
	global_load_lds_dwordx4 v[178:179], off
	v_lshl_add_u64 v[178:179], v[182:183], 0, s[60:61]
	s_mov_b32 m0, s52
	s_nop 0
	global_load_lds_dwordx4 v[178:179], off
	v_lshl_add_u64 v[178:179], v[212:213], 0, s[60:61]
	s_mov_b32 m0, s53
	s_nop 0
	global_load_lds_dwordx4 v[178:179], off
	s_waitcnt vmcnt(8)
	s_waitcnt lgkmcnt(0)
	s_barrier
	s_setprio 1
	s_waitcnt lgkmcnt(0)
	v_mfma_f32_16x16x32_bf16 v[64:67], v[138:141], v[174:177], v[64:67]
	v_mfma_f32_16x16x32_bf16 v[60:63], v[146:149], v[174:177], v[60:63]
	v_mfma_f32_16x16x32_bf16 v[48:51], v[138:141], v[184:187], v[48:51]
	v_mfma_f32_16x16x32_bf16 v[44:47], v[146:149], v[184:187], v[44:47]
	v_mfma_f32_16x16x32_bf16 v[30:33], v[138:141], v[196:199], v[30:33]
	v_mfma_f32_16x16x32_bf16 v[26:29], v[146:149], v[196:199], v[26:29]
	v_mfma_f32_16x16x32_bf16 v[14:17], v[138:141], v[200:203], v[14:17]
	v_mfma_f32_16x16x32_bf16 v[10:13], v[146:149], v[200:203], v[10:13]
	v_mfma_f32_16x16x32_bf16 v[64:67], v[142:145], v[188:191], v[64:67]
	v_mfma_f32_16x16x32_bf16 v[60:63], v[154:157], v[188:191], v[60:63]
	v_mfma_f32_16x16x32_bf16 v[48:51], v[142:145], v[192:195], v[48:51]
	v_mfma_f32_16x16x32_bf16 v[44:47], v[154:157], v[192:195], v[44:47]
	v_mfma_f32_16x16x32_bf16 v[30:33], v[142:145], v[204:207], v[30:33]
	v_mfma_f32_16x16x32_bf16 v[26:29], v[154:157], v[204:207], v[26:29]
	v_mfma_f32_16x16x32_bf16 v[14:17], v[142:145], v[208:211], v[14:17]
	v_mfma_f32_16x16x32_bf16 v[10:13], v[154:157], v[208:211], v[10:13]
	s_setprio 0
	s_setprio 1
	v_mfma_f32_16x16x32_bf16 v[56:59], v[158:161], v[174:177], v[56:59]
	v_mfma_f32_16x16x32_bf16 v[52:55], v[166:169], v[174:177], v[52:55]
	v_mfma_f32_16x16x32_bf16 v[40:43], v[158:161], v[184:187], v[40:43]
	v_mfma_f32_16x16x32_bf16 v[36:39], v[166:169], v[184:187], v[36:39]
	v_mfma_f32_16x16x32_bf16 v[22:25], v[158:161], v[196:199], v[22:25]
	v_mfma_f32_16x16x32_bf16 v[18:21], v[166:169], v[196:199], v[18:21]
	v_mfma_f32_16x16x32_bf16 v[6:9], v[158:161], v[200:203], v[6:9]
	v_mfma_f32_16x16x32_bf16 v[2:5], v[166:169], v[200:203], v[2:5]
	v_mfma_f32_16x16x32_bf16 v[56:59], v[162:165], v[188:191], v[56:59]
	v_mfma_f32_16x16x32_bf16 v[52:55], v[170:173], v[188:191], v[52:55]
	v_mfma_f32_16x16x32_bf16 v[40:43], v[162:165], v[192:195], v[40:43]
	v_mfma_f32_16x16x32_bf16 v[36:39], v[170:173], v[192:195], v[36:39]
	v_mfma_f32_16x16x32_bf16 v[22:25], v[162:165], v[204:207], v[22:25]
	v_mfma_f32_16x16x32_bf16 v[18:21], v[170:173], v[204:207], v[18:21]
	v_mfma_f32_16x16x32_bf16 v[6:9], v[162:165], v[208:211], v[6:9]
	v_mfma_f32_16x16x32_bf16 v[2:5], v[170:173], v[208:211], v[2:5]
	s_setprio 0
	s_barrier
	s_add_i32 s24, s24, 2
	s_add_u32 s8, s8, 0x100
	s_addc_u32 s9, s9, 0
	s_add_u32 s21, s21, 0x100
	s_addc_u32 s23, s23, 0
	s_cmp_gt_u32 s24, 29
	s_cbranch_scc1 .Lpeel_done_P4
.LBB0_1023:
	s_add_u32 s25, s8, 0xfff80080
	s_addc_u32 s28, s9, -1
	s_add_i32 s30, 0, 0x10000
	s_cmp_eq_u32 s24, 28
	s_cselect_b32 s45, s12, s28
	s_cselect_b32 s44, s13, s25
	s_cselect_b32 s29, s19, s23
	s_cselect_b32 s28, s20, s21
	s_add_i32 s25, 0, 0x14000
	ds_read_b128 v[138:141], v1
	ds_read_b128 v[142:145], v150
	ds_read_b128 v[146:149], v1 offset:2048
	ds_read_b128 v[154:157], v150 offset:2048
	ds_read_b128 v[158:161], v1 offset:16384
	ds_read_b128 v[162:165], v150 offset:16384
	ds_read_b128 v[166:169], v1 offset:18432
	ds_read_b128 v[170:173], v150 offset:18432
	v_lshl_add_u64 v[178:179], s[8:9], 0, v[136:137]
	s_add_i32 m0, s46, 0xc000
	ds_read_b128 v[174:177], v151
	ds_read_b128 v[184:187], v151 offset:2048
	ds_read_b128 v[188:191], v152
	ds_read_b128 v[192:195], v152 offset:2048
	ds_read_b128 v[196:199], v151 offset:4096
	ds_read_b128 v[200:203], v151 offset:6144
	ds_read_b128 v[204:207], v152 offset:4096
	ds_read_b128 v[208:211], v152 offset:6144
	global_load_lds_dwordx4 v[178:179], off
	v_lshl_add_u64 v[178:179], s[8:9], 0, v[134:135]
	s_add_i32 m0, s46, 0xe000
	s_nop 0
	global_load_lds_dwordx4 v[178:179], off
	s_waitcnt vmcnt(8)
	s_waitcnt lgkmcnt(0)
	s_barrier
	s_setprio 1
	s_waitcnt lgkmcnt(0)
	v_mfma_f32_16x16x32_bf16 v[128:131], v[138:141], v[174:177], v[128:131]
	v_mfma_f32_16x16x32_bf16 v[124:127], v[146:149], v[174:177], v[124:127]
	v_mfma_f32_16x16x32_bf16 v[112:115], v[138:141], v[184:187], v[112:115]
	v_mfma_f32_16x16x32_bf16 v[108:111], v[146:149], v[184:187], v[108:111]
	v_mfma_f32_16x16x32_bf16 v[96:99], v[138:141], v[196:199], v[96:99]
	v_mfma_f32_16x16x32_bf16 v[92:95], v[146:149], v[196:199], v[92:95]
	v_mfma_f32_16x16x32_bf16 v[80:83], v[138:141], v[200:203], v[80:83]
	v_mfma_f32_16x16x32_bf16 v[76:79], v[146:149], v[200:203], v[76:79]
	v_mfma_f32_16x16x32_bf16 v[128:131], v[142:145], v[188:191], v[128:131]
	v_mfma_f32_16x16x32_bf16 v[124:127], v[154:157], v[188:191], v[124:127]
	v_mfma_f32_16x16x32_bf16 v[112:115], v[142:145], v[192:195], v[112:115]
	v_mfma_f32_16x16x32_bf16 v[108:111], v[154:157], v[192:195], v[108:111]
	v_mfma_f32_16x16x32_bf16 v[96:99], v[142:145], v[204:207], v[96:99]
	v_mfma_f32_16x16x32_bf16 v[92:95], v[154:157], v[204:207], v[92:95]
	v_mfma_f32_16x16x32_bf16 v[80:83], v[142:145], v[208:211], v[80:83]
	v_mfma_f32_16x16x32_bf16 v[76:79], v[154:157], v[208:211], v[76:79]
	s_setprio 0
	s_setprio 1
	v_mfma_f32_16x16x32_bf16 v[120:123], v[158:161], v[174:177], v[120:123]
	v_mfma_f32_16x16x32_bf16 v[116:119], v[166:169], v[174:177], v[116:119]
	v_mfma_f32_16x16x32_bf16 v[104:107], v[158:161], v[184:187], v[104:107]
	v_mfma_f32_16x16x32_bf16 v[100:103], v[166:169], v[184:187], v[100:103]
	v_mfma_f32_16x16x32_bf16 v[88:91], v[158:161], v[196:199], v[88:91]
	v_mfma_f32_16x16x32_bf16 v[84:87], v[166:169], v[196:199], v[84:87]
	v_mfma_f32_16x16x32_bf16 v[72:75], v[158:161], v[200:203], v[72:75]
	v_mfma_f32_16x16x32_bf16 v[68:71], v[166:169], v[200:203], v[68:71]
	v_mfma_f32_16x16x32_bf16 v[120:123], v[162:165], v[188:191], v[120:123]
	v_mfma_f32_16x16x32_bf16 v[116:119], v[170:173], v[188:191], v[116:119]
	v_mfma_f32_16x16x32_bf16 v[104:107], v[162:165], v[192:195], v[104:107]
	v_mfma_f32_16x16x32_bf16 v[100:103], v[170:173], v[192:195], v[100:103]
	v_mfma_f32_16x16x32_bf16 v[88:91], v[162:165], v[204:207], v[88:91]
	v_mfma_f32_16x16x32_bf16 v[84:87], v[170:173], v[204:207], v[84:87]
	v_mfma_f32_16x16x32_bf16 v[72:75], v[162:165], v[208:211], v[72:75]
	v_mfma_f32_16x16x32_bf16 v[68:71], v[170:173], v[208:211], v[68:71]
	s_setprio 0
	s_barrier
	s_add_i32 s30, s30, s33
	v_lshl_add_u64 v[178:179], s[28:29], 0, v[34:35]
	s_mov_b32 m0, s30
	ds_read_b128 v[174:177], v151 offset:16384
	ds_read_b128 v[184:187], v151 offset:18432
	ds_read_b128 v[188:191], v152 offset:16384
	ds_read_b128 v[192:195], v152 offset:18432
	ds_read_b128 v[196:199], v151 offset:20480
	ds_read_b128 v[200:203], v151 offset:22528
	ds_read_b128 v[204:207], v152 offset:20480
	ds_read_b128 v[208:211], v152 offset:22528
	global_load_lds_dwordx4 v[178:179], off
	s_add_i32 m0, s30, 0x2000
	s_add_u32 s30, s28, 0x80000
	v_lshl_add_u64 v[180:181], s[28:29], 0, v[132:133]
	s_addc_u32 s31, s29, 0
	s_add_i32 s25, s25, s33
	global_load_lds_dwordx4 v[180:181], off
	v_lshl_add_u64 v[182:183], s[30:31], 0, v[34:35]
	s_mov_b32 m0, s25
	v_lshl_add_u64 v[212:213], s[44:45], 0, v[134:135]
	global_load_lds_dwordx4 v[182:183], off
	v_lshl_add_u64 v[182:183], s[30:31], 0, v[132:133]
	s_add_i32 m0, s25, 0x2000
	s_nop 0
	global_load_lds_dwordx4 v[182:183], off
	v_lshl_add_u64 v[182:183], s[44:45], 0, v[136:137]
	s_mov_b32 m0, s46
	s_nop 0
	global_load_lds_dwordx4 v[182:183], off
	s_mov_b32 m0, s47
	s_nop 0
	global_load_lds_dwordx4 v[212:213], off
	s_waitcnt vmcnt(8)
	s_waitcnt lgkmcnt(0)
	s_barrier
	s_setprio 1
	s_waitcnt lgkmcnt(0)
	v_mfma_f32_16x16x32_bf16 v[64:67], v[138:141], v[174:177], v[64:67]
	v_mfma_f32_16x16x32_bf16 v[60:63], v[146:149], v[174:177], v[60:63]
	v_mfma_f32_16x16x32_bf16 v[48:51], v[138:141], v[184:187], v[48:51]
	v_mfma_f32_16x16x32_bf16 v[44:47], v[146:149], v[184:187], v[44:47]
	v_mfma_f32_16x16x32_bf16 v[30:33], v[138:141], v[196:199], v[30:33]
	v_mfma_f32_16x16x32_bf16 v[26:29], v[146:149], v[196:199], v[26:29]
	v_mfma_f32_16x16x32_bf16 v[14:17], v[138:141], v[200:203], v[14:17]
	v_mfma_f32_16x16x32_bf16 v[10:13], v[146:149], v[200:203], v[10:13]
	v_mfma_f32_16x16x32_bf16 v[64:67], v[142:145], v[188:191], v[64:67]
	v_mfma_f32_16x16x32_bf16 v[60:63], v[154:157], v[188:191], v[60:63]
	v_mfma_f32_16x16x32_bf16 v[48:51], v[142:145], v[192:195], v[48:51]
	v_mfma_f32_16x16x32_bf16 v[44:47], v[154:157], v[192:195], v[44:47]
	v_mfma_f32_16x16x32_bf16 v[30:33], v[142:145], v[204:207], v[30:33]
	v_mfma_f32_16x16x32_bf16 v[26:29], v[154:157], v[204:207], v[26:29]
	v_mfma_f32_16x16x32_bf16 v[14:17], v[142:145], v[208:211], v[14:17]
	v_mfma_f32_16x16x32_bf16 v[10:13], v[154:157], v[208:211], v[10:13]
	s_setprio 0
	s_setprio 1
	v_mfma_f32_16x16x32_bf16 v[56:59], v[158:161], v[174:177], v[56:59]
	v_mfma_f32_16x16x32_bf16 v[52:55], v[166:169], v[174:177], v[52:55]
	v_mfma_f32_16x16x32_bf16 v[40:43], v[158:161], v[184:187], v[40:43]
	v_mfma_f32_16x16x32_bf16 v[36:39], v[166:169], v[184:187], v[36:39]
	v_mfma_f32_16x16x32_bf16 v[22:25], v[158:161], v[196:199], v[22:25]
	v_mfma_f32_16x16x32_bf16 v[18:21], v[166:169], v[196:199], v[18:21]
	v_mfma_f32_16x16x32_bf16 v[6:9], v[158:161], v[200:203], v[6:9]
	v_mfma_f32_16x16x32_bf16 v[2:5], v[166:169], v[200:203], v[2:5]
	v_mfma_f32_16x16x32_bf16 v[56:59], v[162:165], v[188:191], v[56:59]
	v_mfma_f32_16x16x32_bf16 v[52:55], v[170:173], v[188:191], v[52:55]
	v_mfma_f32_16x16x32_bf16 v[40:43], v[162:165], v[192:195], v[40:43]
	v_mfma_f32_16x16x32_bf16 v[36:39], v[170:173], v[192:195], v[36:39]
	v_mfma_f32_16x16x32_bf16 v[22:25], v[162:165], v[204:207], v[22:25]
	v_mfma_f32_16x16x32_bf16 v[18:21], v[170:173], v[204:207], v[18:21]
	v_mfma_f32_16x16x32_bf16 v[6:9], v[162:165], v[208:211], v[6:9]
	v_mfma_f32_16x16x32_bf16 v[2:5], v[170:173], v[208:211], v[2:5]
	s_setprio 0
	s_barrier
	s_add_i32 s25, 0, 0x18000
	s_add_i32 s34, 0, 0x1c000
	ds_read_b128 v[138:141], v1 offset:32768
	ds_read_b128 v[142:145], v150 offset:32768
	ds_read_b128 v[146:149], v1 offset:34816
	ds_read_b128 v[154:157], v150 offset:34816
	ds_read_b128 v[158:161], v1 offset:49152
	ds_read_b128 v[162:165], v150 offset:49152
	ds_read_b128 v[166:169], v1 offset:51200
	ds_read_b128 v[170:173], v150 offset:51200
	s_add_u32 s30, s44, 0x80000
	s_addc_u32 s31, s45, 0
	s_mov_b32 m0, s48
	v_lshl_add_u64 v[218:219], s[30:31], 0, v[136:137]
	ds_read_b128 v[174:177], v151 offset:32768
	ds_read_b128 v[184:187], v151 offset:34816
	ds_read_b128 v[188:191], v152 offset:32768
	ds_read_b128 v[192:195], v152 offset:34816
	ds_read_b128 v[196:199], v151 offset:36864
	ds_read_b128 v[200:203], v151 offset:38912
	ds_read_b128 v[204:207], v152 offset:36864
	ds_read_b128 v[208:211], v152 offset:38912
	global_load_lds_dwordx4 v[218:219], off
	v_lshl_add_u64 v[218:219], s[30:31], 0, v[134:135]
	s_mov_b32 m0, s49
	s_nop 0
	global_load_lds_dwordx4 v[218:219], off
	s_waitcnt vmcnt(8)
	s_waitcnt lgkmcnt(0)
	s_barrier
	s_setprio 1
	s_waitcnt lgkmcnt(0)
	v_mfma_f32_16x16x32_bf16 v[128:131], v[138:141], v[174:177], v[128:131]
	v_mfma_f32_16x16x32_bf16 v[124:127], v[146:149], v[174:177], v[124:127]
	v_mfma_f32_16x16x32_bf16 v[112:115], v[138:141], v[184:187], v[112:115]
	v_mfma_f32_16x16x32_bf16 v[108:111], v[146:149], v[184:187], v[108:111]
	v_mfma_f32_16x16x32_bf16 v[96:99], v[138:141], v[196:199], v[96:99]
	v_mfma_f32_16x16x32_bf16 v[92:95], v[146:149], v[196:199], v[92:95]
	v_mfma_f32_16x16x32_bf16 v[80:83], v[138:141], v[200:203], v[80:83]
	v_mfma_f32_16x16x32_bf16 v[76:79], v[146:149], v[200:203], v[76:79]
	v_mfma_f32_16x16x32_bf16 v[128:131], v[142:145], v[188:191], v[128:131]
	v_mfma_f32_16x16x32_bf16 v[124:127], v[154:157], v[188:191], v[124:127]
	v_mfma_f32_16x16x32_bf16 v[112:115], v[142:145], v[192:195], v[112:115]
	v_mfma_f32_16x16x32_bf16 v[108:111], v[154:157], v[192:195], v[108:111]
	v_mfma_f32_16x16x32_bf16 v[96:99], v[142:145], v[204:207], v[96:99]
	v_mfma_f32_16x16x32_bf16 v[92:95], v[154:157], v[204:207], v[92:95]
	v_mfma_f32_16x16x32_bf16 v[80:83], v[142:145], v[208:211], v[80:83]
	v_mfma_f32_16x16x32_bf16 v[76:79], v[154:157], v[208:211], v[76:79]
	s_setprio 0
	s_setprio 1
	v_mfma_f32_16x16x32_bf16 v[120:123], v[158:161], v[174:177], v[120:123]
	v_mfma_f32_16x16x32_bf16 v[116:119], v[166:169], v[174:177], v[116:119]
	v_mfma_f32_16x16x32_bf16 v[104:107], v[158:161], v[184:187], v[104:107]
	v_mfma_f32_16x16x32_bf16 v[100:103], v[166:169], v[184:187], v[100:103]
	v_mfma_f32_16x16x32_bf16 v[88:91], v[158:161], v[196:199], v[88:91]
	v_mfma_f32_16x16x32_bf16 v[84:87], v[166:169], v[196:199], v[84:87]
	v_mfma_f32_16x16x32_bf16 v[72:75], v[158:161], v[200:203], v[72:75]
	v_mfma_f32_16x16x32_bf16 v[68:71], v[166:169], v[200:203], v[68:71]
	v_mfma_f32_16x16x32_bf16 v[120:123], v[162:165], v[188:191], v[120:123]
	v_mfma_f32_16x16x32_bf16 v[116:119], v[170:173], v[188:191], v[116:119]
	v_mfma_f32_16x16x32_bf16 v[104:107], v[162:165], v[192:195], v[104:107]
	v_mfma_f32_16x16x32_bf16 v[100:103], v[170:173], v[192:195], v[100:103]
	v_mfma_f32_16x16x32_bf16 v[88:91], v[162:165], v[204:207], v[88:91]
	v_mfma_f32_16x16x32_bf16 v[84:87], v[170:173], v[204:207], v[84:87]
	v_mfma_f32_16x16x32_bf16 v[72:75], v[162:165], v[208:211], v[72:75]
	v_mfma_f32_16x16x32_bf16 v[68:71], v[170:173], v[208:211], v[68:71]
	s_setprio 0
	s_barrier
	s_add_i32 s25, s25, s33
	v_lshl_add_u64 v[178:179], v[178:179], 0, s[60:61]
	s_mov_b32 m0, s25
	ds_read_b128 v[174:177], v151 offset:49152
	ds_read_b128 v[184:187], v151 offset:51200
	ds_read_b128 v[188:191], v152 offset:49152
	ds_read_b128 v[192:195], v152 offset:51200
	ds_read_b128 v[196:199], v151 offset:53248
	ds_read_b128 v[200:203], v151 offset:55296
	ds_read_b128 v[204:207], v152 offset:53248
	ds_read_b128 v[208:211], v152 offset:55296
	global_load_lds_dwordx4 v[178:179], off
	s_add_i32 m0, s25, 0x2000
	s_add_u32 s28, s28, 0x80080
	v_lshl_add_u64 v[178:179], v[180:181], 0, s[60:61]
	s_addc_u32 s29, s29, 0
	s_add_i32 s25, s34, s33
	global_load_lds_dwordx4 v[178:179], off
	v_lshl_add_u64 v[178:179], s[28:29], 0, v[34:35]
	s_mov_b32 m0, s25
	s_nop 0
	global_load_lds_dwordx4 v[178:179], off
	v_lshl_add_u64 v[178:179], s[28:29], 0, v[132:133]
	s_add_i32 m0, s25, 0x2000
	s_nop 0
	global_load_lds_dwordx4 v[178:179], off
	v_lshl_add_u64 v[178:179], v[182:183], 0, s[60:61]
	s_mov_b32 m0, s52
	s_nop 0
	global_load_lds_dwordx4 v[178:179], off
	v_lshl_add_u64 v[178:179], v[212:213], 0, s[60:61]
	s_mov_b32 m0, s53
	s_nop 0
	global_load_lds_dwordx4 v[178:179], off
	s_waitcnt vmcnt(8)
	s_waitcnt lgkmcnt(0)
	s_barrier
	s_setprio 1
	s_waitcnt lgkmcnt(0)
	v_mfma_f32_16x16x32_bf16 v[64:67], v[138:141], v[174:177], v[64:67]
	v_mfma_f32_16x16x32_bf16 v[60:63], v[146:149], v[174:177], v[60:63]
	v_mfma_f32_16x16x32_bf16 v[48:51], v[138:141], v[184:187], v[48:51]
	v_mfma_f32_16x16x32_bf16 v[44:47], v[146:149], v[184:187], v[44:47]
	v_mfma_f32_16x16x32_bf16 v[30:33], v[138:141], v[196:199], v[30:33]
	v_mfma_f32_16x16x32_bf16 v[26:29], v[146:149], v[196:199], v[26:29]
	v_mfma_f32_16x16x32_bf16 v[14:17], v[138:141], v[200:203], v[14:17]
	v_mfma_f32_16x16x32_bf16 v[10:13], v[146:149], v[200:203], v[10:13]
	v_mfma_f32_16x16x32_bf16 v[64:67], v[142:145], v[188:191], v[64:67]
	v_mfma_f32_16x16x32_bf16 v[60:63], v[154:157], v[188:191], v[60:63]
	v_mfma_f32_16x16x32_bf16 v[48:51], v[142:145], v[192:195], v[48:51]
	v_mfma_f32_16x16x32_bf16 v[44:47], v[154:157], v[192:195], v[44:47]
	v_mfma_f32_16x16x32_bf16 v[30:33], v[142:145], v[204:207], v[30:33]
	v_mfma_f32_16x16x32_bf16 v[26:29], v[154:157], v[204:207], v[26:29]
	v_mfma_f32_16x16x32_bf16 v[14:17], v[142:145], v[208:211], v[14:17]
	v_mfma_f32_16x16x32_bf16 v[10:13], v[154:157], v[208:211], v[10:13]
	s_setprio 0
	s_setprio 1
	v_mfma_f32_16x16x32_bf16 v[56:59], v[158:161], v[174:177], v[56:59]
	v_mfma_f32_16x16x32_bf16 v[52:55], v[166:169], v[174:177], v[52:55]
	v_mfma_f32_16x16x32_bf16 v[40:43], v[158:161], v[184:187], v[40:43]
	v_mfma_f32_16x16x32_bf16 v[36:39], v[166:169], v[184:187], v[36:39]
	v_mfma_f32_16x16x32_bf16 v[22:25], v[158:161], v[196:199], v[22:25]
	v_mfma_f32_16x16x32_bf16 v[18:21], v[166:169], v[196:199], v[18:21]
	v_mfma_f32_16x16x32_bf16 v[6:9], v[158:161], v[200:203], v[6:9]
	v_mfma_f32_16x16x32_bf16 v[2:5], v[166:169], v[200:203], v[2:5]
	v_mfma_f32_16x16x32_bf16 v[56:59], v[162:165], v[188:191], v[56:59]
	v_mfma_f32_16x16x32_bf16 v[52:55], v[170:173], v[188:191], v[52:55]
	v_mfma_f32_16x16x32_bf16 v[40:43], v[162:165], v[192:195], v[40:43]
	v_mfma_f32_16x16x32_bf16 v[36:39], v[170:173], v[192:195], v[36:39]
	v_mfma_f32_16x16x32_bf16 v[22:25], v[162:165], v[204:207], v[22:25]
	v_mfma_f32_16x16x32_bf16 v[18:21], v[170:173], v[204:207], v[18:21]
	v_mfma_f32_16x16x32_bf16 v[6:9], v[162:165], v[208:211], v[6:9]
	v_mfma_f32_16x16x32_bf16 v[2:5], v[170:173], v[208:211], v[2:5]
	s_setprio 0
	s_barrier
	s_add_i32 s24, s24, 2
	s_add_u32 s8, s8, 0x100
	s_addc_u32 s9, s9, 0
	s_add_u32 s21, s21, 0x100
	s_addc_u32 s23, s23, 0
	s_cmp_gt_u32 s24, 29
	s_cbranch_scc0 .LBB0_1023

.LBB0_1108:
	v_readlane_b32 s28, v254, 16
	v_readlane_b32 s29, v254, 17
	v_mov_b32_e32 v141, v35
	v_readlane_b32 s20, v254, 12
	v_lshl_add_u64 v[2:3], s[28:29], 0, v[34:35]
	v_lshl_add_u64 v[4:5], s[28:29], 0, v[140:141]
	v_mov_b32_e32 v145, v35
	v_readlane_b32 s21, v254, 13
	s_add_i32 m0, s34, 0x18000
	v_lshl_add_u64 v[2:3], v[2:3], 0, s[10:11]
	v_lshl_add_u64 v[6:7], s[20:21], 0, v[144:145]
	v_mov_b32_e32 v143, v35
	s_waitcnt vmcnt(2)
	s_barrier
	global_load_lds_dwordx4 v[2:3], off
	v_lshl_add_u64 v[2:3], v[4:5], 0, s[10:11]
	s_add_i32 m0, s34, 0x1a000
	s_add_i32 s48, s34, 0x8000
	v_lshl_add_u64 v[8:9], s[20:21], 0, v[142:143]
	global_load_lds_dwordx4 v[2:3], off
	v_lshl_add_u64 v[2:3], v[6:7], 0, s[10:11]
	s_mov_b32 m0, s48
	s_add_i32 s49, s34, 0xa000
	global_load_lds_dwordx4 v[2:3], off
	v_lshl_add_u64 v[2:3], v[8:9], 0, s[10:11]
	v_readlane_b32 s10, v254, 18
	s_mov_b32 m0, s49
	v_readlane_b32 s11, v254, 19
	global_load_lds_dwordx4 v[2:3], off
	s_add_i32 m0, s34, 0x1c000
	v_lshl_add_u64 v[2:3], s[10:11], 0, v[34:35]
	global_load_lds_dwordx4 v[2:3], off
	v_lshl_add_u64 v[2:3], s[10:11], 0, v[140:141]
	s_add_i32 m0, s34, 0x1e000
	s_and_b32 s6, s6, 3
	global_load_lds_dwordx4 v[2:3], off
	s_lshl_b32 s46, s9, 6
	s_lshl_b32 s47, s6, 5
	s_lshl_b32 s50, s6, 6
	v_and_b32_e32 v10, 15, v1
	v_lshlrev_b32_e32 v12, 3, v1
	v_and_b32_e32 v1, 48, v1
	s_movk_i32 s7, 0x70
	s_cmpk_lt_u32 s8, 0x100
	v_or_b32_e32 v11, s46, v10
	v_and_b32_e32 v13, 0x70, v12
	v_bitop3_b32 v12, v12, v1, s7 bitop3:0x6c
	s_cselect_b64 s[6:7], -1, 0
	s_and_b32 s8, s8, 0xffffff00
	s_lshl_b32 s9, s9, 8
	v_lshlrev_b32_e32 v11, 7, v11
	v_or_b32_e32 v10, s47, v10
	s_waitcnt vmcnt(6)
	s_add_i32 s51, s9, 0
	s_or_b32 s52, s8, s50
	v_readlane_b32 s8, v254, 6
	v_bitop3_b32 v14, v11, v13, v1 bitop3:0xf6
	v_lshlrev_b32_e32 v10, 7, v10
	v_bitop3_b32 v2, v11, 64, v12 bitop3:0x36
	v_readlane_b32 s9, v254, 7
	v_bitop3_b32 v1, v10, v13, v1 bitop3:0xf6
	v_bitop3_b32 v146, v10, 64, v12 bitop3:0x36
	v_add_u32_e32 v1, 0x10000, v1
	v_add_u32_e32 v146, 0x10000, v146
	s_add_i32 s51, s51, 0x20400
	s_mov_b32 s53, 0
	v_add_u32_e32 v147, 0, v14
	v_add_u32_e32 v148, 0, v2
	v_readlane_b32 s12, v254, 4
	s_mov_b32 s24, s8
	s_mov_b64 s[8:9], s[20:21]
	s_barrier
	s_branch .LBB0_1111

.LBB0_1113:
	s_ashr_i32 s19, s18, 31
	s_lshl_b64 s[20:21], s[18:19], 20
	v_readlane_b32 s22, v254, 38
	v_readlane_b32 s23, v254, 39
	s_add_u32 s22, s22, s20
	s_addc_u32 s23, s23, s21
	s_and_b64 s[20:21], s[38:39], exec
	s_cselect_b32 s13, s23, s9
	s_cselect_b32 s19, s22, s8
	s_ashr_i32 s11, s10, 31
	s_lshl_b64 s[20:21], s[10:11], 20
	v_readlane_b32 s30, v254, 8
	v_readlane_b32 s31, v254, 9
	s_add_u32 s40, s30, s20
	s_addc_u32 s41, s31, s21
	v_mov_b32_e32 v2, v0
	s_and_b64 s[20:21], s[38:39], exec
	s_cselect_b32 s20, s41, s29
	s_cselect_b32 s21, s40, s28
	s_lshl_b32 s11, s24, 8
	v_and_or_b32 v2, v2, 63, s50
	v_or_b32_e32 v2, s11, v2
	v_ashrrev_i32_e32 v3, 31, v2
	v_readlane_b32 s24, v252, 61
	v_lshlrev_b64 v[2:3], 5, v[2:3]
	v_readlane_b32 s25, v252, 62
	s_add_u32 s8, s8, 0x80080
	s_addc_u32 s9, s9, 0
	v_lshl_add_u64 v[2:3], s[24:25], 0, v[2:3]
	global_load_dwordx4 v[116:119], v[2:3], off offset:16
	global_load_dwordx4 v[120:123], v[2:3], off
	s_add_u32 s24, s28, 0x100
	s_addc_u32 s25, s29, 0
	s_mov_b32 s30, -2
	v_readlane_b32 s57, v255, 20
	v_readlane_b32 s58, v255, 21
	v_readlane_b32 s59, v255, 22
	v_readlane_b32 s60, v255, 23
	s_mov_b64 s[62:63], 0x80
	s_add_u32 s28, s8, 0xfff80080
	s_addc_u32 s29, s9, -1
	s_add_i32 s31, 0, 0x10000
	s_cmp_eq_u32 s30, 28
	s_cselect_b32 s43, s13, s29
	s_cselect_b32 s42, s19, s28
	ds_read_b128 v[150:153], v1
	ds_read_b128 v[154:157], v146
	s_cselect_b32 s29, s20, s25
	s_cselect_b32 s28, s21, s24
	s_add_i32 s56, 0, 0x14000
	ds_read_b128 v[158:161], v1 offset:2048
	ds_read_b128 v[162:165], v146 offset:2048
	ds_read_b128 v[166:169], v1 offset:16384
	ds_read_b128 v[170:173], v146 offset:16384
	ds_read_b128 v[174:177], v1 offset:18432
	ds_read_b128 v[184:187], v146 offset:18432
	v_lshl_add_u64 v[178:179], s[8:9], 0, v[144:145]
	s_add_i32 m0, s34, 0xc000
	ds_read_b128 v[188:191], v147
	ds_read_b128 v[192:195], v147 offset:2048
	ds_read_b128 v[196:199], v148
	ds_read_b128 v[200:203], v148 offset:2048
	ds_read_b128 v[204:207], v147 offset:4096
	ds_read_b128 v[208:211], v147 offset:6144
	ds_read_b128 v[224:227], v148 offset:4096
	ds_read_b128 v[228:231], v148 offset:6144
	global_load_lds_dwordx4 v[178:179], off
	v_lshl_add_u64 v[178:179], s[8:9], 0, v[142:143]
	s_add_i32 m0, s34, 0xe000
	s_nop 0
	global_load_lds_dwordx4 v[178:179], off
	s_waitcnt vmcnt(8)
	s_waitcnt lgkmcnt(0)
	s_barrier
	s_setprio 1
	s_waitcnt lgkmcnt(0)
	v_mfma_f32_16x16x32_bf16 v[132:135], v[150:153], v[188:191], 0
	v_mfma_f32_16x16x32_bf16 v[124:127], v[158:161], v[188:191], 0
	v_mfma_f32_16x16x32_bf16 v[108:111], v[150:153], v[192:195], 0
	v_mfma_f32_16x16x32_bf16 v[100:103], v[158:161], v[192:195], 0
	v_mfma_f32_16x16x32_bf16 v[92:95], v[150:153], v[204:207], 0
	v_mfma_f32_16x16x32_bf16 v[84:87], v[158:161], v[204:207], 0
	v_mfma_f32_16x16x32_bf16 v[76:79], v[150:153], v[208:211], 0
	v_mfma_f32_16x16x32_bf16 v[68:71], v[158:161], v[208:211], 0
	v_mfma_f32_16x16x32_bf16 v[132:135], v[154:157], v[196:199], v[132:135]
	v_mfma_f32_16x16x32_bf16 v[124:127], v[162:165], v[196:199], v[124:127]
	v_mfma_f32_16x16x32_bf16 v[108:111], v[154:157], v[200:203], v[108:111]
	v_mfma_f32_16x16x32_bf16 v[100:103], v[162:165], v[200:203], v[100:103]
	v_mfma_f32_16x16x32_bf16 v[92:95], v[154:157], v[224:227], v[92:95]
	v_mfma_f32_16x16x32_bf16 v[84:87], v[162:165], v[224:227], v[84:87]
	v_mfma_f32_16x16x32_bf16 v[76:79], v[154:157], v[228:231], v[76:79]
	v_mfma_f32_16x16x32_bf16 v[68:71], v[162:165], v[228:231], v[68:71]
	s_setprio 0
	s_setprio 1
	v_mfma_f32_16x16x32_bf16 v[136:139], v[166:169], v[188:191], 0
	v_mfma_f32_16x16x32_bf16 v[128:131], v[174:177], v[188:191], 0
	v_mfma_f32_16x16x32_bf16 v[112:115], v[166:169], v[192:195], 0
	v_mfma_f32_16x16x32_bf16 v[104:107], v[174:177], v[192:195], 0
	v_mfma_f32_16x16x32_bf16 v[96:99], v[166:169], v[204:207], 0
	v_mfma_f32_16x16x32_bf16 v[88:91], v[174:177], v[204:207], 0
	v_mfma_f32_16x16x32_bf16 v[80:83], v[166:169], v[208:211], 0
	v_mfma_f32_16x16x32_bf16 v[72:75], v[174:177], v[208:211], 0
	v_mfma_f32_16x16x32_bf16 v[136:139], v[170:173], v[196:199], v[136:139]
	v_mfma_f32_16x16x32_bf16 v[128:131], v[184:187], v[196:199], v[128:131]
	v_mfma_f32_16x16x32_bf16 v[112:115], v[170:173], v[200:203], v[112:115]
	v_mfma_f32_16x16x32_bf16 v[104:107], v[184:187], v[200:203], v[104:107]
	v_mfma_f32_16x16x32_bf16 v[96:99], v[170:173], v[224:227], v[96:99]
	v_mfma_f32_16x16x32_bf16 v[88:91], v[184:187], v[224:227], v[88:91]
	v_mfma_f32_16x16x32_bf16 v[80:83], v[170:173], v[228:231], v[80:83]
	v_mfma_f32_16x16x32_bf16 v[72:75], v[184:187], v[228:231], v[72:75]
	s_setprio 0
	s_barrier
	s_add_i32 s31, s31, s33
	v_lshl_add_u64 v[178:179], s[28:29], 0, v[34:35]
	s_mov_b32 m0, s31
	ds_read_b128 v[188:191], v147 offset:16384
	ds_read_b128 v[192:195], v147 offset:18432
	ds_read_b128 v[196:199], v148 offset:16384
	ds_read_b128 v[200:203], v148 offset:18432
	ds_read_b128 v[204:207], v147 offset:20480
	ds_read_b128 v[208:211], v147 offset:22528
	ds_read_b128 v[224:227], v148 offset:20480
	ds_read_b128 v[228:231], v148 offset:22528
	global_load_lds_dwordx4 v[178:179], off
	s_add_i32 m0, s31, 0x2000
	s_add_u32 s54, s28, 0x80000
	v_lshl_add_u64 v[180:181], s[28:29], 0, v[140:141]
	s_addc_u32 s55, s29, 0
	s_add_i32 s31, s56, s33
	global_load_lds_dwordx4 v[180:181], off
	v_lshl_add_u64 v[182:183], s[54:55], 0, v[34:35]
	s_mov_b32 m0, s31
	v_lshl_add_u64 v[212:213], s[42:43], 0, v[142:143]
	global_load_lds_dwordx4 v[182:183], off
	v_lshl_add_u64 v[182:183], s[54:55], 0, v[140:141]
	s_add_i32 m0, s31, 0x2000
	s_nop 0
	global_load_lds_dwordx4 v[182:183], off
	v_lshl_add_u64 v[182:183], s[42:43], 0, v[144:145]
	s_mov_b32 m0, s34
	s_nop 0
	global_load_lds_dwordx4 v[182:183], off
	s_mov_b32 m0, s35
	s_nop 0
	global_load_lds_dwordx4 v[212:213], off
	s_waitcnt vmcnt(8)
	s_waitcnt lgkmcnt(0)
	s_barrier
	s_setprio 1
	s_waitcnt lgkmcnt(0)
	v_mfma_f32_16x16x32_bf16 v[60:63], v[150:153], v[188:191], 0
	v_mfma_f32_16x16x32_bf16 v[52:55], v[158:161], v[188:191], 0
	v_mfma_f32_16x16x32_bf16 v[44:47], v[150:153], v[192:195], 0
	v_mfma_f32_16x16x32_bf16 v[36:39], v[158:161], v[192:195], 0
	v_mfma_f32_16x16x32_bf16 v[26:29], v[150:153], v[204:207], 0
	v_mfma_f32_16x16x32_bf16 v[18:21], v[158:161], v[204:207], 0
	v_mfma_f32_16x16x32_bf16 v[10:13], v[150:153], v[208:211], 0
	v_mfma_f32_16x16x32_bf16 v[6:9], v[158:161], v[208:211], 0
	v_mfma_f32_16x16x32_bf16 v[60:63], v[154:157], v[196:199], v[60:63]
	v_mfma_f32_16x16x32_bf16 v[52:55], v[162:165], v[196:199], v[52:55]
	v_mfma_f32_16x16x32_bf16 v[44:47], v[154:157], v[200:203], v[44:47]
	v_mfma_f32_16x16x32_bf16 v[36:39], v[162:165], v[200:203], v[36:39]
	v_mfma_f32_16x16x32_bf16 v[26:29], v[154:157], v[224:227], v[26:29]
	v_mfma_f32_16x16x32_bf16 v[18:21], v[162:165], v[224:227], v[18:21]
	v_mfma_f32_16x16x32_bf16 v[10:13], v[154:157], v[228:231], v[10:13]
	v_mfma_f32_16x16x32_bf16 v[6:9], v[162:165], v[228:231], v[6:9]
	s_setprio 0
	s_setprio 1
	v_mfma_f32_16x16x32_bf16 v[64:67], v[166:169], v[188:191], 0
	v_mfma_f32_16x16x32_bf16 v[56:59], v[174:177], v[188:191], 0
	v_mfma_f32_16x16x32_bf16 v[48:51], v[166:169], v[192:195], 0
	v_mfma_f32_16x16x32_bf16 v[40:43], v[174:177], v[192:195], 0
	v_mfma_f32_16x16x32_bf16 v[30:33], v[166:169], v[204:207], 0
	v_mfma_f32_16x16x32_bf16 v[22:25], v[174:177], v[204:207], 0
	v_mfma_f32_16x16x32_bf16 v[14:17], v[166:169], v[208:211], 0
	v_mfma_f32_16x16x32_bf16 v[2:5], v[174:177], v[208:211], 0
	v_mfma_f32_16x16x32_bf16 v[64:67], v[170:173], v[196:199], v[64:67]
	v_mfma_f32_16x16x32_bf16 v[56:59], v[184:187], v[196:199], v[56:59]
	v_mfma_f32_16x16x32_bf16 v[48:51], v[170:173], v[200:203], v[48:51]
	v_mfma_f32_16x16x32_bf16 v[40:43], v[184:187], v[200:203], v[40:43]
	v_mfma_f32_16x16x32_bf16 v[30:33], v[170:173], v[224:227], v[30:33]
	v_mfma_f32_16x16x32_bf16 v[22:25], v[184:187], v[224:227], v[22:25]
	v_mfma_f32_16x16x32_bf16 v[14:17], v[170:173], v[228:231], v[14:17]
	v_mfma_f32_16x16x32_bf16 v[2:5], v[184:187], v[228:231], v[2:5]
	s_setprio 0
	s_barrier
	s_add_i32 s31, 0, 0x18000
	ds_read_b128 v[150:153], v1 offset:32768
	ds_read_b128 v[154:157], v146 offset:32768
	s_add_i32 s54, 0, 0x1c000
	ds_read_b128 v[158:161], v1 offset:34816
	ds_read_b128 v[162:165], v146 offset:34816
	ds_read_b128 v[166:169], v1 offset:49152
	ds_read_b128 v[170:173], v146 offset:49152
	ds_read_b128 v[174:177], v1 offset:51200
	ds_read_b128 v[184:187], v146 offset:51200
	s_add_u32 s42, s42, 0x80000
	s_addc_u32 s43, s43, 0
	s_mov_b32 m0, s44
	v_lshl_add_u64 v[218:219], s[42:43], 0, v[144:145]
	ds_read_b128 v[188:191], v147 offset:32768
	ds_read_b128 v[192:195], v147 offset:34816
	ds_read_b128 v[196:199], v148 offset:32768
	ds_read_b128 v[200:203], v148 offset:34816
	ds_read_b128 v[204:207], v147 offset:36864
	ds_read_b128 v[208:211], v147 offset:38912
	ds_read_b128 v[224:227], v148 offset:36864
	ds_read_b128 v[228:231], v148 offset:38912
	global_load_lds_dwordx4 v[218:219], off
	v_lshl_add_u64 v[218:219], s[42:43], 0, v[142:143]
	s_mov_b32 m0, s45
	s_nop 0
	global_load_lds_dwordx4 v[218:219], off
	s_waitcnt vmcnt(8)
	s_waitcnt lgkmcnt(0)
	s_barrier
	s_setprio 1
	s_waitcnt lgkmcnt(0)
	v_mfma_f32_16x16x32_bf16 v[132:135], v[150:153], v[188:191], v[132:135]
	v_mfma_f32_16x16x32_bf16 v[124:127], v[158:161], v[188:191], v[124:127]
	v_mfma_f32_16x16x32_bf16 v[108:111], v[150:153], v[192:195], v[108:111]
	v_mfma_f32_16x16x32_bf16 v[100:103], v[158:161], v[192:195], v[100:103]
	v_mfma_f32_16x16x32_bf16 v[92:95], v[150:153], v[204:207], v[92:95]
	v_mfma_f32_16x16x32_bf16 v[84:87], v[158:161], v[204:207], v[84:87]
	v_mfma_f32_16x16x32_bf16 v[76:79], v[150:153], v[208:211], v[76:79]
	v_mfma_f32_16x16x32_bf16 v[68:71], v[158:161], v[208:211], v[68:71]
	v_mfma_f32_16x16x32_bf16 v[132:135], v[154:157], v[196:199], v[132:135]
	v_mfma_f32_16x16x32_bf16 v[124:127], v[162:165], v[196:199], v[124:127]
	v_mfma_f32_16x16x32_bf16 v[108:111], v[154:157], v[200:203], v[108:111]
	v_mfma_f32_16x16x32_bf16 v[100:103], v[162:165], v[200:203], v[100:103]
	v_mfma_f32_16x16x32_bf16 v[92:95], v[154:157], v[224:227], v[92:95]
	v_mfma_f32_16x16x32_bf16 v[84:87], v[162:165], v[224:227], v[84:87]
	v_mfma_f32_16x16x32_bf16 v[76:79], v[154:157], v[228:231], v[76:79]
	v_mfma_f32_16x16x32_bf16 v[68:71], v[162:165], v[228:231], v[68:71]
	s_setprio 0
	s_setprio 1
	v_mfma_f32_16x16x32_bf16 v[136:139], v[166:169], v[188:191], v[136:139]
	v_mfma_f32_16x16x32_bf16 v[128:131], v[174:177], v[188:191], v[128:131]
	v_mfma_f32_16x16x32_bf16 v[112:115], v[166:169], v[192:195], v[112:115]
	v_mfma_f32_16x16x32_bf16 v[104:107], v[174:177], v[192:195], v[104:107]
	v_mfma_f32_16x16x32_bf16 v[96:99], v[166:169], v[204:207], v[96:99]
	v_mfma_f32_16x16x32_bf16 v[88:91], v[174:177], v[204:207], v[88:91]
	v_mfma_f32_16x16x32_bf16 v[80:83], v[166:169], v[208:211], v[80:83]
	v_mfma_f32_16x16x32_bf16 v[72:75], v[174:177], v[208:211], v[72:75]
	v_mfma_f32_16x16x32_bf16 v[136:139], v[170:173], v[196:199], v[136:139]
	v_mfma_f32_16x16x32_bf16 v[128:131], v[184:187], v[196:199], v[128:131]
	v_mfma_f32_16x16x32_bf16 v[112:115], v[170:173], v[200:203], v[112:115]
	v_mfma_f32_16x16x32_bf16 v[104:107], v[184:187], v[200:203], v[104:107]
	v_mfma_f32_16x16x32_bf16 v[96:99], v[170:173], v[224:227], v[96:99]
	v_mfma_f32_16x16x32_bf16 v[88:91], v[184:187], v[224:227], v[88:91]
	v_mfma_f32_16x16x32_bf16 v[80:83], v[170:173], v[228:231], v[80:83]
	v_mfma_f32_16x16x32_bf16 v[72:75], v[184:187], v[228:231], v[72:75]
	s_setprio 0
	s_barrier
	s_add_i32 s31, s31, s33
	v_lshl_add_u64 v[178:179], v[178:179], 0, s[62:63]
	s_mov_b32 m0, s31
	ds_read_b128 v[188:191], v147 offset:49152
	ds_read_b128 v[192:195], v147 offset:51200
	ds_read_b128 v[196:199], v148 offset:49152
	ds_read_b128 v[200:203], v148 offset:51200
	ds_read_b128 v[204:207], v147 offset:53248
	ds_read_b128 v[208:211], v147 offset:55296
	ds_read_b128 v[224:227], v148 offset:53248
	ds_read_b128 v[228:231], v148 offset:55296
	global_load_lds_dwordx4 v[178:179], off
	s_add_i32 m0, s31, 0x2000
	s_add_u32 s28, s28, 0x80080
	v_lshl_add_u64 v[178:179], v[180:181], 0, s[62:63]
	s_addc_u32 s29, s29, 0
	s_add_i32 s31, s54, s33
	global_load_lds_dwordx4 v[178:179], off
	v_lshl_add_u64 v[178:179], s[28:29], 0, v[34:35]
	s_mov_b32 m0, s31
	s_nop 0
	global_load_lds_dwordx4 v[178:179], off
	v_lshl_add_u64 v[178:179], s[28:29], 0, v[140:141]
	s_add_i32 m0, s31, 0x2000
	s_nop 0
	global_load_lds_dwordx4 v[178:179], off
	v_lshl_add_u64 v[178:179], v[182:183], 0, s[62:63]
	s_mov_b32 m0, s48
	s_nop 0
	global_load_lds_dwordx4 v[178:179], off
	v_lshl_add_u64 v[178:179], v[212:213], 0, s[62:63]
	s_mov_b32 m0, s49
	s_nop 0
	global_load_lds_dwordx4 v[178:179], off
	s_waitcnt vmcnt(8)
	s_waitcnt lgkmcnt(0)
	s_barrier
	s_setprio 1
	s_waitcnt lgkmcnt(0)
	v_mfma_f32_16x16x32_bf16 v[60:63], v[150:153], v[188:191], v[60:63]
	v_mfma_f32_16x16x32_bf16 v[52:55], v[158:161], v[188:191], v[52:55]
	v_mfma_f32_16x16x32_bf16 v[44:47], v[150:153], v[192:195], v[44:47]
	v_mfma_f32_16x16x32_bf16 v[36:39], v[158:161], v[192:195], v[36:39]
	v_mfma_f32_16x16x32_bf16 v[26:29], v[150:153], v[204:207], v[26:29]
	v_mfma_f32_16x16x32_bf16 v[18:21], v[158:161], v[204:207], v[18:21]
	v_mfma_f32_16x16x32_bf16 v[10:13], v[150:153], v[208:211], v[10:13]
	v_mfma_f32_16x16x32_bf16 v[6:9], v[158:161], v[208:211], v[6:9]
	v_mfma_f32_16x16x32_bf16 v[60:63], v[154:157], v[196:199], v[60:63]
	v_mfma_f32_16x16x32_bf16 v[52:55], v[162:165], v[196:199], v[52:55]
	v_mfma_f32_16x16x32_bf16 v[44:47], v[154:157], v[200:203], v[44:47]
	v_mfma_f32_16x16x32_bf16 v[36:39], v[162:165], v[200:203], v[36:39]
	v_mfma_f32_16x16x32_bf16 v[26:29], v[154:157], v[224:227], v[26:29]
	v_mfma_f32_16x16x32_bf16 v[18:21], v[162:165], v[224:227], v[18:21]
	v_mfma_f32_16x16x32_bf16 v[10:13], v[154:157], v[228:231], v[10:13]
	v_mfma_f32_16x16x32_bf16 v[6:9], v[162:165], v[228:231], v[6:9]
	s_setprio 0
	s_setprio 1
	v_mfma_f32_16x16x32_bf16 v[64:67], v[166:169], v[188:191], v[64:67]
	v_mfma_f32_16x16x32_bf16 v[56:59], v[174:177], v[188:191], v[56:59]
	v_mfma_f32_16x16x32_bf16 v[48:51], v[166:169], v[192:195], v[48:51]
	v_mfma_f32_16x16x32_bf16 v[40:43], v[174:177], v[192:195], v[40:43]
	v_mfma_f32_16x16x32_bf16 v[30:33], v[166:169], v[204:207], v[30:33]
	v_mfma_f32_16x16x32_bf16 v[22:25], v[174:177], v[204:207], v[22:25]
	v_mfma_f32_16x16x32_bf16 v[14:17], v[166:169], v[208:211], v[14:17]
	v_mfma_f32_16x16x32_bf16 v[2:5], v[174:177], v[208:211], v[2:5]
	v_mfma_f32_16x16x32_bf16 v[64:67], v[170:173], v[196:199], v[64:67]
	v_mfma_f32_16x16x32_bf16 v[56:59], v[184:187], v[196:199], v[56:59]
	v_mfma_f32_16x16x32_bf16 v[48:51], v[170:173], v[200:203], v[48:51]
	v_mfma_f32_16x16x32_bf16 v[40:43], v[184:187], v[200:203], v[40:43]
	v_mfma_f32_16x16x32_bf16 v[30:33], v[170:173], v[224:227], v[30:33]
	v_mfma_f32_16x16x32_bf16 v[22:25], v[184:187], v[224:227], v[22:25]
	v_mfma_f32_16x16x32_bf16 v[14:17], v[170:173], v[228:231], v[14:17]
	v_mfma_f32_16x16x32_bf16 v[2:5], v[184:187], v[228:231], v[2:5]
	s_setprio 0
	s_barrier
	s_add_i32 s30, s30, 2
	s_add_u32 s8, s8, 0x100
	s_addc_u32 s9, s9, 0
	s_add_u32 s24, s24, 0x100
	s_addc_u32 s25, s25, 0
	s_cmp_gt_u32 s30, 29
	s_cbranch_scc1 .Lpeel_done_P6
.LBB0_1114:
	s_add_u32 s28, s8, 0xfff80080
	s_addc_u32 s29, s9, -1
	s_add_i32 s31, 0, 0x10000
	s_cmp_eq_u32 s30, 28
	s_cselect_b32 s43, s13, s29
	s_cselect_b32 s42, s19, s28
	ds_read_b128 v[150:153], v1
	ds_read_b128 v[154:157], v146
	s_cselect_b32 s29, s20, s25
	s_cselect_b32 s28, s21, s24
	s_add_i32 s56, 0, 0x14000
	ds_read_b128 v[158:161], v1 offset:2048
	ds_read_b128 v[162:165], v146 offset:2048
	ds_read_b128 v[166:169], v1 offset:16384
	ds_read_b128 v[170:173], v146 offset:16384
	ds_read_b128 v[174:177], v1 offset:18432
	ds_read_b128 v[184:187], v146 offset:18432
	v_lshl_add_u64 v[178:179], s[8:9], 0, v[144:145]
	s_add_i32 m0, s34, 0xc000
	ds_read_b128 v[188:191], v147
	ds_read_b128 v[192:195], v147 offset:2048
	ds_read_b128 v[196:199], v148
	ds_read_b128 v[200:203], v148 offset:2048
	ds_read_b128 v[204:207], v147 offset:4096
	ds_read_b128 v[208:211], v147 offset:6144
	ds_read_b128 v[224:227], v148 offset:4096
	ds_read_b128 v[228:231], v148 offset:6144
	global_load_lds_dwordx4 v[178:179], off
	v_lshl_add_u64 v[178:179], s[8:9], 0, v[142:143]
	s_add_i32 m0, s34, 0xe000
	s_nop 0
	global_load_lds_dwordx4 v[178:179], off
	s_waitcnt vmcnt(8)
	s_waitcnt lgkmcnt(0)
	s_barrier
	s_setprio 1
	s_waitcnt lgkmcnt(0)
	v_mfma_f32_16x16x32_bf16 v[132:135], v[150:153], v[188:191], v[132:135]
	v_mfma_f32_16x16x32_bf16 v[124:127], v[158:161], v[188:191], v[124:127]
	v_mfma_f32_16x16x32_bf16 v[108:111], v[150:153], v[192:195], v[108:111]
	v_mfma_f32_16x16x32_bf16 v[100:103], v[158:161], v[192:195], v[100:103]
	v_mfma_f32_16x16x32_bf16 v[92:95], v[150:153], v[204:207], v[92:95]
	v_mfma_f32_16x16x32_bf16 v[84:87], v[158:161], v[204:207], v[84:87]
	v_mfma_f32_16x16x32_bf16 v[76:79], v[150:153], v[208:211], v[76:79]
	v_mfma_f32_16x16x32_bf16 v[68:71], v[158:161], v[208:211], v[68:71]
	v_mfma_f32_16x16x32_bf16 v[132:135], v[154:157], v[196:199], v[132:135]
	v_mfma_f32_16x16x32_bf16 v[124:127], v[162:165], v[196:199], v[124:127]
	v_mfma_f32_16x16x32_bf16 v[108:111], v[154:157], v[200:203], v[108:111]
	v_mfma_f32_16x16x32_bf16 v[100:103], v[162:165], v[200:203], v[100:103]
	v_mfma_f32_16x16x32_bf16 v[92:95], v[154:157], v[224:227], v[92:95]
	v_mfma_f32_16x16x32_bf16 v[84:87], v[162:165], v[224:227], v[84:87]
	v_mfma_f32_16x16x32_bf16 v[76:79], v[154:157], v[228:231], v[76:79]
	v_mfma_f32_16x16x32_bf16 v[68:71], v[162:165], v[228:231], v[68:71]
	s_setprio 0
	s_setprio 1
	v_mfma_f32_16x16x32_bf16 v[136:139], v[166:169], v[188:191], v[136:139]
	v_mfma_f32_16x16x32_bf16 v[128:131], v[174:177], v[188:191], v[128:131]
	v_mfma_f32_16x16x32_bf16 v[112:115], v[166:169], v[192:195], v[112:115]
	v_mfma_f32_16x16x32_bf16 v[104:107], v[174:177], v[192:195], v[104:107]
	v_mfma_f32_16x16x32_bf16 v[96:99], v[166:169], v[204:207], v[96:99]
	v_mfma_f32_16x16x32_bf16 v[88:91], v[174:177], v[204:207], v[88:91]
	v_mfma_f32_16x16x32_bf16 v[80:83], v[166:169], v[208:211], v[80:83]
	v_mfma_f32_16x16x32_bf16 v[72:75], v[174:177], v[208:211], v[72:75]
	v_mfma_f32_16x16x32_bf16 v[136:139], v[170:173], v[196:199], v[136:139]
	v_mfma_f32_16x16x32_bf16 v[128:131], v[184:187], v[196:199], v[128:131]
	v_mfma_f32_16x16x32_bf16 v[112:115], v[170:173], v[200:203], v[112:115]
	v_mfma_f32_16x16x32_bf16 v[104:107], v[184:187], v[200:203], v[104:107]
	v_mfma_f32_16x16x32_bf16 v[96:99], v[170:173], v[224:227], v[96:99]
	v_mfma_f32_16x16x32_bf16 v[88:91], v[184:187], v[224:227], v[88:91]
	v_mfma_f32_16x16x32_bf16 v[80:83], v[170:173], v[228:231], v[80:83]
	v_mfma_f32_16x16x32_bf16 v[72:75], v[184:187], v[228:231], v[72:75]
	s_setprio 0
	s_barrier
	s_add_i32 s31, s31, s33
	v_lshl_add_u64 v[178:179], s[28:29], 0, v[34:35]
	s_mov_b32 m0, s31
	ds_read_b128 v[188:191], v147 offset:16384
	ds_read_b128 v[192:195], v147 offset:18432
	ds_read_b128 v[196:199], v148 offset:16384
	ds_read_b128 v[200:203], v148 offset:18432
	ds_read_b128 v[204:207], v147 offset:20480
	ds_read_b128 v[208:211], v147 offset:22528
	ds_read_b128 v[224:227], v148 offset:20480
	ds_read_b128 v[228:231], v148 offset:22528
	global_load_lds_dwordx4 v[178:179], off
	s_add_i32 m0, s31, 0x2000
	s_add_u32 s54, s28, 0x80000
	v_lshl_add_u64 v[180:181], s[28:29], 0, v[140:141]
	s_addc_u32 s55, s29, 0
	s_add_i32 s31, s56, s33
	global_load_lds_dwordx4 v[180:181], off
	v_lshl_add_u64 v[182:183], s[54:55], 0, v[34:35]
	s_mov_b32 m0, s31
	v_lshl_add_u64 v[212:213], s[42:43], 0, v[142:143]
	global_load_lds_dwordx4 v[182:183], off
	v_lshl_add_u64 v[182:183], s[54:55], 0, v[140:141]
	s_add_i32 m0, s31, 0x2000
	s_nop 0
	global_load_lds_dwordx4 v[182:183], off
	v_lshl_add_u64 v[182:183], s[42:43], 0, v[144:145]
	s_mov_b32 m0, s34
	s_nop 0
	global_load_lds_dwordx4 v[182:183], off
	s_mov_b32 m0, s35
	s_nop 0
	global_load_lds_dwordx4 v[212:213], off
	s_waitcnt vmcnt(8)
	s_waitcnt lgkmcnt(0)
	s_barrier
	s_setprio 1
	s_waitcnt lgkmcnt(0)
	v_mfma_f32_16x16x32_bf16 v[60:63], v[150:153], v[188:191], v[60:63]
	v_mfma_f32_16x16x32_bf16 v[52:55], v[158:161], v[188:191], v[52:55]
	v_mfma_f32_16x16x32_bf16 v[44:47], v[150:153], v[192:195], v[44:47]
	v_mfma_f32_16x16x32_bf16 v[36:39], v[158:161], v[192:195], v[36:39]
	v_mfma_f32_16x16x32_bf16 v[26:29], v[150:153], v[204:207], v[26:29]
	v_mfma_f32_16x16x32_bf16 v[18:21], v[158:161], v[204:207], v[18:21]
	v_mfma_f32_16x16x32_bf16 v[10:13], v[150:153], v[208:211], v[10:13]
	v_mfma_f32_16x16x32_bf16 v[6:9], v[158:161], v[208:211], v[6:9]
	v_mfma_f32_16x16x32_bf16 v[60:63], v[154:157], v[196:199], v[60:63]
	v_mfma_f32_16x16x32_bf16 v[52:55], v[162:165], v[196:199], v[52:55]
	v_mfma_f32_16x16x32_bf16 v[44:47], v[154:157], v[200:203], v[44:47]
	v_mfma_f32_16x16x32_bf16 v[36:39], v[162:165], v[200:203], v[36:39]
	v_mfma_f32_16x16x32_bf16 v[26:29], v[154:157], v[224:227], v[26:29]
	v_mfma_f32_16x16x32_bf16 v[18:21], v[162:165], v[224:227], v[18:21]
	v_mfma_f32_16x16x32_bf16 v[10:13], v[154:157], v[228:231], v[10:13]
	v_mfma_f32_16x16x32_bf16 v[6:9], v[162:165], v[228:231], v[6:9]
	s_setprio 0
	s_setprio 1
	v_mfma_f32_16x16x32_bf16 v[64:67], v[166:169], v[188:191], v[64:67]
	v_mfma_f32_16x16x32_bf16 v[56:59], v[174:177], v[188:191], v[56:59]
	v_mfma_f32_16x16x32_bf16 v[48:51], v[166:169], v[192:195], v[48:51]
	v_mfma_f32_16x16x32_bf16 v[40:43], v[174:177], v[192:195], v[40:43]
	v_mfma_f32_16x16x32_bf16 v[30:33], v[166:169], v[204:207], v[30:33]
	v_mfma_f32_16x16x32_bf16 v[22:25], v[174:177], v[204:207], v[22:25]
	v_mfma_f32_16x16x32_bf16 v[14:17], v[166:169], v[208:211], v[14:17]
	v_mfma_f32_16x16x32_bf16 v[2:5], v[174:177], v[208:211], v[2:5]
	v_mfma_f32_16x16x32_bf16 v[64:67], v[170:173], v[196:199], v[64:67]
	v_mfma_f32_16x16x32_bf16 v[56:59], v[184:187], v[196:199], v[56:59]
	v_mfma_f32_16x16x32_bf16 v[48:51], v[170:173], v[200:203], v[48:51]
	v_mfma_f32_16x16x32_bf16 v[40:43], v[184:187], v[200:203], v[40:43]
	v_mfma_f32_16x16x32_bf16 v[30:33], v[170:173], v[224:227], v[30:33]
	v_mfma_f32_16x16x32_bf16 v[22:25], v[184:187], v[224:227], v[22:25]
	v_mfma_f32_16x16x32_bf16 v[14:17], v[170:173], v[228:231], v[14:17]
	v_mfma_f32_16x16x32_bf16 v[2:5], v[184:187], v[228:231], v[2:5]
	s_setprio 0
	s_barrier
	s_add_i32 s31, 0, 0x18000
	ds_read_b128 v[150:153], v1 offset:32768
	ds_read_b128 v[154:157], v146 offset:32768
	s_add_i32 s54, 0, 0x1c000
	ds_read_b128 v[158:161], v1 offset:34816
	ds_read_b128 v[162:165], v146 offset:34816
	ds_read_b128 v[166:169], v1 offset:49152
	ds_read_b128 v[170:173], v146 offset:49152
	ds_read_b128 v[174:177], v1 offset:51200
	ds_read_b128 v[184:187], v146 offset:51200
	s_add_u32 s42, s42, 0x80000
	s_addc_u32 s43, s43, 0
	s_mov_b32 m0, s44
	v_lshl_add_u64 v[218:219], s[42:43], 0, v[144:145]
	ds_read_b128 v[188:191], v147 offset:32768
	ds_read_b128 v[192:195], v147 offset:34816
	ds_read_b128 v[196:199], v148 offset:32768
	ds_read_b128 v[200:203], v148 offset:34816
	ds_read_b128 v[204:207], v147 offset:36864
	ds_read_b128 v[208:211], v147 offset:38912
	ds_read_b128 v[224:227], v148 offset:36864
	ds_read_b128 v[228:231], v148 offset:38912
	global_load_lds_dwordx4 v[218:219], off
	v_lshl_add_u64 v[218:219], s[42:43], 0, v[142:143]
	s_mov_b32 m0, s45
	s_nop 0
	global_load_lds_dwordx4 v[218:219], off
	s_waitcnt vmcnt(8)
	s_waitcnt lgkmcnt(0)
	s_barrier
	s_setprio 1
	s_waitcnt lgkmcnt(0)
	v_mfma_f32_16x16x32_bf16 v[132:135], v[150:153], v[188:191], v[132:135]
	v_mfma_f32_16x16x32_bf16 v[124:127], v[158:161], v[188:191], v[124:127]
	v_mfma_f32_16x16x32_bf16 v[108:111], v[150:153], v[192:195], v[108:111]
	v_mfma_f32_16x16x32_bf16 v[100:103], v[158:161], v[192:195], v[100:103]
	v_mfma_f32_16x16x32_bf16 v[92:95], v[150:153], v[204:207], v[92:95]
	v_mfma_f32_16x16x32_bf16 v[84:87], v[158:161], v[204:207], v[84:87]
	v_mfma_f32_16x16x32_bf16 v[76:79], v[150:153], v[208:211], v[76:79]
	v_mfma_f32_16x16x32_bf16 v[68:71], v[158:161], v[208:211], v[68:71]
	v_mfma_f32_16x16x32_bf16 v[132:135], v[154:157], v[196:199], v[132:135]
	v_mfma_f32_16x16x32_bf16 v[124:127], v[162:165], v[196:199], v[124:127]
	v_mfma_f32_16x16x32_bf16 v[108:111], v[154:157], v[200:203], v[108:111]
	v_mfma_f32_16x16x32_bf16 v[100:103], v[162:165], v[200:203], v[100:103]
	v_mfma_f32_16x16x32_bf16 v[92:95], v[154:157], v[224:227], v[92:95]
	v_mfma_f32_16x16x32_bf16 v[84:87], v[162:165], v[224:227], v[84:87]
	v_mfma_f32_16x16x32_bf16 v[76:79], v[154:157], v[228:231], v[76:79]
	v_mfma_f32_16x16x32_bf16 v[68:71], v[162:165], v[228:231], v[68:71]
	s_setprio 0
	s_setprio 1
	v_mfma_f32_16x16x32_bf16 v[136:139], v[166:169], v[188:191], v[136:139]
	v_mfma_f32_16x16x32_bf16 v[128:131], v[174:177], v[188:191], v[128:131]
	v_mfma_f32_16x16x32_bf16 v[112:115], v[166:169], v[192:195], v[112:115]
	v_mfma_f32_16x16x32_bf16 v[104:107], v[174:177], v[192:195], v[104:107]
	v_mfma_f32_16x16x32_bf16 v[96:99], v[166:169], v[204:207], v[96:99]
	v_mfma_f32_16x16x32_bf16 v[88:91], v[174:177], v[204:207], v[88:91]
	v_mfma_f32_16x16x32_bf16 v[80:83], v[166:169], v[208:211], v[80:83]
	v_mfma_f32_16x16x32_bf16 v[72:75], v[174:177], v[208:211], v[72:75]
	v_mfma_f32_16x16x32_bf16 v[136:139], v[170:173], v[196:199], v[136:139]
	v_mfma_f32_16x16x32_bf16 v[128:131], v[184:187], v[196:199], v[128:131]
	v_mfma_f32_16x16x32_bf16 v[112:115], v[170:173], v[200:203], v[112:115]
	v_mfma_f32_16x16x32_bf16 v[104:107], v[184:187], v[200:203], v[104:107]
	v_mfma_f32_16x16x32_bf16 v[96:99], v[170:173], v[224:227], v[96:99]
	v_mfma_f32_16x16x32_bf16 v[88:91], v[184:187], v[224:227], v[88:91]
	v_mfma_f32_16x16x32_bf16 v[80:83], v[170:173], v[228:231], v[80:83]
	v_mfma_f32_16x16x32_bf16 v[72:75], v[184:187], v[228:231], v[72:75]
	s_setprio 0
	s_barrier
	s_add_i32 s31, s31, s33
	v_lshl_add_u64 v[178:179], v[178:179], 0, s[62:63]
	s_mov_b32 m0, s31
	ds_read_b128 v[188:191], v147 offset:49152
	ds_read_b128 v[192:195], v147 offset:51200
	ds_read_b128 v[196:199], v148 offset:49152
	ds_read_b128 v[200:203], v148 offset:51200
	ds_read_b128 v[204:207], v147 offset:53248
	ds_read_b128 v[208:211], v147 offset:55296
	ds_read_b128 v[224:227], v148 offset:53248
	ds_read_b128 v[228:231], v148 offset:55296
	global_load_lds_dwordx4 v[178:179], off
	s_add_i32 m0, s31, 0x2000
	s_add_u32 s28, s28, 0x80080
	v_lshl_add_u64 v[178:179], v[180:181], 0, s[62:63]
	s_addc_u32 s29, s29, 0
	s_add_i32 s31, s54, s33
	global_load_lds_dwordx4 v[178:179], off
	v_lshl_add_u64 v[178:179], s[28:29], 0, v[34:35]
	s_mov_b32 m0, s31
	s_nop 0
	global_load_lds_dwordx4 v[178:179], off
	v_lshl_add_u64 v[178:179], s[28:29], 0, v[140:141]
	s_add_i32 m0, s31, 0x2000
	s_nop 0
	global_load_lds_dwordx4 v[178:179], off
	v_lshl_add_u64 v[178:179], v[182:183], 0, s[62:63]
	s_mov_b32 m0, s48
	s_nop 0
	global_load_lds_dwordx4 v[178:179], off
	v_lshl_add_u64 v[178:179], v[212:213], 0, s[62:63]
	s_mov_b32 m0, s49
	s_nop 0
	global_load_lds_dwordx4 v[178:179], off
	s_waitcnt vmcnt(8)
	s_waitcnt lgkmcnt(0)
	s_barrier
	s_setprio 1
	s_waitcnt lgkmcnt(0)
	v_mfma_f32_16x16x32_bf16 v[60:63], v[150:153], v[188:191], v[60:63]
	v_mfma_f32_16x16x32_bf16 v[52:55], v[158:161], v[188:191], v[52:55]
	v_mfma_f32_16x16x32_bf16 v[44:47], v[150:153], v[192:195], v[44:47]
	v_mfma_f32_16x16x32_bf16 v[36:39], v[158:161], v[192:195], v[36:39]
	v_mfma_f32_16x16x32_bf16 v[26:29], v[150:153], v[204:207], v[26:29]
	v_mfma_f32_16x16x32_bf16 v[18:21], v[158:161], v[204:207], v[18:21]
	v_mfma_f32_16x16x32_bf16 v[10:13], v[150:153], v[208:211], v[10:13]
	v_mfma_f32_16x16x32_bf16 v[6:9], v[158:161], v[208:211], v[6:9]
	v_mfma_f32_16x16x32_bf16 v[60:63], v[154:157], v[196:199], v[60:63]
	v_mfma_f32_16x16x32_bf16 v[52:55], v[162:165], v[196:199], v[52:55]
	v_mfma_f32_16x16x32_bf16 v[44:47], v[154:157], v[200:203], v[44:47]
	v_mfma_f32_16x16x32_bf16 v[36:39], v[162:165], v[200:203], v[36:39]
	v_mfma_f32_16x16x32_bf16 v[26:29], v[154:157], v[224:227], v[26:29]
	v_mfma_f32_16x16x32_bf16 v[18:21], v[162:165], v[224:227], v[18:21]
	v_mfma_f32_16x16x32_bf16 v[10:13], v[154:157], v[228:231], v[10:13]
	v_mfma_f32_16x16x32_bf16 v[6:9], v[162:165], v[228:231], v[6:9]
	s_setprio 0
	s_setprio 1
	v_mfma_f32_16x16x32_bf16 v[64:67], v[166:169], v[188:191], v[64:67]
	v_mfma_f32_16x16x32_bf16 v[56:59], v[174:177], v[188:191], v[56:59]
	v_mfma_f32_16x16x32_bf16 v[48:51], v[166:169], v[192:195], v[48:51]
	v_mfma_f32_16x16x32_bf16 v[40:43], v[174:177], v[192:195], v[40:43]
	v_mfma_f32_16x16x32_bf16 v[30:33], v[166:169], v[204:207], v[30:33]
	v_mfma_f32_16x16x32_bf16 v[22:25], v[174:177], v[204:207], v[22:25]
	v_mfma_f32_16x16x32_bf16 v[14:17], v[166:169], v[208:211], v[14:17]
	v_mfma_f32_16x16x32_bf16 v[2:5], v[174:177], v[208:211], v[2:5]
	v_mfma_f32_16x16x32_bf16 v[64:67], v[170:173], v[196:199], v[64:67]
	v_mfma_f32_16x16x32_bf16 v[56:59], v[184:187], v[196:199], v[56:59]
	v_mfma_f32_16x16x32_bf16 v[48:51], v[170:173], v[200:203], v[48:51]
	v_mfma_f32_16x16x32_bf16 v[40:43], v[184:187], v[200:203], v[40:43]
	v_mfma_f32_16x16x32_bf16 v[30:33], v[170:173], v[224:227], v[30:33]
	v_mfma_f32_16x16x32_bf16 v[22:25], v[184:187], v[224:227], v[22:25]
	v_mfma_f32_16x16x32_bf16 v[14:17], v[170:173], v[228:231], v[14:17]
	v_mfma_f32_16x16x32_bf16 v[2:5], v[184:187], v[228:231], v[2:5]
	s_setprio 0
	s_barrier
	s_add_i32 s30, s30, 2
	s_add_u32 s8, s8, 0x100
	s_addc_u32 s9, s9, 0
	s_add_u32 s24, s24, 0x100
	s_addc_u32 s25, s25, 0
	s_cmp_gt_u32 s30, 29
	s_cbranch_scc0 .LBB0_1114

.LBB0_1181:
	v_readlane_b32 s18, v255, 11
	v_readlane_b32 s19, v255, 12
	v_readlane_b32 s52, v252, 3
	v_mov_b32_e32 v133, v35
	v_lshl_add_u64 v[2:3], s[18:19], 0, v[34:35]
	v_readlane_b32 s20, v255, 7
	s_cmp_eq_u32 s6, 3
	v_readlane_b32 s64, v252, 15
	v_readlane_b32 s65, v252, 16
	v_lshl_add_u64 v[4:5], s[18:19], 0, v[132:133]
	v_mov_b32_e32 v137, v35
	v_readlane_b32 s21, v255, 8
	v_readlane_b32 s53, v252, 4
	s_cselect_b32 s7, s65, 0
	s_cselect_b32 s6, s64, 0
	s_add_i32 m0, s29, 0x18000
	v_lshl_add_u64 v[2:3], v[2:3], 0, s[12:13]
	v_lshl_add_u64 v[6:7], s[20:21], 0, v[136:137]
	v_mov_b32_e32 v135, v35
	v_readlane_b32 s54, v252, 5
	v_and_b32_e32 v10, 15, v1
	s_lshl_b32 s51, s10, 6
	v_lshlrev_b32_e32 v12, 3, v1
	v_and_b32_e32 v1, 48, v1
	s_movk_i32 s10, 0x70
	s_waitcnt vmcnt(2)
	s_barrier
	global_load_lds_dwordx4 v[2:3], off
	v_lshl_add_u64 v[2:3], v[4:5], 0, s[12:13]
	s_add_i32 m0, s29, 0x1a000
	s_add_i32 s53, s29, 0x8000
	v_lshl_add_u64 v[8:9], s[20:21], 0, v[134:135]
	v_and_b32_e32 v13, 0x70, v12
	v_bitop3_b32 v12, v12, v1, s10 bitop3:0x6c
	global_load_lds_dwordx4 v[2:3], off
	v_lshl_add_u64 v[2:3], v[6:7], 0, s[12:13]
	s_mov_b32 m0, s53
	s_add_i32 s54, s29, 0xa000
	v_readlane_b32 s10, v255, 13
	global_load_lds_dwordx4 v[2:3], off
	v_lshl_add_u64 v[2:3], v[8:9], 0, s[12:13]
	s_mov_b32 m0, s54
	v_readlane_b32 s11, v255, 14
	global_load_lds_dwordx4 v[2:3], off
	s_add_i32 m0, s29, 0x1c000
	v_lshl_add_u64 v[2:3], s[10:11], 0, v[34:35]
	global_load_lds_dwordx4 v[2:3], off
	v_lshl_add_u64 v[2:3], s[10:11], 0, v[132:133]
	s_add_i32 m0, s29, 0x1e000
	s_lshl_b32 s9, s9, 5
	global_load_lds_dwordx4 v[2:3], off
	v_or_b32_e32 v11, s51, v10
	s_and_b32 s52, s9, 0x60
	v_lshlrev_b32_e32 v11, 7, v11
	v_or_b32_e32 v10, s52, v10
	s_waitcnt vmcnt(6)
	s_cmpk_lt_u32 s8, 0x100
	v_readlane_b32 s8, v255, 3
	v_bitop3_b32 v14, v11, v13, v1 bitop3:0xf6
	v_lshlrev_b32_e32 v10, 7, v10
	s_cselect_b64 s[10:11], -1, 0
	v_bitop3_b32 v2, v11, 64, v12 bitop3:0x36
	s_cmp_lg_u64 s[6:7], 0
	v_readlane_b32 s9, v255, 4
	s_mov_b32 s50, 0
	v_readlane_b32 s55, v252, 6
	v_readlane_b32 s56, v252, 7
	v_bitop3_b32 v1, v10, v13, v1 bitop3:0xf6
	v_bitop3_b32 v160, v10, 64, v12 bitop3:0x36
	v_add_u32_e32 v1, 0x10000, v1
	v_add_u32_e32 v160, 0x10000, v160
	s_cselect_b64 s[42:43], -1, 0
	v_add_u32_e32 v161, 0, v14
	v_add_u32_e32 v162, 0, v2
	v_readlane_b32 s12, v254, 62
	s_mov_b32 s13, s8
	s_mov_b64 s[8:9], s[20:21]
	v_readlane_b32 s57, v252, 8
	v_readlane_b32 s58, v252, 9
	v_readlane_b32 s59, v252, 10
	v_readlane_b32 s60, v252, 11
	v_readlane_b32 s61, v252, 12
	v_readlane_b32 s62, v252, 13
	v_readlane_b32 s63, v252, 14
	v_readlane_b32 s66, v252, 17
	v_readlane_b32 s67, v252, 18
	s_barrier
	s_branch .LBB0_1184

.LBB0_1194:
	s_add_u32 s8, s8, 0x160080
	s_addc_u32 s9, s9, 0
	s_add_u32 s20, s18, 0x100
	s_addc_u32 s21, s19, 0
	s_mov_b32 s24, -2
	v_readlane_b32 s35, v255, 20
	v_readlane_b32 s40, v255, 21
	v_readlane_b32 s41, v255, 22
	v_readlane_b32 s57, v255, 23
	s_mov_b64 s[58:59], 0x80
	s_add_u32 s18, s8, 0xffea0080
	s_addc_u32 s19, s9, -1
	s_add_i32 s25, 0, 0x10000
	s_cmpk_eq_i32 s24, 0x54
	s_cselect_b32 s23, s45, s19
	s_cselect_b32 s22, s44, s18
	s_cselect_b32 s19, s47, s21
	s_cselect_b32 s18, s46, s20
	s_add_i32 s34, 0, 0x14000
	ds_read_b128 v[138:141], v1
	ds_read_b128 v[142:145], v160
	ds_read_b128 v[146:149], v1 offset:2048
	ds_read_b128 v[150:153], v160 offset:2048
	ds_read_b128 v[154:157], v1 offset:16384
	ds_read_b128 v[164:167], v160 offset:16384
	ds_read_b128 v[168:171], v1 offset:18432
	ds_read_b128 v[172:175], v160 offset:18432
	v_lshl_add_u64 v[158:159], s[8:9], 0, v[136:137]
	s_add_i32 m0, s29, 0xc000
	ds_read_b128 v[176:179], v161
	ds_read_b128 v[184:187], v161 offset:2048
	ds_read_b128 v[188:191], v162
	ds_read_b128 v[192:195], v162 offset:2048
	ds_read_b128 v[196:199], v161 offset:4096
	ds_read_b128 v[200:203], v161 offset:6144
	ds_read_b128 v[204:207], v162 offset:4096
	ds_read_b128 v[208:211], v162 offset:6144
	global_load_lds_dwordx4 v[158:159], off
	v_lshl_add_u64 v[158:159], s[8:9], 0, v[134:135]
	s_add_i32 m0, s29, 0xe000
	s_nop 0
	global_load_lds_dwordx4 v[158:159], off
	s_waitcnt vmcnt(8)
	s_waitcnt lgkmcnt(0)
	s_barrier
	s_setprio 1
	s_waitcnt lgkmcnt(0)
	v_mfma_f32_16x16x32_bf16 v[128:131], v[138:141], v[176:179], 0
	v_mfma_f32_16x16x32_bf16 v[124:127], v[146:149], v[176:179], 0
	v_mfma_f32_16x16x32_bf16 v[112:115], v[138:141], v[184:187], 0
	v_mfma_f32_16x16x32_bf16 v[108:111], v[146:149], v[184:187], 0
	v_mfma_f32_16x16x32_bf16 v[96:99], v[138:141], v[196:199], 0
	v_mfma_f32_16x16x32_bf16 v[92:95], v[146:149], v[196:199], 0
	v_mfma_f32_16x16x32_bf16 v[80:83], v[138:141], v[200:203], 0
	v_mfma_f32_16x16x32_bf16 v[76:79], v[146:149], v[200:203], 0
	v_mfma_f32_16x16x32_bf16 v[128:131], v[142:145], v[188:191], v[128:131]
	v_mfma_f32_16x16x32_bf16 v[124:127], v[150:153], v[188:191], v[124:127]
	v_mfma_f32_16x16x32_bf16 v[112:115], v[142:145], v[192:195], v[112:115]
	v_mfma_f32_16x16x32_bf16 v[108:111], v[150:153], v[192:195], v[108:111]
	v_mfma_f32_16x16x32_bf16 v[96:99], v[142:145], v[204:207], v[96:99]
	v_mfma_f32_16x16x32_bf16 v[92:95], v[150:153], v[204:207], v[92:95]
	v_mfma_f32_16x16x32_bf16 v[80:83], v[142:145], v[208:211], v[80:83]
	v_mfma_f32_16x16x32_bf16 v[76:79], v[150:153], v[208:211], v[76:79]
	s_setprio 0
	s_setprio 1
	v_mfma_f32_16x16x32_bf16 v[120:123], v[154:157], v[176:179], 0
	v_mfma_f32_16x16x32_bf16 v[116:119], v[168:171], v[176:179], 0
	v_mfma_f32_16x16x32_bf16 v[104:107], v[154:157], v[184:187], 0
	v_mfma_f32_16x16x32_bf16 v[100:103], v[168:171], v[184:187], 0
	v_mfma_f32_16x16x32_bf16 v[88:91], v[154:157], v[196:199], 0
	v_mfma_f32_16x16x32_bf16 v[84:87], v[168:171], v[196:199], 0
	v_mfma_f32_16x16x32_bf16 v[72:75], v[154:157], v[200:203], 0
	v_mfma_f32_16x16x32_bf16 v[68:71], v[168:171], v[200:203], 0
	v_mfma_f32_16x16x32_bf16 v[120:123], v[164:167], v[188:191], v[120:123]
	v_mfma_f32_16x16x32_bf16 v[116:119], v[172:175], v[188:191], v[116:119]
	v_mfma_f32_16x16x32_bf16 v[104:107], v[164:167], v[192:195], v[104:107]
	v_mfma_f32_16x16x32_bf16 v[100:103], v[172:175], v[192:195], v[100:103]
	v_mfma_f32_16x16x32_bf16 v[88:91], v[164:167], v[204:207], v[88:91]
	v_mfma_f32_16x16x32_bf16 v[84:87], v[172:175], v[204:207], v[84:87]
	v_mfma_f32_16x16x32_bf16 v[72:75], v[164:167], v[208:211], v[72:75]
	v_mfma_f32_16x16x32_bf16 v[68:71], v[172:175], v[208:211], v[68:71]
	s_setprio 0
	s_barrier
	s_add_i32 s25, s25, s28
	v_lshl_add_u64 v[158:159], s[18:19], 0, v[34:35]
	s_mov_b32 m0, s25
	ds_read_b128 v[176:179], v161 offset:16384
	ds_read_b128 v[184:187], v161 offset:18432
	ds_read_b128 v[188:191], v162 offset:16384
	ds_read_b128 v[192:195], v162 offset:18432
	ds_read_b128 v[196:199], v161 offset:20480
	ds_read_b128 v[200:203], v161 offset:22528
	ds_read_b128 v[204:207], v162 offset:20480
	ds_read_b128 v[208:211], v162 offset:22528
	global_load_lds_dwordx4 v[158:159], off
	s_add_i32 m0, s25, 0x2000
	s_add_u32 s30, s18, 0x160000
	v_lshl_add_u64 v[180:181], s[18:19], 0, v[132:133]
	s_addc_u32 s31, s19, 0
	s_add_i32 s25, s34, s28
	global_load_lds_dwordx4 v[180:181], off
	v_lshl_add_u64 v[182:183], s[30:31], 0, v[34:35]
	s_mov_b32 m0, s25
	v_lshl_add_u64 v[212:213], s[22:23], 0, v[134:135]
	global_load_lds_dwordx4 v[182:183], off
	v_lshl_add_u64 v[182:183], s[30:31], 0, v[132:133]
	s_add_i32 m0, s25, 0x2000
	s_nop 0
	global_load_lds_dwordx4 v[182:183], off
	v_lshl_add_u64 v[182:183], s[22:23], 0, v[136:137]
	s_mov_b32 m0, s29
	s_nop 0
	global_load_lds_dwordx4 v[182:183], off
	s_mov_b32 m0, s33
	s_nop 0
	global_load_lds_dwordx4 v[212:213], off
	s_waitcnt vmcnt(8)
	s_waitcnt lgkmcnt(0)
	s_barrier
	s_setprio 1
	s_waitcnt lgkmcnt(0)
	v_mfma_f32_16x16x32_bf16 v[64:67], v[138:141], v[176:179], 0
	v_mfma_f32_16x16x32_bf16 v[60:63], v[146:149], v[176:179], 0
	v_mfma_f32_16x16x32_bf16 v[48:51], v[138:141], v[184:187], 0
	v_mfma_f32_16x16x32_bf16 v[44:47], v[146:149], v[184:187], 0
	v_mfma_f32_16x16x32_bf16 v[30:33], v[138:141], v[196:199], 0
	v_mfma_f32_16x16x32_bf16 v[26:29], v[146:149], v[196:199], 0
	v_mfma_f32_16x16x32_bf16 v[14:17], v[138:141], v[200:203], 0
	v_mfma_f32_16x16x32_bf16 v[10:13], v[146:149], v[200:203], 0
	v_mfma_f32_16x16x32_bf16 v[64:67], v[142:145], v[188:191], v[64:67]
	v_mfma_f32_16x16x32_bf16 v[60:63], v[150:153], v[188:191], v[60:63]
	v_mfma_f32_16x16x32_bf16 v[48:51], v[142:145], v[192:195], v[48:51]
	v_mfma_f32_16x16x32_bf16 v[44:47], v[150:153], v[192:195], v[44:47]
	v_mfma_f32_16x16x32_bf16 v[30:33], v[142:145], v[204:207], v[30:33]
	v_mfma_f32_16x16x32_bf16 v[26:29], v[150:153], v[204:207], v[26:29]
	v_mfma_f32_16x16x32_bf16 v[14:17], v[142:145], v[208:211], v[14:17]
	v_mfma_f32_16x16x32_bf16 v[10:13], v[150:153], v[208:211], v[10:13]
	s_setprio 0
	s_setprio 1
	v_mfma_f32_16x16x32_bf16 v[56:59], v[154:157], v[176:179], 0
	v_mfma_f32_16x16x32_bf16 v[52:55], v[168:171], v[176:179], 0
	v_mfma_f32_16x16x32_bf16 v[40:43], v[154:157], v[184:187], 0
	v_mfma_f32_16x16x32_bf16 v[36:39], v[168:171], v[184:187], 0
	v_mfma_f32_16x16x32_bf16 v[22:25], v[154:157], v[196:199], 0
	v_mfma_f32_16x16x32_bf16 v[18:21], v[168:171], v[196:199], 0
	v_mfma_f32_16x16x32_bf16 v[6:9], v[154:157], v[200:203], 0
	v_mfma_f32_16x16x32_bf16 v[2:5], v[168:171], v[200:203], 0
	v_mfma_f32_16x16x32_bf16 v[56:59], v[164:167], v[188:191], v[56:59]
	v_mfma_f32_16x16x32_bf16 v[52:55], v[172:175], v[188:191], v[52:55]
	v_mfma_f32_16x16x32_bf16 v[40:43], v[164:167], v[192:195], v[40:43]
	v_mfma_f32_16x16x32_bf16 v[36:39], v[172:175], v[192:195], v[36:39]
	v_mfma_f32_16x16x32_bf16 v[22:25], v[164:167], v[204:207], v[22:25]
	v_mfma_f32_16x16x32_bf16 v[18:21], v[172:175], v[204:207], v[18:21]
	v_mfma_f32_16x16x32_bf16 v[6:9], v[164:167], v[208:211], v[6:9]
	v_mfma_f32_16x16x32_bf16 v[2:5], v[172:175], v[208:211], v[2:5]
	s_setprio 0
	s_barrier
	s_add_i32 s25, 0, 0x18000
	s_add_i32 s30, 0, 0x1c000
	ds_read_b128 v[138:141], v1 offset:32768
	ds_read_b128 v[142:145], v160 offset:32768
	ds_read_b128 v[146:149], v1 offset:34816
	ds_read_b128 v[150:153], v160 offset:34816
	ds_read_b128 v[154:157], v1 offset:49152
	ds_read_b128 v[164:167], v160 offset:49152
	ds_read_b128 v[168:171], v1 offset:51200
	ds_read_b128 v[172:175], v160 offset:51200
	s_add_u32 s22, s22, 0x160000
	s_addc_u32 s23, s23, 0
	s_mov_b32 m0, s48
	v_lshl_add_u64 v[218:219], s[22:23], 0, v[136:137]
	ds_read_b128 v[176:179], v161 offset:32768
	ds_read_b128 v[184:187], v161 offset:34816
	ds_read_b128 v[188:191], v162 offset:32768
	ds_read_b128 v[192:195], v162 offset:34816
	ds_read_b128 v[196:199], v161 offset:36864
	ds_read_b128 v[200:203], v161 offset:38912
	ds_read_b128 v[204:207], v162 offset:36864
	ds_read_b128 v[208:211], v162 offset:38912
	global_load_lds_dwordx4 v[218:219], off
	v_lshl_add_u64 v[218:219], s[22:23], 0, v[134:135]
	s_mov_b32 m0, s49
	s_nop 0
	global_load_lds_dwordx4 v[218:219], off
	s_waitcnt vmcnt(8)
	s_waitcnt lgkmcnt(0)
	s_barrier
	s_setprio 1
	s_waitcnt lgkmcnt(0)
	v_mfma_f32_16x16x32_bf16 v[128:131], v[138:141], v[176:179], v[128:131]
	v_mfma_f32_16x16x32_bf16 v[124:127], v[146:149], v[176:179], v[124:127]
	v_mfma_f32_16x16x32_bf16 v[112:115], v[138:141], v[184:187], v[112:115]
	v_mfma_f32_16x16x32_bf16 v[108:111], v[146:149], v[184:187], v[108:111]
	v_mfma_f32_16x16x32_bf16 v[96:99], v[138:141], v[196:199], v[96:99]
	v_mfma_f32_16x16x32_bf16 v[92:95], v[146:149], v[196:199], v[92:95]
	v_mfma_f32_16x16x32_bf16 v[80:83], v[138:141], v[200:203], v[80:83]
	v_mfma_f32_16x16x32_bf16 v[76:79], v[146:149], v[200:203], v[76:79]
	v_mfma_f32_16x16x32_bf16 v[128:131], v[142:145], v[188:191], v[128:131]
	v_mfma_f32_16x16x32_bf16 v[124:127], v[150:153], v[188:191], v[124:127]
	v_mfma_f32_16x16x32_bf16 v[112:115], v[142:145], v[192:195], v[112:115]
	v_mfma_f32_16x16x32_bf16 v[108:111], v[150:153], v[192:195], v[108:111]
	v_mfma_f32_16x16x32_bf16 v[96:99], v[142:145], v[204:207], v[96:99]
	v_mfma_f32_16x16x32_bf16 v[92:95], v[150:153], v[204:207], v[92:95]
	v_mfma_f32_16x16x32_bf16 v[80:83], v[142:145], v[208:211], v[80:83]
	v_mfma_f32_16x16x32_bf16 v[76:79], v[150:153], v[208:211], v[76:79]
	s_setprio 0
	s_setprio 1
	v_mfma_f32_16x16x32_bf16 v[120:123], v[154:157], v[176:179], v[120:123]
	v_mfma_f32_16x16x32_bf16 v[116:119], v[168:171], v[176:179], v[116:119]
	v_mfma_f32_16x16x32_bf16 v[104:107], v[154:157], v[184:187], v[104:107]
	v_mfma_f32_16x16x32_bf16 v[100:103], v[168:171], v[184:187], v[100:103]
	v_mfma_f32_16x16x32_bf16 v[88:91], v[154:157], v[196:199], v[88:91]
	v_mfma_f32_16x16x32_bf16 v[84:87], v[168:171], v[196:199], v[84:87]
	v_mfma_f32_16x16x32_bf16 v[72:75], v[154:157], v[200:203], v[72:75]
	v_mfma_f32_16x16x32_bf16 v[68:71], v[168:171], v[200:203], v[68:71]
	v_mfma_f32_16x16x32_bf16 v[120:123], v[164:167], v[188:191], v[120:123]
	v_mfma_f32_16x16x32_bf16 v[116:119], v[172:175], v[188:191], v[116:119]
	v_mfma_f32_16x16x32_bf16 v[104:107], v[164:167], v[192:195], v[104:107]
	v_mfma_f32_16x16x32_bf16 v[100:103], v[172:175], v[192:195], v[100:103]
	v_mfma_f32_16x16x32_bf16 v[88:91], v[164:167], v[204:207], v[88:91]
	v_mfma_f32_16x16x32_bf16 v[84:87], v[172:175], v[204:207], v[84:87]
	v_mfma_f32_16x16x32_bf16 v[72:75], v[164:167], v[208:211], v[72:75]
	v_mfma_f32_16x16x32_bf16 v[68:71], v[172:175], v[208:211], v[68:71]
	s_setprio 0
	s_barrier
	s_add_i32 s22, s25, s28
	v_lshl_add_u64 v[158:159], v[158:159], 0, s[58:59]
	s_mov_b32 m0, s22
	ds_read_b128 v[176:179], v161 offset:49152
	ds_read_b128 v[184:187], v161 offset:51200
	ds_read_b128 v[188:191], v162 offset:49152
	ds_read_b128 v[192:195], v162 offset:51200
	ds_read_b128 v[196:199], v161 offset:53248
	ds_read_b128 v[200:203], v161 offset:55296
	ds_read_b128 v[204:207], v162 offset:53248
	ds_read_b128 v[208:211], v162 offset:55296
	global_load_lds_dwordx4 v[158:159], off
	s_add_i32 m0, s22, 0x2000
	s_add_u32 s18, s18, 0x160080
	v_lshl_add_u64 v[158:159], v[180:181], 0, s[58:59]
	s_addc_u32 s19, s19, 0
	s_add_i32 s22, s30, s28
	global_load_lds_dwordx4 v[158:159], off
	v_lshl_add_u64 v[158:159], s[18:19], 0, v[34:35]
	s_mov_b32 m0, s22
	s_nop 0
	global_load_lds_dwordx4 v[158:159], off
	v_lshl_add_u64 v[158:159], s[18:19], 0, v[132:133]
	s_add_i32 m0, s22, 0x2000
	s_nop 0
	global_load_lds_dwordx4 v[158:159], off
	v_lshl_add_u64 v[158:159], v[182:183], 0, s[58:59]
	s_mov_b32 m0, s53
	s_nop 0
	global_load_lds_dwordx4 v[158:159], off
	v_lshl_add_u64 v[158:159], v[212:213], 0, s[58:59]
	s_mov_b32 m0, s54
	s_nop 0
	global_load_lds_dwordx4 v[158:159], off
	s_waitcnt vmcnt(8)
	s_waitcnt lgkmcnt(0)
	s_barrier
	s_setprio 1
	s_waitcnt lgkmcnt(0)
	v_mfma_f32_16x16x32_bf16 v[64:67], v[138:141], v[176:179], v[64:67]
	v_mfma_f32_16x16x32_bf16 v[60:63], v[146:149], v[176:179], v[60:63]
	v_mfma_f32_16x16x32_bf16 v[48:51], v[138:141], v[184:187], v[48:51]
	v_mfma_f32_16x16x32_bf16 v[44:47], v[146:149], v[184:187], v[44:47]
	v_mfma_f32_16x16x32_bf16 v[30:33], v[138:141], v[196:199], v[30:33]
	v_mfma_f32_16x16x32_bf16 v[26:29], v[146:149], v[196:199], v[26:29]
	v_mfma_f32_16x16x32_bf16 v[14:17], v[138:141], v[200:203], v[14:17]
	v_mfma_f32_16x16x32_bf16 v[10:13], v[146:149], v[200:203], v[10:13]
	v_mfma_f32_16x16x32_bf16 v[64:67], v[142:145], v[188:191], v[64:67]
	v_mfma_f32_16x16x32_bf16 v[60:63], v[150:153], v[188:191], v[60:63]
	v_mfma_f32_16x16x32_bf16 v[48:51], v[142:145], v[192:195], v[48:51]
	v_mfma_f32_16x16x32_bf16 v[44:47], v[150:153], v[192:195], v[44:47]
	v_mfma_f32_16x16x32_bf16 v[30:33], v[142:145], v[204:207], v[30:33]
	v_mfma_f32_16x16x32_bf16 v[26:29], v[150:153], v[204:207], v[26:29]
	v_mfma_f32_16x16x32_bf16 v[14:17], v[142:145], v[208:211], v[14:17]
	v_mfma_f32_16x16x32_bf16 v[10:13], v[150:153], v[208:211], v[10:13]
	s_setprio 0
	s_setprio 1
	v_mfma_f32_16x16x32_bf16 v[56:59], v[154:157], v[176:179], v[56:59]
	v_mfma_f32_16x16x32_bf16 v[52:55], v[168:171], v[176:179], v[52:55]
	v_mfma_f32_16x16x32_bf16 v[40:43], v[154:157], v[184:187], v[40:43]
	v_mfma_f32_16x16x32_bf16 v[36:39], v[168:171], v[184:187], v[36:39]
	v_mfma_f32_16x16x32_bf16 v[22:25], v[154:157], v[196:199], v[22:25]
	v_mfma_f32_16x16x32_bf16 v[18:21], v[168:171], v[196:199], v[18:21]
	v_mfma_f32_16x16x32_bf16 v[6:9], v[154:157], v[200:203], v[6:9]
	v_mfma_f32_16x16x32_bf16 v[2:5], v[168:171], v[200:203], v[2:5]
	v_mfma_f32_16x16x32_bf16 v[56:59], v[164:167], v[188:191], v[56:59]
	v_mfma_f32_16x16x32_bf16 v[52:55], v[172:175], v[188:191], v[52:55]
	v_mfma_f32_16x16x32_bf16 v[40:43], v[164:167], v[192:195], v[40:43]
	v_mfma_f32_16x16x32_bf16 v[36:39], v[172:175], v[192:195], v[36:39]
	v_mfma_f32_16x16x32_bf16 v[22:25], v[164:167], v[204:207], v[22:25]
	v_mfma_f32_16x16x32_bf16 v[18:21], v[172:175], v[204:207], v[18:21]
	v_mfma_f32_16x16x32_bf16 v[6:9], v[164:167], v[208:211], v[6:9]
	v_mfma_f32_16x16x32_bf16 v[2:5], v[172:175], v[208:211], v[2:5]
	s_setprio 0
	s_barrier
	s_add_i32 s24, s24, 2
	s_add_u32 s8, s8, 0x100
	s_addc_u32 s9, s9, 0
	s_add_u32 s20, s20, 0x100
	s_addc_u32 s21, s21, 0
	s_cmpk_gt_u32 s24, 0x55
	s_cbranch_scc1 .Lpeel_done_P7
.LBB0_1195:
	s_add_u32 s18, s8, 0xffea0080
	s_addc_u32 s19, s9, -1
	s_add_i32 s25, 0, 0x10000
	s_cmpk_eq_i32 s24, 0x54
	s_cselect_b32 s23, s45, s19
	s_cselect_b32 s22, s44, s18
	s_cselect_b32 s19, s47, s21
	s_cselect_b32 s18, s46, s20
	s_add_i32 s34, 0, 0x14000
	ds_read_b128 v[138:141], v1
	ds_read_b128 v[142:145], v160
	ds_read_b128 v[146:149], v1 offset:2048
	ds_read_b128 v[150:153], v160 offset:2048
	ds_read_b128 v[154:157], v1 offset:16384
	ds_read_b128 v[164:167], v160 offset:16384
	ds_read_b128 v[168:171], v1 offset:18432
	ds_read_b128 v[172:175], v160 offset:18432
	v_lshl_add_u64 v[158:159], s[8:9], 0, v[136:137]
	s_add_i32 m0, s29, 0xc000
	ds_read_b128 v[176:179], v161
	ds_read_b128 v[184:187], v161 offset:2048
	ds_read_b128 v[188:191], v162
	ds_read_b128 v[192:195], v162 offset:2048
	ds_read_b128 v[196:199], v161 offset:4096
	ds_read_b128 v[200:203], v161 offset:6144
	ds_read_b128 v[204:207], v162 offset:4096
	ds_read_b128 v[208:211], v162 offset:6144
	global_load_lds_dwordx4 v[158:159], off
	v_lshl_add_u64 v[158:159], s[8:9], 0, v[134:135]
	s_add_i32 m0, s29, 0xe000
	s_nop 0
	global_load_lds_dwordx4 v[158:159], off
	s_waitcnt vmcnt(8)
	s_waitcnt lgkmcnt(0)
	s_barrier
	s_setprio 1
	s_waitcnt lgkmcnt(0)
	v_mfma_f32_16x16x32_bf16 v[128:131], v[138:141], v[176:179], v[128:131]
	v_mfma_f32_16x16x32_bf16 v[124:127], v[146:149], v[176:179], v[124:127]
	v_mfma_f32_16x16x32_bf16 v[112:115], v[138:141], v[184:187], v[112:115]
	v_mfma_f32_16x16x32_bf16 v[108:111], v[146:149], v[184:187], v[108:111]
	v_mfma_f32_16x16x32_bf16 v[96:99], v[138:141], v[196:199], v[96:99]
	v_mfma_f32_16x16x32_bf16 v[92:95], v[146:149], v[196:199], v[92:95]
	v_mfma_f32_16x16x32_bf16 v[80:83], v[138:141], v[200:203], v[80:83]
	v_mfma_f32_16x16x32_bf16 v[76:79], v[146:149], v[200:203], v[76:79]
	v_mfma_f32_16x16x32_bf16 v[128:131], v[142:145], v[188:191], v[128:131]
	v_mfma_f32_16x16x32_bf16 v[124:127], v[150:153], v[188:191], v[124:127]
	v_mfma_f32_16x16x32_bf16 v[112:115], v[142:145], v[192:195], v[112:115]
	v_mfma_f32_16x16x32_bf16 v[108:111], v[150:153], v[192:195], v[108:111]
	v_mfma_f32_16x16x32_bf16 v[96:99], v[142:145], v[204:207], v[96:99]
	v_mfma_f32_16x16x32_bf16 v[92:95], v[150:153], v[204:207], v[92:95]
	v_mfma_f32_16x16x32_bf16 v[80:83], v[142:145], v[208:211], v[80:83]
	v_mfma_f32_16x16x32_bf16 v[76:79], v[150:153], v[208:211], v[76:79]
	s_setprio 0
	s_setprio 1
	v_mfma_f32_16x16x32_bf16 v[120:123], v[154:157], v[176:179], v[120:123]
	v_mfma_f32_16x16x32_bf16 v[116:119], v[168:171], v[176:179], v[116:119]
	v_mfma_f32_16x16x32_bf16 v[104:107], v[154:157], v[184:187], v[104:107]
	v_mfma_f32_16x16x32_bf16 v[100:103], v[168:171], v[184:187], v[100:103]
	v_mfma_f32_16x16x32_bf16 v[88:91], v[154:157], v[196:199], v[88:91]
	v_mfma_f32_16x16x32_bf16 v[84:87], v[168:171], v[196:199], v[84:87]
	v_mfma_f32_16x16x32_bf16 v[72:75], v[154:157], v[200:203], v[72:75]
	v_mfma_f32_16x16x32_bf16 v[68:71], v[168:171], v[200:203], v[68:71]
	v_mfma_f32_16x16x32_bf16 v[120:123], v[164:167], v[188:191], v[120:123]
	v_mfma_f32_16x16x32_bf16 v[116:119], v[172:175], v[188:191], v[116:119]
	v_mfma_f32_16x16x32_bf16 v[104:107], v[164:167], v[192:195], v[104:107]
	v_mfma_f32_16x16x32_bf16 v[100:103], v[172:175], v[192:195], v[100:103]
	v_mfma_f32_16x16x32_bf16 v[88:91], v[164:167], v[204:207], v[88:91]
	v_mfma_f32_16x16x32_bf16 v[84:87], v[172:175], v[204:207], v[84:87]
	v_mfma_f32_16x16x32_bf16 v[72:75], v[164:167], v[208:211], v[72:75]
	v_mfma_f32_16x16x32_bf16 v[68:71], v[172:175], v[208:211], v[68:71]
	s_setprio 0
	s_barrier
	s_add_i32 s25, s25, s28
	v_lshl_add_u64 v[158:159], s[18:19], 0, v[34:35]
	s_mov_b32 m0, s25
	ds_read_b128 v[176:179], v161 offset:16384
	ds_read_b128 v[184:187], v161 offset:18432
	ds_read_b128 v[188:191], v162 offset:16384
	ds_read_b128 v[192:195], v162 offset:18432
	ds_read_b128 v[196:199], v161 offset:20480
	ds_read_b128 v[200:203], v161 offset:22528
	ds_read_b128 v[204:207], v162 offset:20480
	ds_read_b128 v[208:211], v162 offset:22528
	global_load_lds_dwordx4 v[158:159], off
	s_add_i32 m0, s25, 0x2000
	s_add_u32 s30, s18, 0x160000
	v_lshl_add_u64 v[180:181], s[18:19], 0, v[132:133]
	s_addc_u32 s31, s19, 0
	s_add_i32 s25, s34, s28
	global_load_lds_dwordx4 v[180:181], off
	v_lshl_add_u64 v[182:183], s[30:31], 0, v[34:35]
	s_mov_b32 m0, s25
	v_lshl_add_u64 v[212:213], s[22:23], 0, v[134:135]
	global_load_lds_dwordx4 v[182:183], off
	v_lshl_add_u64 v[182:183], s[30:31], 0, v[132:133]
	s_add_i32 m0, s25, 0x2000
	s_nop 0
	global_load_lds_dwordx4 v[182:183], off
	v_lshl_add_u64 v[182:183], s[22:23], 0, v[136:137]
	s_mov_b32 m0, s29
	s_nop 0
	global_load_lds_dwordx4 v[182:183], off
	s_mov_b32 m0, s33
	s_nop 0
	global_load_lds_dwordx4 v[212:213], off
	s_waitcnt vmcnt(8)
	s_waitcnt lgkmcnt(0)
	s_barrier
	s_setprio 1
	s_waitcnt lgkmcnt(0)
	v_mfma_f32_16x16x32_bf16 v[64:67], v[138:141], v[176:179], v[64:67]
	v_mfma_f32_16x16x32_bf16 v[60:63], v[146:149], v[176:179], v[60:63]
	v_mfma_f32_16x16x32_bf16 v[48:51], v[138:141], v[184:187], v[48:51]
	v_mfma_f32_16x16x32_bf16 v[44:47], v[146:149], v[184:187], v[44:47]
	v_mfma_f32_16x16x32_bf16 v[30:33], v[138:141], v[196:199], v[30:33]
	v_mfma_f32_16x16x32_bf16 v[26:29], v[146:149], v[196:199], v[26:29]
	v_mfma_f32_16x16x32_bf16 v[14:17], v[138:141], v[200:203], v[14:17]
	v_mfma_f32_16x16x32_bf16 v[10:13], v[146:149], v[200:203], v[10:13]
	v_mfma_f32_16x16x32_bf16 v[64:67], v[142:145], v[188:191], v[64:67]
	v_mfma_f32_16x16x32_bf16 v[60:63], v[150:153], v[188:191], v[60:63]
	v_mfma_f32_16x16x32_bf16 v[48:51], v[142:145], v[192:195], v[48:51]
	v_mfma_f32_16x16x32_bf16 v[44:47], v[150:153], v[192:195], v[44:47]
	v_mfma_f32_16x16x32_bf16 v[30:33], v[142:145], v[204:207], v[30:33]
	v_mfma_f32_16x16x32_bf16 v[26:29], v[150:153], v[204:207], v[26:29]
	v_mfma_f32_16x16x32_bf16 v[14:17], v[142:145], v[208:211], v[14:17]
	v_mfma_f32_16x16x32_bf16 v[10:13], v[150:153], v[208:211], v[10:13]
	s_setprio 0
	s_setprio 1
	v_mfma_f32_16x16x32_bf16 v[56:59], v[154:157], v[176:179], v[56:59]
	v_mfma_f32_16x16x32_bf16 v[52:55], v[168:171], v[176:179], v[52:55]
	v_mfma_f32_16x16x32_bf16 v[40:43], v[154:157], v[184:187], v[40:43]
	v_mfma_f32_16x16x32_bf16 v[36:39], v[168:171], v[184:187], v[36:39]
	v_mfma_f32_16x16x32_bf16 v[22:25], v[154:157], v[196:199], v[22:25]
	v_mfma_f32_16x16x32_bf16 v[18:21], v[168:171], v[196:199], v[18:21]
	v_mfma_f32_16x16x32_bf16 v[6:9], v[154:157], v[200:203], v[6:9]
	v_mfma_f32_16x16x32_bf16 v[2:5], v[168:171], v[200:203], v[2:5]
	v_mfma_f32_16x16x32_bf16 v[56:59], v[164:167], v[188:191], v[56:59]
	v_mfma_f32_16x16x32_bf16 v[52:55], v[172:175], v[188:191], v[52:55]
	v_mfma_f32_16x16x32_bf16 v[40:43], v[164:167], v[192:195], v[40:43]
	v_mfma_f32_16x16x32_bf16 v[36:39], v[172:175], v[192:195], v[36:39]
	v_mfma_f32_16x16x32_bf16 v[22:25], v[164:167], v[204:207], v[22:25]
	v_mfma_f32_16x16x32_bf16 v[18:21], v[172:175], v[204:207], v[18:21]
	v_mfma_f32_16x16x32_bf16 v[6:9], v[164:167], v[208:211], v[6:9]
	v_mfma_f32_16x16x32_bf16 v[2:5], v[172:175], v[208:211], v[2:5]
	s_setprio 0
	s_barrier
	s_add_i32 s25, 0, 0x18000
	s_add_i32 s30, 0, 0x1c000
	ds_read_b128 v[138:141], v1 offset:32768
	ds_read_b128 v[142:145], v160 offset:32768
	ds_read_b128 v[146:149], v1 offset:34816
	ds_read_b128 v[150:153], v160 offset:34816
	ds_read_b128 v[154:157], v1 offset:49152
	ds_read_b128 v[164:167], v160 offset:49152
	ds_read_b128 v[168:171], v1 offset:51200
	ds_read_b128 v[172:175], v160 offset:51200
	s_add_u32 s22, s22, 0x160000
	s_addc_u32 s23, s23, 0
	s_mov_b32 m0, s48
	v_lshl_add_u64 v[218:219], s[22:23], 0, v[136:137]
	ds_read_b128 v[176:179], v161 offset:32768
	ds_read_b128 v[184:187], v161 offset:34816
	ds_read_b128 v[188:191], v162 offset:32768
	ds_read_b128 v[192:195], v162 offset:34816
	ds_read_b128 v[196:199], v161 offset:36864
	ds_read_b128 v[200:203], v161 offset:38912
	ds_read_b128 v[204:207], v162 offset:36864
	ds_read_b128 v[208:211], v162 offset:38912
	global_load_lds_dwordx4 v[218:219], off
	v_lshl_add_u64 v[218:219], s[22:23], 0, v[134:135]
	s_mov_b32 m0, s49
	s_nop 0
	global_load_lds_dwordx4 v[218:219], off
	s_waitcnt vmcnt(8)
	s_waitcnt lgkmcnt(0)
	s_barrier
	s_setprio 1
	s_waitcnt lgkmcnt(0)
	v_mfma_f32_16x16x32_bf16 v[128:131], v[138:141], v[176:179], v[128:131]
	v_mfma_f32_16x16x32_bf16 v[124:127], v[146:149], v[176:179], v[124:127]
	v_mfma_f32_16x16x32_bf16 v[112:115], v[138:141], v[184:187], v[112:115]
	v_mfma_f32_16x16x32_bf16 v[108:111], v[146:149], v[184:187], v[108:111]
	v_mfma_f32_16x16x32_bf16 v[96:99], v[138:141], v[196:199], v[96:99]
	v_mfma_f32_16x16x32_bf16 v[92:95], v[146:149], v[196:199], v[92:95]
	v_mfma_f32_16x16x32_bf16 v[80:83], v[138:141], v[200:203], v[80:83]
	v_mfma_f32_16x16x32_bf16 v[76:79], v[146:149], v[200:203], v[76:79]
	v_mfma_f32_16x16x32_bf16 v[128:131], v[142:145], v[188:191], v[128:131]
	v_mfma_f32_16x16x32_bf16 v[124:127], v[150:153], v[188:191], v[124:127]
	v_mfma_f32_16x16x32_bf16 v[112:115], v[142:145], v[192:195], v[112:115]
	v_mfma_f32_16x16x32_bf16 v[108:111], v[150:153], v[192:195], v[108:111]
	v_mfma_f32_16x16x32_bf16 v[96:99], v[142:145], v[204:207], v[96:99]
	v_mfma_f32_16x16x32_bf16 v[92:95], v[150:153], v[204:207], v[92:95]
	v_mfma_f32_16x16x32_bf16 v[80:83], v[142:145], v[208:211], v[80:83]
	v_mfma_f32_16x16x32_bf16 v[76:79], v[150:153], v[208:211], v[76:79]
	s_setprio 0
	s_setprio 1
	v_mfma_f32_16x16x32_bf16 v[120:123], v[154:157], v[176:179], v[120:123]
	v_mfma_f32_16x16x32_bf16 v[116:119], v[168:171], v[176:179], v[116:119]
	v_mfma_f32_16x16x32_bf16 v[104:107], v[154:157], v[184:187], v[104:107]
	v_mfma_f32_16x16x32_bf16 v[100:103], v[168:171], v[184:187], v[100:103]
	v_mfma_f32_16x16x32_bf16 v[88:91], v[154:157], v[196:199], v[88:91]
	v_mfma_f32_16x16x32_bf16 v[84:87], v[168:171], v[196:199], v[84:87]
	v_mfma_f32_16x16x32_bf16 v[72:75], v[154:157], v[200:203], v[72:75]
	v_mfma_f32_16x16x32_bf16 v[68:71], v[168:171], v[200:203], v[68:71]
	v_mfma_f32_16x16x32_bf16 v[120:123], v[164:167], v[188:191], v[120:123]
	v_mfma_f32_16x16x32_bf16 v[116:119], v[172:175], v[188:191], v[116:119]
	v_mfma_f32_16x16x32_bf16 v[104:107], v[164:167], v[192:195], v[104:107]
	v_mfma_f32_16x16x32_bf16 v[100:103], v[172:175], v[192:195], v[100:103]
	v_mfma_f32_16x16x32_bf16 v[88:91], v[164:167], v[204:207], v[88:91]
	v_mfma_f32_16x16x32_bf16 v[84:87], v[172:175], v[204:207], v[84:87]
	v_mfma_f32_16x16x32_bf16 v[72:75], v[164:167], v[208:211], v[72:75]
	v_mfma_f32_16x16x32_bf16 v[68:71], v[172:175], v[208:211], v[68:71]
	s_setprio 0
	s_barrier
	s_add_i32 s22, s25, s28
	v_lshl_add_u64 v[158:159], v[158:159], 0, s[58:59]
	s_mov_b32 m0, s22
	ds_read_b128 v[176:179], v161 offset:49152
	ds_read_b128 v[184:187], v161 offset:51200
	ds_read_b128 v[188:191], v162 offset:49152
	ds_read_b128 v[192:195], v162 offset:51200
	ds_read_b128 v[196:199], v161 offset:53248
	ds_read_b128 v[200:203], v161 offset:55296
	ds_read_b128 v[204:207], v162 offset:53248
	ds_read_b128 v[208:211], v162 offset:55296
	global_load_lds_dwordx4 v[158:159], off
	s_add_i32 m0, s22, 0x2000
	s_add_u32 s18, s18, 0x160080
	v_lshl_add_u64 v[158:159], v[180:181], 0, s[58:59]
	s_addc_u32 s19, s19, 0
	s_add_i32 s22, s30, s28
	global_load_lds_dwordx4 v[158:159], off
	v_lshl_add_u64 v[158:159], s[18:19], 0, v[34:35]
	s_mov_b32 m0, s22
	s_nop 0
	global_load_lds_dwordx4 v[158:159], off
	v_lshl_add_u64 v[158:159], s[18:19], 0, v[132:133]
	s_add_i32 m0, s22, 0x2000
	s_nop 0
	global_load_lds_dwordx4 v[158:159], off
	v_lshl_add_u64 v[158:159], v[182:183], 0, s[58:59]
	s_mov_b32 m0, s53
	s_nop 0
	global_load_lds_dwordx4 v[158:159], off
	v_lshl_add_u64 v[158:159], v[212:213], 0, s[58:59]
	s_mov_b32 m0, s54
	s_nop 0
	global_load_lds_dwordx4 v[158:159], off
	s_waitcnt vmcnt(8)
	s_waitcnt lgkmcnt(0)
	s_barrier
	s_setprio 1
	s_waitcnt lgkmcnt(0)
	v_mfma_f32_16x16x32_bf16 v[64:67], v[138:141], v[176:179], v[64:67]
	v_mfma_f32_16x16x32_bf16 v[60:63], v[146:149], v[176:179], v[60:63]
	v_mfma_f32_16x16x32_bf16 v[48:51], v[138:141], v[184:187], v[48:51]
	v_mfma_f32_16x16x32_bf16 v[44:47], v[146:149], v[184:187], v[44:47]
	v_mfma_f32_16x16x32_bf16 v[30:33], v[138:141], v[196:199], v[30:33]
	v_mfma_f32_16x16x32_bf16 v[26:29], v[146:149], v[196:199], v[26:29]
	v_mfma_f32_16x16x32_bf16 v[14:17], v[138:141], v[200:203], v[14:17]
	v_mfma_f32_16x16x32_bf16 v[10:13], v[146:149], v[200:203], v[10:13]
	v_mfma_f32_16x16x32_bf16 v[64:67], v[142:145], v[188:191], v[64:67]
	v_mfma_f32_16x16x32_bf16 v[60:63], v[150:153], v[188:191], v[60:63]
	v_mfma_f32_16x16x32_bf16 v[48:51], v[142:145], v[192:195], v[48:51]
	v_mfma_f32_16x16x32_bf16 v[44:47], v[150:153], v[192:195], v[44:47]
	v_mfma_f32_16x16x32_bf16 v[30:33], v[142:145], v[204:207], v[30:33]
	v_mfma_f32_16x16x32_bf16 v[26:29], v[150:153], v[204:207], v[26:29]
	v_mfma_f32_16x16x32_bf16 v[14:17], v[142:145], v[208:211], v[14:17]
	v_mfma_f32_16x16x32_bf16 v[10:13], v[150:153], v[208:211], v[10:13]
	s_setprio 0
	s_setprio 1
	v_mfma_f32_16x16x32_bf16 v[56:59], v[154:157], v[176:179], v[56:59]
	v_mfma_f32_16x16x32_bf16 v[52:55], v[168:171], v[176:179], v[52:55]
	v_mfma_f32_16x16x32_bf16 v[40:43], v[154:157], v[184:187], v[40:43]
	v_mfma_f32_16x16x32_bf16 v[36:39], v[168:171], v[184:187], v[36:39]
	v_mfma_f32_16x16x32_bf16 v[22:25], v[154:157], v[196:199], v[22:25]
	v_mfma_f32_16x16x32_bf16 v[18:21], v[168:171], v[196:199], v[18:21]
	v_mfma_f32_16x16x32_bf16 v[6:9], v[154:157], v[200:203], v[6:9]
	v_mfma_f32_16x16x32_bf16 v[2:5], v[168:171], v[200:203], v[2:5]
	v_mfma_f32_16x16x32_bf16 v[56:59], v[164:167], v[188:191], v[56:59]
	v_mfma_f32_16x16x32_bf16 v[52:55], v[172:175], v[188:191], v[52:55]
	v_mfma_f32_16x16x32_bf16 v[40:43], v[164:167], v[192:195], v[40:43]
	v_mfma_f32_16x16x32_bf16 v[36:39], v[172:175], v[192:195], v[36:39]
	v_mfma_f32_16x16x32_bf16 v[22:25], v[164:167], v[204:207], v[22:25]
	v_mfma_f32_16x16x32_bf16 v[18:21], v[172:175], v[204:207], v[18:21]
	v_mfma_f32_16x16x32_bf16 v[6:9], v[164:167], v[208:211], v[6:9]
	v_mfma_f32_16x16x32_bf16 v[2:5], v[172:175], v[208:211], v[2:5]
	s_setprio 0
	s_barrier
	s_add_i32 s24, s24, 2
	s_add_u32 s8, s8, 0x100
	s_addc_u32 s9, s9, 0
	s_add_u32 s20, s20, 0x100
	s_addc_u32 s21, s21, 0
	s_cmpk_gt_u32 s24, 0x55
	s_cbranch_scc0 .LBB0_1195
